# GEMM K-loops: s_sleep 1 at the head of every load segment (lets the partner wave's MFMA block start uncontended)
# baseline (speedup 1.0000x reference)
; #define PG8_STAGE(bufoff, gbase, voff) do { _Pragma("unroll") for (int _i = 0; _i < 2; ++_i) \
;         __builtin_amdgcn_global_load_lds((const unsigned*)((const char*)(gbase) + (voff)[_i]), (PG8_LAS unsigned*)(lds + (bufoff) + ldsw + _i * 8192), 16, 0, 0); } while (0)
; #define PG8_LDA(dst, b, h) do { _Pragma("unroll") for (int m = 0; m < 4; ++m) _Pragma("unroll") for (int k = 0; k < 2; ++k) dst[m][k] = *(const PG8_LAS bf16x8*)(lds + PG8_SA(b, h) + aoff + m * 2048 + k * 1024); } while (0)
; #define PG8_LDB(dst, b, h) do { _Pragma("unroll") for (int n = 0; n < 2; ++n) _Pragma("unroll") for (int k = 0; k < 2; ++k) dst[n][k] = *(const PG8_LAS bf16x8*)(lds + PG8_SB(b, h) + boff + n * 2048 + k * 1024); } while (0)
; #define PG8_MMA(ai, bj, At, Bt) do { __builtin_amdgcn_s_setprio(1); _Pragma("unroll") for (int m = 0; m < 4; ++m) _Pragma("unroll") for (int n = 0; n < 2; ++n) _Pragma("unroll") for (int k = 0; k < 2; ++k) \
;         acc[ai][bj][m][n] = __builtin_amdgcn_mfma_f32_16x16x32_bf16(Bt[n][k], At[m][k], acc[ai][bj][m][n], 0, 0, 0); __builtin_amdgcn_s_setprio(0); } while (0)
; #define PG8_WAIT_V(n) asm volatile("s_waitcnt vmcnt(" #n ")" ::: "memory")
; #define PG8_WAIT_L(n) asm volatile("s_waitcnt lgkmcnt(" #n ")" ::: "memory")
; #define PG8_BAR __builtin_amdgcn_s_barrier()
; #define PG8_SCHED __builtin_amdgcn_sched_barrier(0)
; template <class Epi, class Sched, bool ALIGN_EPI = false, bool SP2 = false>
; __device__ __forceinline__ void gemm_phase(PG8_LAS unsigned char* lds, const Gemm g, const Sched& S, const Epi& E) {
;     ...
;             PG8_LDB(B0, 0, 0); PG8_LDB(B1, 0, 1); PG8_SCHED; PG8_LDA(At, 0, 0); PG8_STAGE(PG8_SA(1, 1), a1 + hstep, voffA);
;             PG8_WAIT_V(8); PG8_WAIT_L(0); PG8_BAR; PG8_MMA(0, 0, At, B0); PG8_MMA(0, 1, At, B1); PG8_BAR; PG8_SCHED;
;             PG8_LDA(At, 0, 1); PG8_STAGE(PG8_SB(0, 0), b2, voffB); PG8_STAGE(PG8_SB(0, 1), b2 + hstep, voffB); PG8_STAGE(PG8_SA(0, 0), a2, voffA);
;             PG8_WAIT_V(8); PG8_WAIT_L(0); PG8_BAR; PG8_MMA(1, 0, At, B0); PG8_MMA(1, 1, At, B1); PG8_BAR; PG8_SCHED;
.LBB0_192:
	ds_read_b128 v[152:155], v149
	ds_read_b128 v[156:159], v149 offset:1024
	ds_read_b128 v[160:163], v149 offset:2048
	ds_read_b128 v[164:167], v149 offset:3072
	ds_read_b128 v[168:171], v150
	ds_read_b128 v[172:175], v150 offset:1024
	ds_read_b128 v[176:179], v150 offset:2048
	ds_read_b128 v[182:185], v150 offset:3072
	s_add_u32 s44, s42, 0xfffc0080
	s_addc_u32 s45, s43, -1
	s_cmp_eq_u32 s92, 12
	s_cselect_b32 s47, s23, s45
	s_cselect_b32 s46, s88, s44
	s_cselect_b32 s45, s21, s91
	s_cselect_b32 s44, s89, s90
	v_lshl_add_u64 v[144:145], s[42:43], 0, v[136:137]
	s_add_i32 m0, s41, 0xc000
	ds_read_b128 v[186:189], v151
	ds_read_b128 v[192:195], v151 offset:1024
	ds_read_b128 v[196:199], v151 offset:2048
	ds_read_b128 v[200:203], v151 offset:3072
	ds_read_b128 v[204:207], v151 offset:4096
	ds_read_b128 v[208:211], v151 offset:5120
	ds_read_b128 v[212:215], v151 offset:6144
	ds_read_b128 v[216:219], v151 offset:7168
	global_load_lds_dwordx4 v[144:145], off
	v_lshl_add_u64 v[144:145], s[42:43], 0, v[138:139]
	s_add_i32 m0, s41, 0xe000
	s_nop 0
	global_load_lds_dwordx4 v[144:145], off
	s_waitcnt vmcnt(8)
	s_waitcnt lgkmcnt(0)
	s_barrier
	s_setprio 1
	s_waitcnt lgkmcnt(0)
	v_mfma_f32_16x16x32_bf16 v[124:127], v[152:155], v[186:189], v[124:127]
	v_mfma_f32_16x16x32_bf16 v[116:119], v[160:163], v[186:189], v[116:119]
	v_mfma_f32_16x16x32_bf16 v[108:111], v[152:155], v[196:199], v[108:111]
	v_mfma_f32_16x16x32_bf16 v[100:103], v[160:163], v[196:199], v[100:103]
	v_mfma_f32_16x16x32_bf16 v[92:95], v[152:155], v[204:207], v[92:95]
	v_mfma_f32_16x16x32_bf16 v[84:87], v[160:163], v[204:207], v[84:87]
	v_mfma_f32_16x16x32_bf16 v[76:79], v[152:155], v[212:215], v[76:79]
	v_mfma_f32_16x16x32_bf16 v[68:71], v[160:163], v[212:215], v[68:71]
	v_mfma_f32_16x16x32_bf16 v[124:127], v[156:159], v[192:195], v[124:127]
	v_mfma_f32_16x16x32_bf16 v[116:119], v[164:167], v[192:195], v[116:119]
	v_mfma_f32_16x16x32_bf16 v[108:111], v[156:159], v[200:203], v[108:111]
	v_mfma_f32_16x16x32_bf16 v[100:103], v[164:167], v[200:203], v[100:103]
	v_mfma_f32_16x16x32_bf16 v[92:95], v[156:159], v[208:211], v[92:95]
	v_mfma_f32_16x16x32_bf16 v[84:87], v[164:167], v[208:211], v[84:87]
	v_mfma_f32_16x16x32_bf16 v[76:79], v[156:159], v[216:219], v[76:79]
	v_mfma_f32_16x16x32_bf16 v[68:71], v[164:167], v[216:219], v[68:71]
	s_setprio 0
	s_setprio 1
	v_mfma_f32_16x16x32_bf16 v[120:123], v[168:171], v[186:189], v[120:123]
	v_mfma_f32_16x16x32_bf16 v[112:115], v[176:179], v[186:189], v[112:115]
	v_mfma_f32_16x16x32_bf16 v[104:107], v[168:171], v[196:199], v[104:107]
	v_mfma_f32_16x16x32_bf16 v[96:99], v[176:179], v[196:199], v[96:99]
	v_mfma_f32_16x16x32_bf16 v[88:91], v[168:171], v[204:207], v[88:91]
	v_mfma_f32_16x16x32_bf16 v[80:83], v[176:179], v[204:207], v[80:83]
	v_mfma_f32_16x16x32_bf16 v[72:75], v[168:171], v[212:215], v[72:75]
	v_mfma_f32_16x16x32_bf16 v[64:67], v[176:179], v[212:215], v[64:67]
	v_mfma_f32_16x16x32_bf16 v[120:123], v[172:175], v[192:195], v[120:123]
	v_mfma_f32_16x16x32_bf16 v[112:115], v[182:185], v[192:195], v[112:115]
	v_mfma_f32_16x16x32_bf16 v[104:107], v[172:175], v[200:203], v[104:107]
	v_mfma_f32_16x16x32_bf16 v[96:99], v[182:185], v[200:203], v[96:99]
	v_mfma_f32_16x16x32_bf16 v[88:91], v[172:175], v[208:211], v[88:91]
	v_mfma_f32_16x16x32_bf16 v[80:83], v[182:185], v[208:211], v[80:83]
	v_mfma_f32_16x16x32_bf16 v[72:75], v[172:175], v[216:219], v[72:75]
	v_mfma_f32_16x16x32_bf16 v[64:67], v[182:185], v[216:219], v[64:67]
	s_setprio 0
	s_barrier
	s_sleep 1
	s_add_i32 s93, s84, s48
	v_lshl_add_u64 v[144:145], s[44:45], 0, v[132:133]
	s_mov_b32 m0, s93
	ds_read_b128 v[186:189], v151 offset:16384
	ds_read_b128 v[192:195], v151 offset:17408
	ds_read_b128 v[196:199], v151 offset:18432
	ds_read_b128 v[200:203], v151 offset:19456
	ds_read_b128 v[204:207], v151 offset:20480
	ds_read_b128 v[208:211], v151 offset:21504
	ds_read_b128 v[212:215], v151 offset:22528
	ds_read_b128 v[216:219], v151 offset:23552
	global_load_lds_dwordx4 v[144:145], off
	s_add_i32 m0, s93, 0x2000
	s_add_u32 s94, s44, 0x40000
	v_lshl_add_u64 v[220:221], s[44:45], 0, v[128:129]
	s_addc_u32 s95, s45, 0
	s_add_i32 s93, s85, s48
	global_load_lds_dwordx4 v[220:221], off
	v_lshl_add_u64 v[222:223], s[94:95], 0, v[132:133]
	s_mov_b32 m0, s93
	v_lshl_add_u64 v[224:225], s[46:47], 0, v[130:131]
	global_load_lds_dwordx4 v[222:223], off
	v_lshl_add_u64 v[222:223], s[94:95], 0, v[128:129]
	s_add_i32 m0, s93, 0x2000
	s_nop 0
	global_load_lds_dwordx4 v[222:223], off
	v_lshl_add_u64 v[222:223], s[46:47], 0, v[134:135]
	s_mov_b32 m0, s41
	s_nop 0
	global_load_lds_dwordx4 v[222:223], off
	s_mov_b32 m0, s61
	s_nop 0
	global_load_lds_dwordx4 v[224:225], off
	s_waitcnt vmcnt(8)
	s_waitcnt lgkmcnt(0)
	s_barrier
; #define PG8_STAGE(bufoff, gbase, voff) do { _Pragma("unroll") for (int _i = 0; _i < 2; ++_i) \
;         __builtin_amdgcn_global_load_lds((const unsigned*)((const char*)(gbase) + (voff)[_i]), (PG8_LAS unsigned*)(lds + (bufoff) + ldsw + _i * 8192), 16, 0, 0); } while (0)
; #define PG8_LDA(dst, b, h) do { _Pragma("unroll") for (int m = 0; m < 4; ++m) _Pragma("unroll") for (int k = 0; k < 2; ++k) dst[m][k] = *(const PG8_LAS bf16x8*)(lds + PG8_SA(b, h) + aoff + m * 2048 + k * 1024); } while (0)
; #define PG8_LDB(dst, b, h) do { _Pragma("unroll") for (int n = 0; n < 2; ++n) _Pragma("unroll") for (int k = 0; k < 2; ++k) dst[n][k] = *(const PG8_LAS bf16x8*)(lds + PG8_SB(b, h) + boff + n * 2048 + k * 1024); } while (0)
; #define PG8_MMA(ai, bj, At, Bt) do { __builtin_amdgcn_s_setprio(1); _Pragma("unroll") for (int m = 0; m < 4; ++m) _Pragma("unroll") for (int n = 0; n < 2; ++n) _Pragma("unroll") for (int k = 0; k < 2; ++k) \
;         acc[ai][bj][m][n] = __builtin_amdgcn_mfma_f32_16x16x32_bf16(Bt[n][k], At[m][k], acc[ai][bj][m][n], 0, 0, 0); __builtin_amdgcn_s_setprio(0); } while (0)
; #define PG8_WAIT_V(n) asm volatile("s_waitcnt vmcnt(" #n ")" ::: "memory")
; #define PG8_WAIT_L(n) asm volatile("s_waitcnt lgkmcnt(" #n ")" ::: "memory")
; #define PG8_BAR __builtin_amdgcn_s_barrier()
; #define PG8_SCHED __builtin_amdgcn_sched_barrier(0)
; template <class Epi, class Sched, bool ALIGN_EPI = false, bool SP2 = false>
; __device__ __forceinline__ void gemm_phase(PG8_LAS unsigned char* lds, const Gemm g, const Sched& S, const Epi& E) {
;     ...
;             PG8_WAIT_V(8); PG8_WAIT_L(0); PG8_BAR; PG8_MMA(1, 0, At, B0); PG8_MMA(1, 1, At, B1); PG8_BAR; PG8_SCHED;
;             PG8_LDB(B0, 1, 0); PG8_LDB(B1, 1, 1); PG8_SCHED; PG8_LDA(At, 1, 0); PG8_STAGE(PG8_SA(0, 1), a2 + hstep, voffA);
;             PG8_WAIT_V(8); PG8_WAIT_L(0); PG8_BAR; PG8_MMA(0, 0, At, B0); PG8_MMA(0, 1, At, B1); PG8_BAR; PG8_SCHED;
	s_setprio 1
	s_waitcnt lgkmcnt(0)
	v_mfma_f32_16x16x32_bf16 v[60:63], v[152:155], v[186:189], v[60:63]
	v_mfma_f32_16x16x32_bf16 v[52:55], v[160:163], v[186:189], v[52:55]
	v_mfma_f32_16x16x32_bf16 v[44:47], v[152:155], v[196:199], v[44:47]
	v_mfma_f32_16x16x32_bf16 v[36:39], v[160:163], v[196:199], v[36:39]
	v_mfma_f32_16x16x32_bf16 v[28:31], v[152:155], v[204:207], v[28:31]
	v_mfma_f32_16x16x32_bf16 v[20:23], v[160:163], v[204:207], v[20:23]
	v_mfma_f32_16x16x32_bf16 v[12:15], v[152:155], v[212:215], v[12:15]
	v_mfma_f32_16x16x32_bf16 v[4:7], v[160:163], v[212:215], v[4:7]
	v_mfma_f32_16x16x32_bf16 v[60:63], v[156:159], v[192:195], v[60:63]
	v_mfma_f32_16x16x32_bf16 v[52:55], v[164:167], v[192:195], v[52:55]
	v_mfma_f32_16x16x32_bf16 v[44:47], v[156:159], v[200:203], v[44:47]
	v_mfma_f32_16x16x32_bf16 v[36:39], v[164:167], v[200:203], v[36:39]
	v_mfma_f32_16x16x32_bf16 v[28:31], v[156:159], v[208:211], v[28:31]
	v_mfma_f32_16x16x32_bf16 v[20:23], v[164:167], v[208:211], v[20:23]
	v_mfma_f32_16x16x32_bf16 v[12:15], v[156:159], v[216:219], v[12:15]
	v_mfma_f32_16x16x32_bf16 v[4:7], v[164:167], v[216:219], v[4:7]
	s_setprio 0
	s_setprio 1
	v_mfma_f32_16x16x32_bf16 v[56:59], v[168:171], v[186:189], v[56:59]
	v_mfma_f32_16x16x32_bf16 v[48:51], v[176:179], v[186:189], v[48:51]
	v_mfma_f32_16x16x32_bf16 v[40:43], v[168:171], v[196:199], v[40:43]
	v_mfma_f32_16x16x32_bf16 v[32:35], v[176:179], v[196:199], v[32:35]
	v_mfma_f32_16x16x32_bf16 v[24:27], v[168:171], v[204:207], v[24:27]
	v_mfma_f32_16x16x32_bf16 v[16:19], v[176:179], v[204:207], v[16:19]
	v_mfma_f32_16x16x32_bf16 v[8:11], v[168:171], v[212:215], v[8:11]
	v_mfma_f32_16x16x32_bf16 v[0:3], v[176:179], v[212:215], v[0:3]
	v_mfma_f32_16x16x32_bf16 v[56:59], v[172:175], v[192:195], v[56:59]
	v_mfma_f32_16x16x32_bf16 v[48:51], v[182:185], v[192:195], v[48:51]
	v_mfma_f32_16x16x32_bf16 v[40:43], v[172:175], v[200:203], v[40:43]
	v_mfma_f32_16x16x32_bf16 v[32:35], v[182:185], v[200:203], v[32:35]
	v_mfma_f32_16x16x32_bf16 v[24:27], v[172:175], v[208:211], v[24:27]
	v_mfma_f32_16x16x32_bf16 v[16:19], v[182:185], v[208:211], v[16:19]
	v_mfma_f32_16x16x32_bf16 v[8:11], v[172:175], v[216:219], v[8:11]
	v_mfma_f32_16x16x32_bf16 v[0:3], v[182:185], v[216:219], v[0:3]
	s_setprio 0
	s_barrier
	s_sleep 1
	s_add_i32 s93, 0, 0x18000
	s_add_i32 s94, 0, 0x1c000
	v_add_u32_e32 v164, s93, v147
	v_add_u32_e32 v181, s94, v147
	ds_read_b128 v[152:155], v164
	ds_read_b128 v[156:159], v164 offset:1024
	ds_read_b128 v[160:163], v164 offset:2048
	ds_read_b128 v[164:167], v164 offset:3072
	ds_read_b128 v[168:171], v181
	ds_read_b128 v[172:175], v181 offset:1024
	ds_read_b128 v[176:179], v181 offset:2048
	ds_read_b128 v[182:185], v181 offset:3072
	s_add_u32 s46, s46, 0x40000
	s_addc_u32 s47, s47, 0
	s_mov_b32 m0, s78
	v_lshl_add_u64 v[226:227], s[46:47], 0, v[134:135]
	ds_read_b128 v[186:189], v151 offset:32768
	ds_read_b128 v[192:195], v151 offset:33792
	ds_read_b128 v[196:199], v151 offset:34816
	ds_read_b128 v[200:203], v151 offset:35840
	ds_read_b128 v[204:207], v151 offset:36864
	ds_read_b128 v[208:211], v151 offset:37888
	ds_read_b128 v[212:215], v151 offset:38912
	ds_read_b128 v[216:219], v151 offset:39936
	global_load_lds_dwordx4 v[226:227], off
	v_lshl_add_u64 v[226:227], s[46:47], 0, v[130:131]
	s_mov_b32 m0, s79
	s_nop 0
	global_load_lds_dwordx4 v[226:227], off
	s_waitcnt vmcnt(8)
	s_waitcnt lgkmcnt(0)
	s_barrier
	s_setprio 1
	s_waitcnt lgkmcnt(0)
	v_mfma_f32_16x16x32_bf16 v[124:127], v[152:155], v[186:189], v[124:127]
	v_mfma_f32_16x16x32_bf16 v[116:119], v[160:163], v[186:189], v[116:119]
	v_mfma_f32_16x16x32_bf16 v[108:111], v[152:155], v[196:199], v[108:111]
	v_mfma_f32_16x16x32_bf16 v[100:103], v[160:163], v[196:199], v[100:103]
	v_mfma_f32_16x16x32_bf16 v[92:95], v[152:155], v[204:207], v[92:95]
	v_mfma_f32_16x16x32_bf16 v[84:87], v[160:163], v[204:207], v[84:87]
	v_mfma_f32_16x16x32_bf16 v[76:79], v[152:155], v[212:215], v[76:79]
	v_mfma_f32_16x16x32_bf16 v[68:71], v[160:163], v[212:215], v[68:71]
	v_mfma_f32_16x16x32_bf16 v[124:127], v[156:159], v[192:195], v[124:127]
	v_mfma_f32_16x16x32_bf16 v[116:119], v[164:167], v[192:195], v[116:119]
	v_mfma_f32_16x16x32_bf16 v[108:111], v[156:159], v[200:203], v[108:111]
	v_mfma_f32_16x16x32_bf16 v[100:103], v[164:167], v[200:203], v[100:103]
	v_mfma_f32_16x16x32_bf16 v[92:95], v[156:159], v[208:211], v[92:95]
	v_mfma_f32_16x16x32_bf16 v[84:87], v[164:167], v[208:211], v[84:87]
	v_mfma_f32_16x16x32_bf16 v[76:79], v[156:159], v[216:219], v[76:79]
	v_mfma_f32_16x16x32_bf16 v[68:71], v[164:167], v[216:219], v[68:71]
	s_setprio 0
	s_setprio 1
	v_mfma_f32_16x16x32_bf16 v[120:123], v[168:171], v[186:189], v[120:123]
	v_mfma_f32_16x16x32_bf16 v[112:115], v[176:179], v[186:189], v[112:115]
	v_mfma_f32_16x16x32_bf16 v[104:107], v[168:171], v[196:199], v[104:107]
	v_mfma_f32_16x16x32_bf16 v[96:99], v[176:179], v[196:199], v[96:99]
	v_mfma_f32_16x16x32_bf16 v[88:91], v[168:171], v[204:207], v[88:91]
	v_mfma_f32_16x16x32_bf16 v[80:83], v[176:179], v[204:207], v[80:83]
	v_mfma_f32_16x16x32_bf16 v[72:75], v[168:171], v[212:215], v[72:75]
	v_mfma_f32_16x16x32_bf16 v[64:67], v[176:179], v[212:215], v[64:67]
	v_mfma_f32_16x16x32_bf16 v[120:123], v[172:175], v[192:195], v[120:123]
	v_mfma_f32_16x16x32_bf16 v[112:115], v[182:185], v[192:195], v[112:115]
	v_mfma_f32_16x16x32_bf16 v[104:107], v[172:175], v[200:203], v[104:107]
	v_mfma_f32_16x16x32_bf16 v[96:99], v[182:185], v[200:203], v[96:99]
	v_mfma_f32_16x16x32_bf16 v[88:91], v[172:175], v[208:211], v[88:91]
	v_mfma_f32_16x16x32_bf16 v[80:83], v[182:185], v[208:211], v[80:83]
	v_mfma_f32_16x16x32_bf16 v[72:75], v[172:175], v[216:219], v[72:75]
	v_mfma_f32_16x16x32_bf16 v[64:67], v[182:185], v[216:219], v[64:67]
	s_setprio 0
	s_barrier
; #define PG8_STAGE(bufoff, gbase, voff) do { _Pragma("unroll") for (int _i = 0; _i < 2; ++_i) \
;         __builtin_amdgcn_global_load_lds((const unsigned*)((const char*)(gbase) + (voff)[_i]), (PG8_LAS unsigned*)(lds + (bufoff) + ldsw + _i * 8192), 16, 0, 0); } while (0)
; #define PG8_LDA(dst, b, h) do { _Pragma("unroll") for (int m = 0; m < 4; ++m) _Pragma("unroll") for (int k = 0; k < 2; ++k) dst[m][k] = *(const PG8_LAS bf16x8*)(lds + PG8_SA(b, h) + aoff + m * 2048 + k * 1024); } while (0)
; #define PG8_MMA(ai, bj, At, Bt) do { __builtin_amdgcn_s_setprio(1); _Pragma("unroll") for (int m = 0; m < 4; ++m) _Pragma("unroll") for (int n = 0; n < 2; ++n) _Pragma("unroll") for (int k = 0; k < 2; ++k) \
;         acc[ai][bj][m][n] = __builtin_amdgcn_mfma_f32_16x16x32_bf16(Bt[n][k], At[m][k], acc[ai][bj][m][n], 0, 0, 0); __builtin_amdgcn_s_setprio(0); } while (0)
; #define PG8_WAIT_V(n) asm volatile("s_waitcnt vmcnt(" #n ")" ::: "memory")
; #define PG8_WAIT_L(n) asm volatile("s_waitcnt lgkmcnt(" #n ")" ::: "memory")
; #define PG8_BAR __builtin_amdgcn_s_barrier()
; #define PG8_SCHED __builtin_amdgcn_sched_barrier(0)
; template <class Epi, class Sched, bool ALIGN_EPI = false, bool SP2 = false>
; __device__ __forceinline__ void gemm_phase(PG8_LAS unsigned char* lds, const Gemm g, const Sched& S, const Epi& E) {
;     ...
;             PG8_LDA(At, 1, 1); PG8_STAGE(PG8_SB(1, 0), b3, voffB); PG8_STAGE(PG8_SB(1, 1), b3 + hstep, voffB); PG8_STAGE(PG8_SA(1, 0), a3, voffA);
;             PG8_WAIT_V(8); PG8_WAIT_L(0); PG8_BAR; PG8_MMA(1, 0, At, B0); PG8_MMA(1, 1, At, B1); PG8_BAR; PG8_SCHED;
	s_sleep 1
	s_add_i32 s46, s93, s48
	v_lshl_add_u64 v[144:145], v[144:145], 0, s[6:7]
	s_mov_b32 m0, s46
	ds_read_b128 v[186:189], v151 offset:49152
	ds_read_b128 v[192:195], v151 offset:50176
	ds_read_b128 v[196:199], v151 offset:51200
	ds_read_b128 v[200:203], v151 offset:52224
	ds_read_b128 v[204:207], v151 offset:53248
	ds_read_b128 v[208:211], v151 offset:54272
	ds_read_b128 v[212:215], v151 offset:55296
	ds_read_b128 v[216:219], v151 offset:56320
	global_load_lds_dwordx4 v[144:145], off
	s_add_i32 m0, s46, 0x2000
	s_add_u32 s44, s44, 0x40080
	v_lshl_add_u64 v[144:145], v[220:221], 0, s[6:7]
	s_addc_u32 s45, s45, 0
	s_add_i32 s46, s94, s48
	global_load_lds_dwordx4 v[144:145], off
	v_lshl_add_u64 v[144:145], s[44:45], 0, v[132:133]
	s_mov_b32 m0, s46
	s_nop 0
	global_load_lds_dwordx4 v[144:145], off
	v_lshl_add_u64 v[144:145], s[44:45], 0, v[128:129]
	s_add_i32 m0, s46, 0x2000
	s_nop 0
	global_load_lds_dwordx4 v[144:145], off
	v_lshl_add_u64 v[144:145], v[222:223], 0, s[6:7]
	s_mov_b32 m0, s81
	s_nop 0
	global_load_lds_dwordx4 v[144:145], off
	v_lshl_add_u64 v[144:145], v[224:225], 0, s[6:7]
	s_mov_b32 m0, s82
	s_nop 0
	global_load_lds_dwordx4 v[144:145], off
	s_waitcnt vmcnt(8)
	s_waitcnt lgkmcnt(0)
	s_barrier
	s_setprio 1
	s_waitcnt lgkmcnt(0)
	v_mfma_f32_16x16x32_bf16 v[60:63], v[152:155], v[186:189], v[60:63]
	v_mfma_f32_16x16x32_bf16 v[52:55], v[160:163], v[186:189], v[52:55]
	v_mfma_f32_16x16x32_bf16 v[44:47], v[152:155], v[196:199], v[44:47]
	v_mfma_f32_16x16x32_bf16 v[36:39], v[160:163], v[196:199], v[36:39]
	v_mfma_f32_16x16x32_bf16 v[28:31], v[152:155], v[204:207], v[28:31]
	v_mfma_f32_16x16x32_bf16 v[20:23], v[160:163], v[204:207], v[20:23]
	v_mfma_f32_16x16x32_bf16 v[12:15], v[152:155], v[212:215], v[12:15]
	v_mfma_f32_16x16x32_bf16 v[4:7], v[160:163], v[212:215], v[4:7]
	v_mfma_f32_16x16x32_bf16 v[60:63], v[156:159], v[192:195], v[60:63]
	v_mfma_f32_16x16x32_bf16 v[52:55], v[164:167], v[192:195], v[52:55]
	v_mfma_f32_16x16x32_bf16 v[44:47], v[156:159], v[200:203], v[44:47]
	v_mfma_f32_16x16x32_bf16 v[36:39], v[164:167], v[200:203], v[36:39]
	v_mfma_f32_16x16x32_bf16 v[28:31], v[156:159], v[208:211], v[28:31]
	v_mfma_f32_16x16x32_bf16 v[20:23], v[164:167], v[208:211], v[20:23]
	v_mfma_f32_16x16x32_bf16 v[12:15], v[156:159], v[216:219], v[12:15]
	v_mfma_f32_16x16x32_bf16 v[4:7], v[164:167], v[216:219], v[4:7]
	s_setprio 0
	s_setprio 1
	v_mfma_f32_16x16x32_bf16 v[56:59], v[168:171], v[186:189], v[56:59]
	v_mfma_f32_16x16x32_bf16 v[48:51], v[176:179], v[186:189], v[48:51]
	v_mfma_f32_16x16x32_bf16 v[40:43], v[168:171], v[196:199], v[40:43]
	v_mfma_f32_16x16x32_bf16 v[32:35], v[176:179], v[196:199], v[32:35]
	v_mfma_f32_16x16x32_bf16 v[24:27], v[168:171], v[204:207], v[24:27]
	v_mfma_f32_16x16x32_bf16 v[16:19], v[176:179], v[204:207], v[16:19]
	v_mfma_f32_16x16x32_bf16 v[8:11], v[168:171], v[212:215], v[8:11]
	v_mfma_f32_16x16x32_bf16 v[0:3], v[176:179], v[212:215], v[0:3]
	v_mfma_f32_16x16x32_bf16 v[56:59], v[172:175], v[192:195], v[56:59]
	v_mfma_f32_16x16x32_bf16 v[48:51], v[182:185], v[192:195], v[48:51]
	v_mfma_f32_16x16x32_bf16 v[40:43], v[172:175], v[200:203], v[40:43]
	v_mfma_f32_16x16x32_bf16 v[32:35], v[182:185], v[200:203], v[32:35]
	v_mfma_f32_16x16x32_bf16 v[24:27], v[172:175], v[208:211], v[24:27]
	v_mfma_f32_16x16x32_bf16 v[16:19], v[182:185], v[208:211], v[16:19]
	v_mfma_f32_16x16x32_bf16 v[8:11], v[172:175], v[216:219], v[8:11]
	v_mfma_f32_16x16x32_bf16 v[0:3], v[182:185], v[216:219], v[0:3]
	s_setprio 0
	s_barrier
	s_sleep 1
	s_add_i32 s92, s92, 2
	s_add_u32 s42, s42, 0x100
	s_addc_u32 s43, s43, 0
	s_add_u32 s90, s90, 0x100
	s_addc_u32 s91, s91, 0
	s_cmp_gt_u32 s92, 13
	s_cbranch_scc0 .LBB0_192
	s_and_b64 vcc, exec, s[18:19]
	s_cbranch_vccz .LBB0_195
	s_barrier

; #define PG8_STAGE(bufoff, gbase, voff) do { _Pragma("unroll") for (int _i = 0; _i < 2; ++_i) \
;         __builtin_amdgcn_global_load_lds((const unsigned*)((const char*)(gbase) + (voff)[_i]), (PG8_LAS unsigned*)(lds + (bufoff) + ldsw + _i * 8192), 16, 0, 0); } while (0)
; #define PG8_LDA(dst, b, h) do { _Pragma("unroll") for (int m = 0; m < 4; ++m) _Pragma("unroll") for (int k = 0; k < 2; ++k) dst[m][k] = *(const PG8_LAS bf16x8*)(lds + PG8_SA(b, h) + aoff + m * 2048 + k * 1024); } while (0)
; #define PG8_LDB(dst, b, h) do { _Pragma("unroll") for (int n = 0; n < 2; ++n) _Pragma("unroll") for (int k = 0; k < 2; ++k) dst[n][k] = *(const PG8_LAS bf16x8*)(lds + PG8_SB(b, h) + boff + n * 2048 + k * 1024); } while (0)
; #define PG8_MMA(ai, bj, At, Bt) do { __builtin_amdgcn_s_setprio(1); _Pragma("unroll") for (int m = 0; m < 4; ++m) _Pragma("unroll") for (int n = 0; n < 2; ++n) _Pragma("unroll") for (int k = 0; k < 2; ++k) \
;         acc[ai][bj][m][n] = __builtin_amdgcn_mfma_f32_16x16x32_bf16(Bt[n][k], At[m][k], acc[ai][bj][m][n], 0, 0, 0); __builtin_amdgcn_s_setprio(0); } while (0)
; #define PG8_WAIT_V(n) asm volatile("s_waitcnt vmcnt(" #n ")" ::: "memory")
; #define PG8_WAIT_L(n) asm volatile("s_waitcnt lgkmcnt(" #n ")" ::: "memory")
; #define PG8_BAR __builtin_amdgcn_s_barrier()
; #define PG8_SCHED __builtin_amdgcn_sched_barrier(0)
; template <class Epi, class Sched, bool ALIGN_EPI = false, bool SP2 = false>
; __device__ __forceinline__ void gemm_phase(PG8_LAS unsigned char* lds, const Gemm g, const Sched& S, const Epi& E) {
;     ...
;             PG8_LDB(B0, 0, 0); PG8_LDB(B1, 0, 1); PG8_SCHED; PG8_LDA(At, 0, 0); PG8_STAGE(PG8_SA(1, 1), a1 + hstep, voffA);
;             PG8_WAIT_V(8); PG8_WAIT_L(0); PG8_BAR; PG8_MMA(0, 0, At, B0); PG8_MMA(0, 1, At, B1); PG8_BAR; PG8_SCHED;
;             PG8_LDA(At, 0, 1); PG8_STAGE(PG8_SB(0, 0), b2, voffB); PG8_STAGE(PG8_SB(0, 1), b2 + hstep, voffB); PG8_STAGE(PG8_SA(0, 0), a2, voffA);
;             PG8_WAIT_V(8); PG8_WAIT_L(0); PG8_BAR; PG8_MMA(1, 0, At, B0); PG8_MMA(1, 1, At, B1); PG8_BAR; PG8_SCHED;
.LBB0_266:
	ds_read_b128 v[128:131], v171
	ds_read_b128 v[132:135], v171 offset:1024
	ds_read_b128 v[136:139], v171 offset:2048
	ds_read_b128 v[140:143], v171 offset:3072
	ds_read_b128 v[160:163], v172
	ds_read_b128 v[164:167], v172 offset:1024
	ds_read_b128 v[176:179], v172 offset:2048
	ds_read_b128 v[182:185], v172 offset:3072
	s_add_u32 s22, s20, 0xfff50080
	s_addc_u32 s23, s21, -1
	s_cmp_eq_u32 s86, 40
	s_cselect_b32 s25, s1, s23
	s_cselect_b32 s24, s0, s22
	s_cselect_b32 s23, s7, s85
	s_cselect_b32 s22, s6, s84
	v_lshl_add_u64 v[220:221], s[20:21], 0, v[152:153]
	s_add_i32 m0, s40, 0xc000
	ds_read_b128 v[186:189], v173
	ds_read_b128 v[192:195], v173 offset:1024
	ds_read_b128 v[196:199], v173 offset:2048
	ds_read_b128 v[200:203], v173 offset:3072
	ds_read_b128 v[204:207], v173 offset:4096
	ds_read_b128 v[208:211], v173 offset:5120
	ds_read_b128 v[212:215], v173 offset:6144
	ds_read_b128 v[216:219], v173 offset:7168
	global_load_lds_dwordx4 v[220:221], off
	v_lshl_add_u64 v[220:221], s[20:21], 0, v[154:155]
	s_add_i32 m0, s40, 0xe000
	s_nop 0
	global_load_lds_dwordx4 v[220:221], off
	s_waitcnt vmcnt(8)
	s_waitcnt lgkmcnt(0)
	s_barrier
	s_setprio 1
	s_waitcnt lgkmcnt(0)
	v_mfma_f32_16x16x32_bf16 v[124:127], v[128:131], v[186:189], v[124:127]
	v_mfma_f32_16x16x32_bf16 v[120:123], v[136:139], v[186:189], v[120:123]
	v_mfma_f32_16x16x32_bf16 v[108:111], v[128:131], v[196:199], v[108:111]
	v_mfma_f32_16x16x32_bf16 v[104:107], v[136:139], v[196:199], v[104:107]
	v_mfma_f32_16x16x32_bf16 v[92:95], v[128:131], v[204:207], v[92:95]
	v_mfma_f32_16x16x32_bf16 v[88:91], v[136:139], v[204:207], v[88:91]
	v_mfma_f32_16x16x32_bf16 v[76:79], v[128:131], v[212:215], v[76:79]
	v_mfma_f32_16x16x32_bf16 v[72:75], v[136:139], v[212:215], v[72:75]
	v_mfma_f32_16x16x32_bf16 v[124:127], v[132:135], v[192:195], v[124:127]
	v_mfma_f32_16x16x32_bf16 v[120:123], v[140:143], v[192:195], v[120:123]
	v_mfma_f32_16x16x32_bf16 v[108:111], v[132:135], v[200:203], v[108:111]
	v_mfma_f32_16x16x32_bf16 v[104:107], v[140:143], v[200:203], v[104:107]
	v_mfma_f32_16x16x32_bf16 v[92:95], v[132:135], v[208:211], v[92:95]
	v_mfma_f32_16x16x32_bf16 v[88:91], v[140:143], v[208:211], v[88:91]
	v_mfma_f32_16x16x32_bf16 v[76:79], v[132:135], v[216:219], v[76:79]
	v_mfma_f32_16x16x32_bf16 v[72:75], v[140:143], v[216:219], v[72:75]
	s_setprio 0
	s_setprio 1
	v_mfma_f32_16x16x32_bf16 v[116:119], v[160:163], v[186:189], v[116:119]
	v_mfma_f32_16x16x32_bf16 v[112:115], v[176:179], v[186:189], v[112:115]
	v_mfma_f32_16x16x32_bf16 v[100:103], v[160:163], v[196:199], v[100:103]
	v_mfma_f32_16x16x32_bf16 v[96:99], v[176:179], v[196:199], v[96:99]
	v_mfma_f32_16x16x32_bf16 v[84:87], v[160:163], v[204:207], v[84:87]
	v_mfma_f32_16x16x32_bf16 v[80:83], v[176:179], v[204:207], v[80:83]
	v_mfma_f32_16x16x32_bf16 v[68:71], v[160:163], v[212:215], v[68:71]
	v_mfma_f32_16x16x32_bf16 v[64:67], v[176:179], v[212:215], v[64:67]
	v_mfma_f32_16x16x32_bf16 v[116:119], v[164:167], v[192:195], v[116:119]
	v_mfma_f32_16x16x32_bf16 v[112:115], v[182:185], v[192:195], v[112:115]
	v_mfma_f32_16x16x32_bf16 v[100:103], v[164:167], v[200:203], v[100:103]
	v_mfma_f32_16x16x32_bf16 v[96:99], v[182:185], v[200:203], v[96:99]
	v_mfma_f32_16x16x32_bf16 v[84:87], v[164:167], v[208:211], v[84:87]
	v_mfma_f32_16x16x32_bf16 v[80:83], v[182:185], v[208:211], v[80:83]
	v_mfma_f32_16x16x32_bf16 v[68:71], v[164:167], v[216:219], v[68:71]
	v_mfma_f32_16x16x32_bf16 v[64:67], v[182:185], v[216:219], v[64:67]
	s_setprio 0
	s_barrier
	s_sleep 1
	s_add_i32 s87, s78, s27
	v_lshl_add_u64 v[220:221], s[22:23], 0, v[146:147]
	s_mov_b32 m0, s87
	ds_read_b128 v[186:189], v173 offset:16384
	ds_read_b128 v[192:195], v173 offset:17408
	ds_read_b128 v[196:199], v173 offset:18432
	ds_read_b128 v[200:203], v173 offset:19456
	ds_read_b128 v[204:207], v173 offset:20480
	ds_read_b128 v[208:211], v173 offset:21504
	ds_read_b128 v[212:215], v173 offset:22528
	ds_read_b128 v[216:219], v173 offset:23552
	global_load_lds_dwordx4 v[220:221], off
	s_add_i32 m0, s87, 0x2000
	s_add_u32 s88, s22, 0xb0000
	v_lshl_add_u64 v[222:223], s[22:23], 0, v[150:151]
	s_addc_u32 s89, s23, 0
	s_add_i32 s87, s79, s27
	global_load_lds_dwordx4 v[222:223], off
	v_lshl_add_u64 v[224:225], s[88:89], 0, v[146:147]
	s_mov_b32 m0, s87
	v_lshl_add_u64 v[226:227], s[24:25], 0, v[148:149]
	global_load_lds_dwordx4 v[224:225], off
	v_lshl_add_u64 v[224:225], s[88:89], 0, v[150:151]
	s_add_i32 m0, s87, 0x2000
	s_nop 0
	global_load_lds_dwordx4 v[224:225], off
	v_lshl_add_u64 v[224:225], s[24:25], 0, v[144:145]
	s_mov_b32 m0, s40
	s_nop 0
	global_load_lds_dwordx4 v[224:225], off
	s_mov_b32 m0, s41
	s_nop 0
	global_load_lds_dwordx4 v[226:227], off
	s_waitcnt vmcnt(8)
	s_waitcnt lgkmcnt(0)
	s_barrier
; #define PG8_STAGE(bufoff, gbase, voff) do { _Pragma("unroll") for (int _i = 0; _i < 2; ++_i) \
;         __builtin_amdgcn_global_load_lds((const unsigned*)((const char*)(gbase) + (voff)[_i]), (PG8_LAS unsigned*)(lds + (bufoff) + ldsw + _i * 8192), 16, 0, 0); } while (0)
; #define PG8_LDA(dst, b, h) do { _Pragma("unroll") for (int m = 0; m < 4; ++m) _Pragma("unroll") for (int k = 0; k < 2; ++k) dst[m][k] = *(const PG8_LAS bf16x8*)(lds + PG8_SA(b, h) + aoff + m * 2048 + k * 1024); } while (0)
; #define PG8_LDB(dst, b, h) do { _Pragma("unroll") for (int n = 0; n < 2; ++n) _Pragma("unroll") for (int k = 0; k < 2; ++k) dst[n][k] = *(const PG8_LAS bf16x8*)(lds + PG8_SB(b, h) + boff + n * 2048 + k * 1024); } while (0)
; #define PG8_MMA(ai, bj, At, Bt) do { __builtin_amdgcn_s_setprio(1); _Pragma("unroll") for (int m = 0; m < 4; ++m) _Pragma("unroll") for (int n = 0; n < 2; ++n) _Pragma("unroll") for (int k = 0; k < 2; ++k) \
;         acc[ai][bj][m][n] = __builtin_amdgcn_mfma_f32_16x16x32_bf16(Bt[n][k], At[m][k], acc[ai][bj][m][n], 0, 0, 0); __builtin_amdgcn_s_setprio(0); } while (0)
; #define PG8_WAIT_V(n) asm volatile("s_waitcnt vmcnt(" #n ")" ::: "memory")
; #define PG8_WAIT_L(n) asm volatile("s_waitcnt lgkmcnt(" #n ")" ::: "memory")
; #define PG8_BAR __builtin_amdgcn_s_barrier()
; #define PG8_SCHED __builtin_amdgcn_sched_barrier(0)
; template <class Epi, class Sched, bool ALIGN_EPI = false, bool SP2 = false>
; __device__ __forceinline__ void gemm_phase(PG8_LAS unsigned char* lds, const Gemm g, const Sched& S, const Epi& E) {
;     ...
;             PG8_WAIT_V(8); PG8_WAIT_L(0); PG8_BAR; PG8_MMA(1, 0, At, B0); PG8_MMA(1, 1, At, B1); PG8_BAR; PG8_SCHED;
;             PG8_LDB(B0, 1, 0); PG8_LDB(B1, 1, 1); PG8_SCHED; PG8_LDA(At, 1, 0); PG8_STAGE(PG8_SA(0, 1), a2 + hstep, voffA);
;             PG8_WAIT_V(8); PG8_WAIT_L(0); PG8_BAR; PG8_MMA(0, 0, At, B0); PG8_MMA(0, 1, At, B1); PG8_BAR; PG8_SCHED;
	s_setprio 1
	s_waitcnt lgkmcnt(0)
	v_mfma_f32_16x16x32_bf16 v[60:63], v[128:131], v[186:189], v[60:63]
	v_mfma_f32_16x16x32_bf16 v[56:59], v[136:139], v[186:189], v[56:59]
	v_mfma_f32_16x16x32_bf16 v[44:47], v[128:131], v[196:199], v[44:47]
	v_mfma_f32_16x16x32_bf16 v[40:43], v[136:139], v[196:199], v[40:43]
	v_mfma_f32_16x16x32_bf16 v[28:31], v[128:131], v[204:207], v[28:31]
	v_mfma_f32_16x16x32_bf16 v[24:27], v[136:139], v[204:207], v[24:27]
	v_mfma_f32_16x16x32_bf16 v[12:15], v[128:131], v[212:215], v[12:15]
	v_mfma_f32_16x16x32_bf16 v[8:11], v[136:139], v[212:215], v[8:11]
	v_mfma_f32_16x16x32_bf16 v[60:63], v[132:135], v[192:195], v[60:63]
	v_mfma_f32_16x16x32_bf16 v[56:59], v[140:143], v[192:195], v[56:59]
	v_mfma_f32_16x16x32_bf16 v[44:47], v[132:135], v[200:203], v[44:47]
	v_mfma_f32_16x16x32_bf16 v[40:43], v[140:143], v[200:203], v[40:43]
	v_mfma_f32_16x16x32_bf16 v[28:31], v[132:135], v[208:211], v[28:31]
	v_mfma_f32_16x16x32_bf16 v[24:27], v[140:143], v[208:211], v[24:27]
	v_mfma_f32_16x16x32_bf16 v[12:15], v[132:135], v[216:219], v[12:15]
	v_mfma_f32_16x16x32_bf16 v[8:11], v[140:143], v[216:219], v[8:11]
	s_setprio 0
	s_setprio 1
	v_mfma_f32_16x16x32_bf16 v[52:55], v[160:163], v[186:189], v[52:55]
	v_mfma_f32_16x16x32_bf16 v[48:51], v[176:179], v[186:189], v[48:51]
	v_mfma_f32_16x16x32_bf16 v[36:39], v[160:163], v[196:199], v[36:39]
	v_mfma_f32_16x16x32_bf16 v[32:35], v[176:179], v[196:199], v[32:35]
	v_mfma_f32_16x16x32_bf16 v[20:23], v[160:163], v[204:207], v[20:23]
	v_mfma_f32_16x16x32_bf16 v[16:19], v[176:179], v[204:207], v[16:19]
	v_mfma_f32_16x16x32_bf16 v[4:7], v[160:163], v[212:215], v[4:7]
	v_mfma_f32_16x16x32_bf16 v[0:3], v[176:179], v[212:215], v[0:3]
	v_mfma_f32_16x16x32_bf16 v[52:55], v[164:167], v[192:195], v[52:55]
	v_mfma_f32_16x16x32_bf16 v[48:51], v[182:185], v[192:195], v[48:51]
	v_mfma_f32_16x16x32_bf16 v[36:39], v[164:167], v[200:203], v[36:39]
	v_mfma_f32_16x16x32_bf16 v[32:35], v[182:185], v[200:203], v[32:35]
	v_mfma_f32_16x16x32_bf16 v[20:23], v[164:167], v[208:211], v[20:23]
	v_mfma_f32_16x16x32_bf16 v[16:19], v[182:185], v[208:211], v[16:19]
	v_mfma_f32_16x16x32_bf16 v[4:7], v[164:167], v[216:219], v[4:7]
	v_mfma_f32_16x16x32_bf16 v[0:3], v[182:185], v[216:219], v[0:3]
	s_setprio 0
	s_barrier
	s_sleep 1
	s_add_i32 s87, 0, 0x18000
	s_add_i32 s88, 0, 0x1c000
	v_add_u32_e32 v140, s87, v169
	v_add_u32_e32 v175, s88, v169
	ds_read_b128 v[128:131], v140
	ds_read_b128 v[132:135], v140 offset:1024
	ds_read_b128 v[136:139], v140 offset:2048
	ds_read_b128 v[140:143], v140 offset:3072
	ds_read_b128 v[160:163], v175
	ds_read_b128 v[164:167], v175 offset:1024
	ds_read_b128 v[176:179], v175 offset:2048
	ds_read_b128 v[182:185], v175 offset:3072
	s_add_u32 s24, s24, 0xb0000
	s_addc_u32 s25, s25, 0
	s_mov_b32 m0, s42
	v_lshl_add_u64 v[228:229], s[24:25], 0, v[144:145]
	ds_read_b128 v[186:189], v173 offset:32768
	ds_read_b128 v[192:195], v173 offset:33792
	ds_read_b128 v[196:199], v173 offset:34816
	ds_read_b128 v[200:203], v173 offset:35840
	ds_read_b128 v[204:207], v173 offset:36864
	ds_read_b128 v[208:211], v173 offset:37888
	ds_read_b128 v[212:215], v173 offset:38912
	ds_read_b128 v[216:219], v173 offset:39936
	global_load_lds_dwordx4 v[228:229], off
	v_lshl_add_u64 v[228:229], s[24:25], 0, v[148:149]
	s_mov_b32 m0, s43
	s_nop 0
	global_load_lds_dwordx4 v[228:229], off
	s_waitcnt vmcnt(8)
	s_waitcnt lgkmcnt(0)
	s_barrier
	s_setprio 1
	s_waitcnt lgkmcnt(0)
	v_mfma_f32_16x16x32_bf16 v[124:127], v[128:131], v[186:189], v[124:127]
	v_mfma_f32_16x16x32_bf16 v[120:123], v[136:139], v[186:189], v[120:123]
	v_mfma_f32_16x16x32_bf16 v[108:111], v[128:131], v[196:199], v[108:111]
	v_mfma_f32_16x16x32_bf16 v[104:107], v[136:139], v[196:199], v[104:107]
	v_mfma_f32_16x16x32_bf16 v[92:95], v[128:131], v[204:207], v[92:95]
	v_mfma_f32_16x16x32_bf16 v[88:91], v[136:139], v[204:207], v[88:91]
	v_mfma_f32_16x16x32_bf16 v[76:79], v[128:131], v[212:215], v[76:79]
	v_mfma_f32_16x16x32_bf16 v[72:75], v[136:139], v[212:215], v[72:75]
	v_mfma_f32_16x16x32_bf16 v[124:127], v[132:135], v[192:195], v[124:127]
	v_mfma_f32_16x16x32_bf16 v[120:123], v[140:143], v[192:195], v[120:123]
	v_mfma_f32_16x16x32_bf16 v[108:111], v[132:135], v[200:203], v[108:111]
	v_mfma_f32_16x16x32_bf16 v[104:107], v[140:143], v[200:203], v[104:107]
	v_mfma_f32_16x16x32_bf16 v[92:95], v[132:135], v[208:211], v[92:95]
	v_mfma_f32_16x16x32_bf16 v[88:91], v[140:143], v[208:211], v[88:91]
	v_mfma_f32_16x16x32_bf16 v[76:79], v[132:135], v[216:219], v[76:79]
	v_mfma_f32_16x16x32_bf16 v[72:75], v[140:143], v[216:219], v[72:75]
	s_setprio 0
	s_setprio 1
	v_mfma_f32_16x16x32_bf16 v[116:119], v[160:163], v[186:189], v[116:119]
	v_mfma_f32_16x16x32_bf16 v[112:115], v[176:179], v[186:189], v[112:115]
	v_mfma_f32_16x16x32_bf16 v[100:103], v[160:163], v[196:199], v[100:103]
	v_mfma_f32_16x16x32_bf16 v[96:99], v[176:179], v[196:199], v[96:99]
	v_mfma_f32_16x16x32_bf16 v[84:87], v[160:163], v[204:207], v[84:87]
	v_mfma_f32_16x16x32_bf16 v[80:83], v[176:179], v[204:207], v[80:83]
	v_mfma_f32_16x16x32_bf16 v[68:71], v[160:163], v[212:215], v[68:71]
	v_mfma_f32_16x16x32_bf16 v[64:67], v[176:179], v[212:215], v[64:67]
	v_mfma_f32_16x16x32_bf16 v[116:119], v[164:167], v[192:195], v[116:119]
	v_mfma_f32_16x16x32_bf16 v[112:115], v[182:185], v[192:195], v[112:115]
	v_mfma_f32_16x16x32_bf16 v[100:103], v[164:167], v[200:203], v[100:103]
	v_mfma_f32_16x16x32_bf16 v[96:99], v[182:185], v[200:203], v[96:99]
	v_mfma_f32_16x16x32_bf16 v[84:87], v[164:167], v[208:211], v[84:87]
	v_mfma_f32_16x16x32_bf16 v[80:83], v[182:185], v[208:211], v[80:83]
	v_mfma_f32_16x16x32_bf16 v[68:71], v[164:167], v[216:219], v[68:71]
	v_mfma_f32_16x16x32_bf16 v[64:67], v[182:185], v[216:219], v[64:67]
	s_setprio 0
	s_barrier
; #define PG8_STAGE(bufoff, gbase, voff) do { _Pragma("unroll") for (int _i = 0; _i < 2; ++_i) \
;         __builtin_amdgcn_global_load_lds((const unsigned*)((const char*)(gbase) + (voff)[_i]), (PG8_LAS unsigned*)(lds + (bufoff) + ldsw + _i * 8192), 16, 0, 0); } while (0)
; #define PG8_LDA(dst, b, h) do { _Pragma("unroll") for (int m = 0; m < 4; ++m) _Pragma("unroll") for (int k = 0; k < 2; ++k) dst[m][k] = *(const PG8_LAS bf16x8*)(lds + PG8_SA(b, h) + aoff + m * 2048 + k * 1024); } while (0)
; #define PG8_MMA(ai, bj, At, Bt) do { __builtin_amdgcn_s_setprio(1); _Pragma("unroll") for (int m = 0; m < 4; ++m) _Pragma("unroll") for (int n = 0; n < 2; ++n) _Pragma("unroll") for (int k = 0; k < 2; ++k) \
;         acc[ai][bj][m][n] = __builtin_amdgcn_mfma_f32_16x16x32_bf16(Bt[n][k], At[m][k], acc[ai][bj][m][n], 0, 0, 0); __builtin_amdgcn_s_setprio(0); } while (0)
; #define PG8_WAIT_V(n) asm volatile("s_waitcnt vmcnt(" #n ")" ::: "memory")
; #define PG8_WAIT_L(n) asm volatile("s_waitcnt lgkmcnt(" #n ")" ::: "memory")
; #define PG8_BAR __builtin_amdgcn_s_barrier()
; #define PG8_SCHED __builtin_amdgcn_sched_barrier(0)
; template <class Epi, class Sched, bool ALIGN_EPI = false, bool SP2 = false>
; __device__ __forceinline__ void gemm_phase(PG8_LAS unsigned char* lds, const Gemm g, const Sched& S, const Epi& E) {
;     ...
;             PG8_LDA(At, 1, 1); PG8_STAGE(PG8_SB(1, 0), b3, voffB); PG8_STAGE(PG8_SB(1, 1), b3 + hstep, voffB); PG8_STAGE(PG8_SA(1, 0), a3, voffA);
;             PG8_WAIT_V(8); PG8_WAIT_L(0); PG8_BAR; PG8_MMA(1, 0, At, B0); PG8_MMA(1, 1, At, B1); PG8_BAR; PG8_SCHED;
	s_sleep 1
	s_add_i32 s24, s87, s27
	v_lshl_add_u64 v[220:221], v[220:221], 0, s[18:19]
	s_mov_b32 m0, s24
	ds_read_b128 v[186:189], v173 offset:49152
	ds_read_b128 v[192:195], v173 offset:50176
	ds_read_b128 v[196:199], v173 offset:51200
	ds_read_b128 v[200:203], v173 offset:52224
	ds_read_b128 v[204:207], v173 offset:53248
	ds_read_b128 v[208:211], v173 offset:54272
	ds_read_b128 v[212:215], v173 offset:55296
	ds_read_b128 v[216:219], v173 offset:56320
	global_load_lds_dwordx4 v[220:221], off
	s_add_i32 m0, s24, 0x2000
	s_add_u32 s22, s22, 0xb0080
	v_lshl_add_u64 v[220:221], v[222:223], 0, s[18:19]
	s_addc_u32 s23, s23, 0
	s_add_i32 s24, s88, s27
	global_load_lds_dwordx4 v[220:221], off
	v_lshl_add_u64 v[220:221], s[22:23], 0, v[146:147]
	s_mov_b32 m0, s24
	s_nop 0
	global_load_lds_dwordx4 v[220:221], off
	v_lshl_add_u64 v[220:221], s[22:23], 0, v[150:151]
	s_add_i32 m0, s24, 0x2000
	s_nop 0
	global_load_lds_dwordx4 v[220:221], off
	v_lshl_add_u64 v[220:221], v[224:225], 0, s[18:19]
	s_mov_b32 m0, s45
	s_nop 0
	global_load_lds_dwordx4 v[220:221], off
	v_lshl_add_u64 v[220:221], v[226:227], 0, s[18:19]
	s_mov_b32 m0, s46
	s_nop 0
	global_load_lds_dwordx4 v[220:221], off
	s_waitcnt vmcnt(8)
	s_waitcnt lgkmcnt(0)
	s_barrier
	s_setprio 1
	s_waitcnt lgkmcnt(0)
	v_mfma_f32_16x16x32_bf16 v[60:63], v[128:131], v[186:189], v[60:63]
	v_mfma_f32_16x16x32_bf16 v[56:59], v[136:139], v[186:189], v[56:59]
	v_mfma_f32_16x16x32_bf16 v[44:47], v[128:131], v[196:199], v[44:47]
	v_mfma_f32_16x16x32_bf16 v[40:43], v[136:139], v[196:199], v[40:43]
	v_mfma_f32_16x16x32_bf16 v[28:31], v[128:131], v[204:207], v[28:31]
	v_mfma_f32_16x16x32_bf16 v[24:27], v[136:139], v[204:207], v[24:27]
	v_mfma_f32_16x16x32_bf16 v[12:15], v[128:131], v[212:215], v[12:15]
	v_mfma_f32_16x16x32_bf16 v[8:11], v[136:139], v[212:215], v[8:11]
	v_mfma_f32_16x16x32_bf16 v[60:63], v[132:135], v[192:195], v[60:63]
	v_mfma_f32_16x16x32_bf16 v[56:59], v[140:143], v[192:195], v[56:59]
	v_mfma_f32_16x16x32_bf16 v[44:47], v[132:135], v[200:203], v[44:47]
	v_mfma_f32_16x16x32_bf16 v[40:43], v[140:143], v[200:203], v[40:43]
	v_mfma_f32_16x16x32_bf16 v[28:31], v[132:135], v[208:211], v[28:31]
	v_mfma_f32_16x16x32_bf16 v[24:27], v[140:143], v[208:211], v[24:27]
	v_mfma_f32_16x16x32_bf16 v[12:15], v[132:135], v[216:219], v[12:15]
	v_mfma_f32_16x16x32_bf16 v[8:11], v[140:143], v[216:219], v[8:11]
	s_setprio 0
	s_setprio 1
	v_mfma_f32_16x16x32_bf16 v[52:55], v[160:163], v[186:189], v[52:55]
	v_mfma_f32_16x16x32_bf16 v[48:51], v[176:179], v[186:189], v[48:51]
	v_mfma_f32_16x16x32_bf16 v[36:39], v[160:163], v[196:199], v[36:39]
	v_mfma_f32_16x16x32_bf16 v[32:35], v[176:179], v[196:199], v[32:35]
	v_mfma_f32_16x16x32_bf16 v[20:23], v[160:163], v[204:207], v[20:23]
	v_mfma_f32_16x16x32_bf16 v[16:19], v[176:179], v[204:207], v[16:19]
	v_mfma_f32_16x16x32_bf16 v[4:7], v[160:163], v[212:215], v[4:7]
	v_mfma_f32_16x16x32_bf16 v[0:3], v[176:179], v[212:215], v[0:3]
	v_mfma_f32_16x16x32_bf16 v[52:55], v[164:167], v[192:195], v[52:55]
	v_mfma_f32_16x16x32_bf16 v[48:51], v[182:185], v[192:195], v[48:51]
	v_mfma_f32_16x16x32_bf16 v[36:39], v[164:167], v[200:203], v[36:39]
	v_mfma_f32_16x16x32_bf16 v[32:35], v[182:185], v[200:203], v[32:35]
	v_mfma_f32_16x16x32_bf16 v[20:23], v[164:167], v[208:211], v[20:23]
	v_mfma_f32_16x16x32_bf16 v[16:19], v[182:185], v[208:211], v[16:19]
	v_mfma_f32_16x16x32_bf16 v[4:7], v[164:167], v[216:219], v[4:7]
	v_mfma_f32_16x16x32_bf16 v[0:3], v[182:185], v[216:219], v[0:3]
	s_setprio 0
	s_barrier
	s_sleep 1
	s_add_i32 s86, s86, 2
	s_add_u32 s20, s20, 0x100
	s_addc_u32 s21, s21, 0
	s_add_u32 s84, s84, 0x100
	s_addc_u32 s85, s85, 0
	s_cmp_gt_u32 s86, 41
	s_cbranch_scc0 .LBB0_266
; __device__ __forceinline__ u32x2 pack4(f32x4 v) { u32x2 w; w.x = cvt_pk_bf16(v[0], v[1]); w.y = cvt_pk_bf16(v[2], v[3]); return w; }
;     __device__ __forceinline__ void operator()(const f32x4 (&acc)[2][2][4][2], const Unit& u, int wr, int wc, int fr, int fq) const {
;         const int row0 = u.pm * BM + wr * 64 + fr, col0 = u.pn * BM + wc * 32 + 8 * fq;
;         const float* base = (u.pm * BM < split) ? base0 : base1; bf16_t* const xn = (bf16_t*)(ws + WS_XN); float* const ssq = (float*)(ws + WS_SSQ);
; #pragma unroll
;         for (int ai = 0; ai < 2; ++ai)
; #pragma unroll
;         for (int mh = 0; mh < 4; mh += 2) {
;             f32x4 pre[4][2][2];
; #pragma unroll
;             for (int m = mh; m < mh + 2; ++m)
; #pragma unroll
;                 for (int bj = 0; bj < 2; ++bj)
; #pragma unroll
;                     for (int n = 0; n < 2; ++n) pre[m][bj][n] = *(const f32x4*)(base + (size_t)(row0 + ai * HALF + m * 16) * 1024 + col0 + bj * HALF + n * 4);
;             asm volatile("" ::: "memory");
; #pragma unroll
;             for (int m = mh; m < mh + 2; ++m) { const int row = row0 + ai * HALF + m * 16; const size_t off = (size_t)row * 1024 + col0; float ss = 0.f;
; #pragma unroll
;                 for (int bj = 0; bj < 2; ++bj) { u32x4e w;
; #pragma unroll
;                     for (int n = 0; n < 2; ++n) { const f32x4 o = pre[m][bj][n] + acc[ai][bj][m][n] * s;
;                         *(f32x4*)(out + off + bj * HALF + n * 4) = o;
;                         if (NORMOUT) { const u32x2 p = pack4(o); w[2 * n] = p.x; w[2 * n + 1] = p.y; ss += (o[0] * o[0] + o[1] * o[1]) + (o[2] * o[2] + o[3] * o[3]); } }
;                     if (NORMOUT) *(u32x4e*)(xn + off + bj * HALF) = w; }
;                 if (NORMOUT) { ss += __shfl_xor(ss, 16); ss += __shfl_xor(ss, 32); if (fq == 0) ssq[(size_t)row * 16 + u.pn * 4 + wc] = ss; } }
	s_cmpk_lt_i32 s83, 0x80
	v_lshl_add_u32 v162, s83, 8, v168
	v_lshl_or_b32 v160, s82, 8, v170
	s_cselect_b32 s20, s37, s39
	s_cselect_b32 s21, s36, s38
	v_mov_b32_e32 v128, s21
	v_mov_b32_e32 v129, s20
	v_ashrrev_i32_e32 v161, 31, v160
	v_ashrrev_i32_e32 v163, 31, v162
	v_lshl_add_u64 v[164:165], v[160:161], 2, v[128:129]
	v_lshlrev_b64 v[128:129], 12, v[162:163]
	v_lshl_add_u64 v[128:129], v[164:165], 0, v[128:129]
	global_load_dwordx4 v[182:185], v[128:129], off
	global_load_dwordx4 v[186:189], v[128:129], off offset:16
	global_load_dwordx4 v[192:195], v[128:129], off offset:512
	global_load_dwordx4 v[196:199], v[128:129], off offset:528
	v_or_b32_e32 v166, 16, v162
	v_ashrrev_i32_e32 v167, 31, v166
	v_lshlrev_b64 v[128:129], 12, v[166:167]
	v_lshl_add_u64 v[132:133], v[164:165], 0, v[128:129]
	global_load_dwordx4 v[136:139], v[132:133], off offset:16
	global_load_dwordx4 v[140:143], v[132:133], off
	global_load_dwordx4 v[128:131], v[132:133], off offset:528
	s_nop 0
	global_load_dwordx4 v[132:135], v[132:133], off offset:512
	v_and_b32_e32 v176, 64, v174
	v_xor_b32_e32 v175, 16, v174
	v_add_u32_e32 v176, 64, v176
	v_lshlrev_b64 v[178:179], 10, v[162:163]
	v_xor_b32_e32 v177, 32, v174
	v_cmp_lt_i32_e32 vcc, v175, v176
	v_lshl_add_u64 v[178:179], v[178:179], 0, v[160:161]
	v_lshl_add_u64 v[200:201], v[178:179], 1, s[64:65]
	v_cndmask_b32_e32 v175, v174, v175, vcc
	v_cmp_lt_i32_e32 vcc, v177, v176
	v_lshl_add_u64 v[178:179], v[178:179], 2, s[56:57]
	v_lshlrev_b32_e32 v176, 2, v175
	v_cndmask_b32_e32 v177, v174, v177, vcc
	v_lshlrev_b32_e32 v175, 2, v177
	s_lshl_b32 s20, s82, 2
	s_ashr_i32 s21, s20, 31
	s_lshl_b64 s[20:21], s[20:21], 2
	s_add_u32 s20, s49, s20
	s_addc_u32 s21, s60, s21
	s_waitcnt vmcnt(0)
	v_pk_fma_f32 v[126:127], v[126:127], 0.5, v[184:185] op_sel_hi:[1,0,1]
	v_pk_fma_f32 v[124:125], v[124:125], 0.5, v[182:183] op_sel_hi:[1,0,1]
	v_pk_fma_f32 v[122:123], v[122:123], 0.5, v[188:189] op_sel_hi:[1,0,1]
	v_pk_fma_f32 v[120:121], v[120:121], 0.5, v[186:187] op_sel_hi:[1,0,1]
	v_pk_fma_f32 v[118:119], v[118:119], 0.5, v[194:195] op_sel_hi:[1,0,1]
	v_pk_fma_f32 v[116:117], v[116:117], 0.5, v[192:193] op_sel_hi:[1,0,1]
	v_pk_fma_f32 v[184:185], v[114:115], 0.5, v[198:199] op_sel_hi:[1,0,1]
	v_pk_fma_f32 v[182:183], v[112:113], 0.5, v[196:197] op_sel_hi:[1,0,1]
	global_store_dwordx4 v[178:179], v[124:127], off
	v_cvt_pk_bf16_f32 v112, v124, v125
	v_cvt_pk_bf16_f32 v113, v126, v127
	v_mul_f32_e32 v125, v125, v125
	v_mul_f32_e32 v127, v127, v127
	global_store_dwordx4 v[178:179], v[120:123], off offset:16
	v_cvt_pk_bf16_f32 v114, v120, v121
	v_cvt_pk_bf16_f32 v115, v122, v123
	v_mul_f32_e32 v121, v121, v121
	v_mul_f32_e32 v123, v123, v123
	v_mul_f32_e32 v177, v117, v117
	v_mul_f32_e32 v181, v119, v119
	v_fmac_f32_e32 v125, v124, v124
	v_fmac_f32_e32 v127, v126, v126
	v_fmac_f32_e32 v121, v120, v120
	v_fmac_f32_e32 v123, v122, v122
	v_mul_f32_e32 v186, v183, v183
	v_mul_f32_e32 v187, v185, v185
	v_fmac_f32_e32 v177, v116, v116
	v_fmac_f32_e32 v181, v118, v118
	v_add_f32_e32 v120, v125, v127
	v_add_f32_e32 v121, v121, v123
	v_fmac_f32_e32 v186, v182, v182
	v_fmac_f32_e32 v187, v184, v184
	v_add_f32_e32 v122, v177, v181
	v_add_f32_e32 v120, v120, v121
	v_add_f32_e32 v120, v122, v120
	v_add_f32_e32 v121, v186, v187
	v_add_f32_e32 v120, v121, v120
	ds_bpermute_b32 v121, v176, v120
	global_store_dwordx4 v[200:201], v[112:115], off
	global_store_dwordx4 v[178:179], v[116:119], off offset:512
	global_store_dwordx4 v[178:179], v[182:185], off offset:528
	v_cvt_pk_bf16_f32 v114, v116, v117
	v_cvt_pk_bf16_f32 v115, v118, v119
	s_waitcnt lgkmcnt(0)
	v_add_f32_e32 v112, v120, v121
	ds_bpermute_b32 v113, v175, v112
	v_cvt_pk_bf16_f32 v116, v182, v183
	v_cvt_pk_bf16_f32 v117, v184, v185
	global_store_dwordx4 v[200:201], v[114:117], off offset:256
	s_and_saveexec_b64 s[22:23], s[2:3]
	s_cbranch_execz .LBB0_269
	v_lshlrev_b64 v[114:115], 6, v[162:163]
	v_lshl_add_u64 v[114:115], s[20:21], 0, v[114:115]
	s_waitcnt lgkmcnt(0)
	v_add_f32_e32 v112, v112, v113
	global_store_dword v[114:115], v112, off

; #define PG8_STAGE(bufoff, gbase, voff) do { _Pragma("unroll") for (int _i = 0; _i < 2; ++_i) \
;         __builtin_amdgcn_global_load_lds((const unsigned*)((const char*)(gbase) + (voff)[_i]), (PG8_LAS unsigned*)(lds + (bufoff) + ldsw + _i * 8192), 16, 0, 0); } while (0)
; #define PG8_LDA(dst, b, h) do { _Pragma("unroll") for (int m = 0; m < 4; ++m) _Pragma("unroll") for (int k = 0; k < 2; ++k) dst[m][k] = *(const PG8_LAS bf16x8*)(lds + PG8_SA(b, h) + aoff + m * 2048 + k * 1024); } while (0)
; #define PG8_LDB(dst, b, h) do { _Pragma("unroll") for (int n = 0; n < 2; ++n) _Pragma("unroll") for (int k = 0; k < 2; ++k) dst[n][k] = *(const PG8_LAS bf16x8*)(lds + PG8_SB(b, h) + boff + n * 2048 + k * 1024); } while (0)
; #define PG8_MMA(ai, bj, At, Bt) do { __builtin_amdgcn_s_setprio(1); _Pragma("unroll") for (int m = 0; m < 4; ++m) _Pragma("unroll") for (int n = 0; n < 2; ++n) _Pragma("unroll") for (int k = 0; k < 2; ++k) \
;         acc[ai][bj][m][n] = __builtin_amdgcn_mfma_f32_16x16x32_bf16(Bt[n][k], At[m][k], acc[ai][bj][m][n], 0, 0, 0); __builtin_amdgcn_s_setprio(0); } while (0)
; #define PG8_WAIT_V(n) asm volatile("s_waitcnt vmcnt(" #n ")" ::: "memory")
; #define PG8_WAIT_L(n) asm volatile("s_waitcnt lgkmcnt(" #n ")" ::: "memory")
; #define PG8_BAR __builtin_amdgcn_s_barrier()
; #define PG8_SCHED __builtin_amdgcn_sched_barrier(0)
; template <class Epi, class Sched, bool ALIGN_EPI = false, bool SP2 = false>
; __device__ __forceinline__ void gemm_phase(PG8_LAS unsigned char* lds, const Gemm g, const Sched& S, const Epi& E) {
;     ...
;             PG8_LDB(B0, 0, 0); PG8_LDB(B1, 0, 1); PG8_SCHED; PG8_LDA(At, 0, 0); PG8_STAGE(PG8_SA(1, 1), a1 + hstep, voffA);
;             PG8_WAIT_V(8); PG8_WAIT_L(0); PG8_BAR; PG8_MMA(0, 0, At, B0); PG8_MMA(0, 1, At, B1); PG8_BAR; PG8_SCHED;
;             PG8_LDA(At, 0, 1); PG8_STAGE(PG8_SB(0, 0), b2, voffB); PG8_STAGE(PG8_SB(0, 1), b2 + hstep, voffB); PG8_STAGE(PG8_SA(0, 0), a2, voffA);
;             PG8_WAIT_V(8); PG8_WAIT_L(0); PG8_BAR; PG8_MMA(1, 0, At, B0); PG8_MMA(1, 1, At, B1); PG8_BAR; PG8_SCHED;
.LBB0_348:
	ds_read_b128 v[128:131], v186
	ds_read_b128 v[132:135], v186 offset:1024
	ds_read_b128 v[136:139], v186 offset:2048
	ds_read_b128 v[164:167], v186 offset:3072
	ds_read_b128 v[168:171], v187
	ds_read_b128 v[172:175], v187 offset:1024
	ds_read_b128 v[176:179], v187 offset:2048
	ds_read_b128 v[196:199], v187 offset:3072
	s_add_u32 s48, s6, 0xfffc0080
	s_addc_u32 s49, s7, -1
	s_cmp_eq_u32 s79, 12
	s_cselect_b32 s75, s1, s49
	s_cselect_b32 s74, s43, s48
	s_cselect_b32 s49, s41, s78
	s_cselect_b32 s48, s76, s77
	v_lshl_add_u64 v[228:229], s[6:7], 0, v[156:157]
	s_add_i32 m0, s83, 0xc000
	ds_read_b128 v[200:203], v188
	ds_read_b128 v[204:207], v188 offset:1024
	ds_read_b128 v[208:211], v188 offset:2048
	ds_read_b128 v[212:215], v188 offset:3072
	ds_read_b128 v[216:219], v188 offset:4096
	ds_read_b128 v[220:223], v188 offset:5120
	ds_read_b128 v[224:227], v188 offset:6144
	ds_read_b128 v[232:235], v188 offset:7168
	global_load_lds_dwordx4 v[228:229], off
	v_lshl_add_u64 v[228:229], s[6:7], 0, v[158:159]
	s_add_i32 m0, s83, 0xe000
	s_nop 0
	global_load_lds_dwordx4 v[228:229], off
	s_waitcnt vmcnt(8)
	s_waitcnt lgkmcnt(0)
	s_barrier
	s_setprio 1
	s_waitcnt lgkmcnt(0)
	v_mfma_f32_16x16x32_bf16 v[124:127], v[128:131], v[200:203], v[124:127]
	v_mfma_f32_16x16x32_bf16 v[120:123], v[136:139], v[200:203], v[120:123]
	v_mfma_f32_16x16x32_bf16 v[108:111], v[128:131], v[208:211], v[108:111]
	v_mfma_f32_16x16x32_bf16 v[104:107], v[136:139], v[208:211], v[104:107]
	v_mfma_f32_16x16x32_bf16 v[92:95], v[128:131], v[216:219], v[92:95]
	v_mfma_f32_16x16x32_bf16 v[88:91], v[136:139], v[216:219], v[88:91]
	v_mfma_f32_16x16x32_bf16 v[76:79], v[128:131], v[224:227], v[76:79]
	v_mfma_f32_16x16x32_bf16 v[72:75], v[136:139], v[224:227], v[72:75]
	v_mfma_f32_16x16x32_bf16 v[124:127], v[132:135], v[204:207], v[124:127]
	v_mfma_f32_16x16x32_bf16 v[120:123], v[164:167], v[204:207], v[120:123]
	v_mfma_f32_16x16x32_bf16 v[108:111], v[132:135], v[212:215], v[108:111]
	v_mfma_f32_16x16x32_bf16 v[104:107], v[164:167], v[212:215], v[104:107]
	v_mfma_f32_16x16x32_bf16 v[92:95], v[132:135], v[220:223], v[92:95]
	v_mfma_f32_16x16x32_bf16 v[88:91], v[164:167], v[220:223], v[88:91]
	v_mfma_f32_16x16x32_bf16 v[76:79], v[132:135], v[232:235], v[76:79]
	v_mfma_f32_16x16x32_bf16 v[72:75], v[164:167], v[232:235], v[72:75]
	s_setprio 0
	s_setprio 1
	v_mfma_f32_16x16x32_bf16 v[116:119], v[168:171], v[200:203], v[116:119]
	v_mfma_f32_16x16x32_bf16 v[112:115], v[176:179], v[200:203], v[112:115]
	v_mfma_f32_16x16x32_bf16 v[100:103], v[168:171], v[208:211], v[100:103]
	v_mfma_f32_16x16x32_bf16 v[96:99], v[176:179], v[208:211], v[96:99]
	v_mfma_f32_16x16x32_bf16 v[84:87], v[168:171], v[216:219], v[84:87]
	v_mfma_f32_16x16x32_bf16 v[80:83], v[176:179], v[216:219], v[80:83]
	v_mfma_f32_16x16x32_bf16 v[68:71], v[168:171], v[224:227], v[68:71]
	v_mfma_f32_16x16x32_bf16 v[64:67], v[176:179], v[224:227], v[64:67]
	v_mfma_f32_16x16x32_bf16 v[116:119], v[172:175], v[204:207], v[116:119]
	v_mfma_f32_16x16x32_bf16 v[112:115], v[196:199], v[204:207], v[112:115]
	v_mfma_f32_16x16x32_bf16 v[100:103], v[172:175], v[212:215], v[100:103]
	v_mfma_f32_16x16x32_bf16 v[96:99], v[196:199], v[212:215], v[96:99]
	v_mfma_f32_16x16x32_bf16 v[84:87], v[172:175], v[220:223], v[84:87]
	v_mfma_f32_16x16x32_bf16 v[80:83], v[196:199], v[220:223], v[80:83]
	v_mfma_f32_16x16x32_bf16 v[68:71], v[172:175], v[232:235], v[68:71]
	v_mfma_f32_16x16x32_bf16 v[64:67], v[196:199], v[232:235], v[64:67]
	s_setprio 0
	s_barrier
	s_sleep 1
	s_add_i32 vcc_lo, s97, s80
	v_lshl_add_u64 v[228:229], s[48:49], 0, v[144:145]
	s_mov_b32 m0, vcc_lo
	ds_read_b128 v[200:203], v188 offset:16384
	ds_read_b128 v[204:207], v188 offset:17408
	ds_read_b128 v[208:211], v188 offset:18432
	ds_read_b128 v[212:215], v188 offset:19456
	ds_read_b128 v[216:219], v188 offset:20480
	ds_read_b128 v[220:223], v188 offset:21504
	ds_read_b128 v[224:227], v188 offset:22528
	ds_read_b128 v[232:235], v188 offset:23552
	global_load_lds_dwordx4 v[228:229], off
	s_add_i32 m0, vcc_lo, 0x2000
	s_add_u32 vcc_lo, s48, 0x40000
	v_lshl_add_u64 v[236:237], s[48:49], 0, v[140:141]
	s_addc_u32 vcc_hi, s49, 0
	s_add_i32 s94, s60, s80
	global_load_lds_dwordx4 v[236:237], off
	v_lshl_add_u64 v[238:239], vcc, 0, v[144:145]
	s_mov_b32 m0, s94
	v_lshl_add_u64 v[240:241], s[74:75], 0, v[142:143]
	global_load_lds_dwordx4 v[238:239], off
	v_lshl_add_u64 v[238:239], vcc, 0, v[140:141]
	s_add_i32 m0, s94, 0x2000
	s_nop 0
	global_load_lds_dwordx4 v[238:239], off
	v_lshl_add_u64 v[238:239], s[74:75], 0, v[146:147]
	s_mov_b32 m0, s83
	s_nop 0
	global_load_lds_dwordx4 v[238:239], off
	s_mov_b32 m0, s84
	s_nop 0
	global_load_lds_dwordx4 v[240:241], off
	s_waitcnt vmcnt(8)
	s_waitcnt lgkmcnt(0)
	s_barrier
; #define PG8_STAGE(bufoff, gbase, voff) do { _Pragma("unroll") for (int _i = 0; _i < 2; ++_i) \
;         __builtin_amdgcn_global_load_lds((const unsigned*)((const char*)(gbase) + (voff)[_i]), (PG8_LAS unsigned*)(lds + (bufoff) + ldsw + _i * 8192), 16, 0, 0); } while (0)
; #define PG8_LDA(dst, b, h) do { _Pragma("unroll") for (int m = 0; m < 4; ++m) _Pragma("unroll") for (int k = 0; k < 2; ++k) dst[m][k] = *(const PG8_LAS bf16x8*)(lds + PG8_SA(b, h) + aoff + m * 2048 + k * 1024); } while (0)
; #define PG8_LDB(dst, b, h) do { _Pragma("unroll") for (int n = 0; n < 2; ++n) _Pragma("unroll") for (int k = 0; k < 2; ++k) dst[n][k] = *(const PG8_LAS bf16x8*)(lds + PG8_SB(b, h) + boff + n * 2048 + k * 1024); } while (0)
; #define PG8_MMA(ai, bj, At, Bt) do { __builtin_amdgcn_s_setprio(1); _Pragma("unroll") for (int m = 0; m < 4; ++m) _Pragma("unroll") for (int n = 0; n < 2; ++n) _Pragma("unroll") for (int k = 0; k < 2; ++k) \
;         acc[ai][bj][m][n] = __builtin_amdgcn_mfma_f32_16x16x32_bf16(Bt[n][k], At[m][k], acc[ai][bj][m][n], 0, 0, 0); __builtin_amdgcn_s_setprio(0); } while (0)
; #define PG8_WAIT_V(n) asm volatile("s_waitcnt vmcnt(" #n ")" ::: "memory")
; #define PG8_WAIT_L(n) asm volatile("s_waitcnt lgkmcnt(" #n ")" ::: "memory")
; #define PG8_BAR __builtin_amdgcn_s_barrier()
; #define PG8_SCHED __builtin_amdgcn_sched_barrier(0)
; template <class Epi, class Sched, bool ALIGN_EPI = false, bool SP2 = false>
; __device__ __forceinline__ void gemm_phase(PG8_LAS unsigned char* lds, const Gemm g, const Sched& S, const Epi& E) {
;     ...
;             PG8_WAIT_V(8); PG8_WAIT_L(0); PG8_BAR; PG8_MMA(1, 0, At, B0); PG8_MMA(1, 1, At, B1); PG8_BAR; PG8_SCHED;
;             PG8_LDB(B0, 1, 0); PG8_LDB(B1, 1, 1); PG8_SCHED; PG8_LDA(At, 1, 0); PG8_STAGE(PG8_SA(0, 1), a2 + hstep, voffA);
;             PG8_WAIT_V(8); PG8_WAIT_L(0); PG8_BAR; PG8_MMA(0, 0, At, B0); PG8_MMA(0, 1, At, B1); PG8_BAR; PG8_SCHED;
	s_setprio 1
	s_waitcnt lgkmcnt(0)
	v_mfma_f32_16x16x32_bf16 v[60:63], v[128:131], v[200:203], v[60:63]
	v_mfma_f32_16x16x32_bf16 v[56:59], v[136:139], v[200:203], v[56:59]
	v_mfma_f32_16x16x32_bf16 v[44:47], v[128:131], v[208:211], v[44:47]
	v_mfma_f32_16x16x32_bf16 v[40:43], v[136:139], v[208:211], v[40:43]
	v_mfma_f32_16x16x32_bf16 v[28:31], v[128:131], v[216:219], v[28:31]
	v_mfma_f32_16x16x32_bf16 v[24:27], v[136:139], v[216:219], v[24:27]
	v_mfma_f32_16x16x32_bf16 v[12:15], v[128:131], v[224:227], v[12:15]
	v_mfma_f32_16x16x32_bf16 v[8:11], v[136:139], v[224:227], v[8:11]
	v_mfma_f32_16x16x32_bf16 v[60:63], v[132:135], v[204:207], v[60:63]
	v_mfma_f32_16x16x32_bf16 v[56:59], v[164:167], v[204:207], v[56:59]
	v_mfma_f32_16x16x32_bf16 v[44:47], v[132:135], v[212:215], v[44:47]
	v_mfma_f32_16x16x32_bf16 v[40:43], v[164:167], v[212:215], v[40:43]
	v_mfma_f32_16x16x32_bf16 v[28:31], v[132:135], v[220:223], v[28:31]
	v_mfma_f32_16x16x32_bf16 v[24:27], v[164:167], v[220:223], v[24:27]
	v_mfma_f32_16x16x32_bf16 v[12:15], v[132:135], v[232:235], v[12:15]
	v_mfma_f32_16x16x32_bf16 v[8:11], v[164:167], v[232:235], v[8:11]
	s_setprio 0
	s_setprio 1
	v_mfma_f32_16x16x32_bf16 v[52:55], v[168:171], v[200:203], v[52:55]
	v_mfma_f32_16x16x32_bf16 v[48:51], v[176:179], v[200:203], v[48:51]
	v_mfma_f32_16x16x32_bf16 v[36:39], v[168:171], v[208:211], v[36:39]
	v_mfma_f32_16x16x32_bf16 v[32:35], v[176:179], v[208:211], v[32:35]
	v_mfma_f32_16x16x32_bf16 v[20:23], v[168:171], v[216:219], v[20:23]
	v_mfma_f32_16x16x32_bf16 v[16:19], v[176:179], v[216:219], v[16:19]
	v_mfma_f32_16x16x32_bf16 v[4:7], v[168:171], v[224:227], v[4:7]
	v_mfma_f32_16x16x32_bf16 v[0:3], v[176:179], v[224:227], v[0:3]
	v_mfma_f32_16x16x32_bf16 v[52:55], v[172:175], v[204:207], v[52:55]
	v_mfma_f32_16x16x32_bf16 v[48:51], v[196:199], v[204:207], v[48:51]
	v_mfma_f32_16x16x32_bf16 v[36:39], v[172:175], v[212:215], v[36:39]
	v_mfma_f32_16x16x32_bf16 v[32:35], v[196:199], v[212:215], v[32:35]
	v_mfma_f32_16x16x32_bf16 v[20:23], v[172:175], v[220:223], v[20:23]
	v_mfma_f32_16x16x32_bf16 v[16:19], v[196:199], v[220:223], v[16:19]
	v_mfma_f32_16x16x32_bf16 v[4:7], v[172:175], v[232:235], v[4:7]
	v_mfma_f32_16x16x32_bf16 v[0:3], v[196:199], v[232:235], v[0:3]
	s_setprio 0
	s_barrier
	s_sleep 1
	s_add_i32 s94, 0, 0x18000
	v_add_u32_e32 v148, s94, v181
	s_add_i32 vcc_lo, 0, 0x1c000
	ds_read_b128 v[128:131], v148
	ds_read_b128 v[132:135], v148 offset:1024
	ds_read_b128 v[136:139], v148 offset:2048
	ds_read_b128 v[164:167], v148 offset:3072
	v_add_u32_e32 v148, vcc_lo, v181
	ds_read_b128 v[168:171], v148
	ds_read_b128 v[172:175], v148 offset:1024
	ds_read_b128 v[176:179], v148 offset:2048
	ds_read_b128 v[196:199], v148 offset:3072
	s_add_u32 s74, s74, 0x40000
	s_addc_u32 s75, s75, 0
	s_mov_b32 m0, s85
	v_lshl_add_u64 v[242:243], s[74:75], 0, v[146:147]
	ds_read_b128 v[200:203], v188 offset:32768
	ds_read_b128 v[204:207], v188 offset:33792
	ds_read_b128 v[208:211], v188 offset:34816
	ds_read_b128 v[212:215], v188 offset:35840
	ds_read_b128 v[216:219], v188 offset:36864
	ds_read_b128 v[220:223], v188 offset:37888
	ds_read_b128 v[224:227], v188 offset:38912
	ds_read_b128 v[232:235], v188 offset:39936
	global_load_lds_dwordx4 v[242:243], off
	v_lshl_add_u64 v[242:243], s[74:75], 0, v[142:143]
	s_mov_b32 m0, s86
	s_nop 0
	global_load_lds_dwordx4 v[242:243], off
	s_waitcnt vmcnt(8)
	s_waitcnt lgkmcnt(0)
	s_barrier
	s_setprio 1
	s_waitcnt lgkmcnt(0)
	v_mfma_f32_16x16x32_bf16 v[124:127], v[128:131], v[200:203], v[124:127]
	v_mfma_f32_16x16x32_bf16 v[120:123], v[136:139], v[200:203], v[120:123]
	v_mfma_f32_16x16x32_bf16 v[108:111], v[128:131], v[208:211], v[108:111]
	v_mfma_f32_16x16x32_bf16 v[104:107], v[136:139], v[208:211], v[104:107]
	v_mfma_f32_16x16x32_bf16 v[92:95], v[128:131], v[216:219], v[92:95]
	v_mfma_f32_16x16x32_bf16 v[88:91], v[136:139], v[216:219], v[88:91]
	v_mfma_f32_16x16x32_bf16 v[76:79], v[128:131], v[224:227], v[76:79]
	v_mfma_f32_16x16x32_bf16 v[72:75], v[136:139], v[224:227], v[72:75]
	v_mfma_f32_16x16x32_bf16 v[124:127], v[132:135], v[204:207], v[124:127]
	v_mfma_f32_16x16x32_bf16 v[120:123], v[164:167], v[204:207], v[120:123]
	v_mfma_f32_16x16x32_bf16 v[108:111], v[132:135], v[212:215], v[108:111]
	v_mfma_f32_16x16x32_bf16 v[104:107], v[164:167], v[212:215], v[104:107]
	v_mfma_f32_16x16x32_bf16 v[92:95], v[132:135], v[220:223], v[92:95]
	v_mfma_f32_16x16x32_bf16 v[88:91], v[164:167], v[220:223], v[88:91]
	v_mfma_f32_16x16x32_bf16 v[76:79], v[132:135], v[232:235], v[76:79]
	v_mfma_f32_16x16x32_bf16 v[72:75], v[164:167], v[232:235], v[72:75]
	s_setprio 0
	s_setprio 1
	v_mfma_f32_16x16x32_bf16 v[116:119], v[168:171], v[200:203], v[116:119]
	v_mfma_f32_16x16x32_bf16 v[112:115], v[176:179], v[200:203], v[112:115]
	v_mfma_f32_16x16x32_bf16 v[100:103], v[168:171], v[208:211], v[100:103]
	v_mfma_f32_16x16x32_bf16 v[96:99], v[176:179], v[208:211], v[96:99]
	v_mfma_f32_16x16x32_bf16 v[84:87], v[168:171], v[216:219], v[84:87]
	v_mfma_f32_16x16x32_bf16 v[80:83], v[176:179], v[216:219], v[80:83]
	v_mfma_f32_16x16x32_bf16 v[68:71], v[168:171], v[224:227], v[68:71]
	v_mfma_f32_16x16x32_bf16 v[64:67], v[176:179], v[224:227], v[64:67]
	v_mfma_f32_16x16x32_bf16 v[116:119], v[172:175], v[204:207], v[116:119]
	v_mfma_f32_16x16x32_bf16 v[112:115], v[196:199], v[204:207], v[112:115]
	v_mfma_f32_16x16x32_bf16 v[100:103], v[172:175], v[212:215], v[100:103]
	v_mfma_f32_16x16x32_bf16 v[96:99], v[196:199], v[212:215], v[96:99]
	v_mfma_f32_16x16x32_bf16 v[84:87], v[172:175], v[220:223], v[84:87]
	v_mfma_f32_16x16x32_bf16 v[80:83], v[196:199], v[220:223], v[80:83]
	v_mfma_f32_16x16x32_bf16 v[68:71], v[172:175], v[232:235], v[68:71]
	v_mfma_f32_16x16x32_bf16 v[64:67], v[196:199], v[232:235], v[64:67]
	s_setprio 0
	s_barrier
; #define PG8_STAGE(bufoff, gbase, voff) do { _Pragma("unroll") for (int _i = 0; _i < 2; ++_i) \
;         __builtin_amdgcn_global_load_lds((const unsigned*)((const char*)(gbase) + (voff)[_i]), (PG8_LAS unsigned*)(lds + (bufoff) + ldsw + _i * 8192), 16, 0, 0); } while (0)
; #define PG8_LDA(dst, b, h) do { _Pragma("unroll") for (int m = 0; m < 4; ++m) _Pragma("unroll") for (int k = 0; k < 2; ++k) dst[m][k] = *(const PG8_LAS bf16x8*)(lds + PG8_SA(b, h) + aoff + m * 2048 + k * 1024); } while (0)
; #define PG8_MMA(ai, bj, At, Bt) do { __builtin_amdgcn_s_setprio(1); _Pragma("unroll") for (int m = 0; m < 4; ++m) _Pragma("unroll") for (int n = 0; n < 2; ++n) _Pragma("unroll") for (int k = 0; k < 2; ++k) \
;         acc[ai][bj][m][n] = __builtin_amdgcn_mfma_f32_16x16x32_bf16(Bt[n][k], At[m][k], acc[ai][bj][m][n], 0, 0, 0); __builtin_amdgcn_s_setprio(0); } while (0)
; #define PG8_WAIT_V(n) asm volatile("s_waitcnt vmcnt(" #n ")" ::: "memory")
; #define PG8_WAIT_L(n) asm volatile("s_waitcnt lgkmcnt(" #n ")" ::: "memory")
; #define PG8_BAR __builtin_amdgcn_s_barrier()
; #define PG8_SCHED __builtin_amdgcn_sched_barrier(0)
; template <class Epi, class Sched, bool ALIGN_EPI = false, bool SP2 = false>
; __device__ __forceinline__ void gemm_phase(PG8_LAS unsigned char* lds, const Gemm g, const Sched& S, const Epi& E) {
;     ...
;             PG8_LDA(At, 1, 1); PG8_STAGE(PG8_SB(1, 0), b3, voffB); PG8_STAGE(PG8_SB(1, 1), b3 + hstep, voffB); PG8_STAGE(PG8_SA(1, 0), a3, voffA);
;             PG8_WAIT_V(8); PG8_WAIT_L(0); PG8_BAR; PG8_MMA(1, 0, At, B0); PG8_MMA(1, 1, At, B1); PG8_BAR; PG8_SCHED;
	s_sleep 1
	s_add_i32 s74, s94, s80
	v_lshl_add_u64 v[228:229], v[228:229], 0, s[22:23]
	s_mov_b32 m0, s74
	ds_read_b128 v[200:203], v188 offset:49152
	ds_read_b128 v[204:207], v188 offset:50176
	ds_read_b128 v[208:211], v188 offset:51200
	ds_read_b128 v[212:215], v188 offset:52224
	ds_read_b128 v[216:219], v188 offset:53248
	ds_read_b128 v[220:223], v188 offset:54272
	ds_read_b128 v[224:227], v188 offset:55296
	ds_read_b128 v[232:235], v188 offset:56320
	global_load_lds_dwordx4 v[228:229], off
	s_add_i32 m0, s74, 0x2000
	s_add_u32 s48, s48, 0x40080
	v_lshl_add_u64 v[228:229], v[236:237], 0, s[22:23]
	s_addc_u32 s49, s49, 0
	s_add_i32 s74, vcc_lo, s80
	global_load_lds_dwordx4 v[228:229], off
	v_lshl_add_u64 v[228:229], s[48:49], 0, v[144:145]
	s_mov_b32 m0, s74
	s_nop 0
	global_load_lds_dwordx4 v[228:229], off
	v_lshl_add_u64 v[228:229], s[48:49], 0, v[140:141]
	s_add_i32 m0, s74, 0x2000
	s_nop 0
	global_load_lds_dwordx4 v[228:229], off
	v_lshl_add_u64 v[228:229], v[238:239], 0, s[22:23]
	s_mov_b32 m0, s89
	s_nop 0
	global_load_lds_dwordx4 v[228:229], off
	v_lshl_add_u64 v[228:229], v[240:241], 0, s[22:23]
	s_mov_b32 m0, s90
	s_nop 0
	global_load_lds_dwordx4 v[228:229], off
	s_waitcnt vmcnt(8)
	s_waitcnt lgkmcnt(0)
	s_barrier
	s_setprio 1
	s_waitcnt lgkmcnt(0)
	v_mfma_f32_16x16x32_bf16 v[60:63], v[128:131], v[200:203], v[60:63]
	v_mfma_f32_16x16x32_bf16 v[56:59], v[136:139], v[200:203], v[56:59]
	v_mfma_f32_16x16x32_bf16 v[44:47], v[128:131], v[208:211], v[44:47]
	v_mfma_f32_16x16x32_bf16 v[40:43], v[136:139], v[208:211], v[40:43]
	v_mfma_f32_16x16x32_bf16 v[28:31], v[128:131], v[216:219], v[28:31]
	v_mfma_f32_16x16x32_bf16 v[24:27], v[136:139], v[216:219], v[24:27]
	v_mfma_f32_16x16x32_bf16 v[12:15], v[128:131], v[224:227], v[12:15]
	v_mfma_f32_16x16x32_bf16 v[8:11], v[136:139], v[224:227], v[8:11]
	v_mfma_f32_16x16x32_bf16 v[60:63], v[132:135], v[204:207], v[60:63]
	v_mfma_f32_16x16x32_bf16 v[56:59], v[164:167], v[204:207], v[56:59]
	v_mfma_f32_16x16x32_bf16 v[44:47], v[132:135], v[212:215], v[44:47]
	v_mfma_f32_16x16x32_bf16 v[40:43], v[164:167], v[212:215], v[40:43]
	v_mfma_f32_16x16x32_bf16 v[28:31], v[132:135], v[220:223], v[28:31]
	v_mfma_f32_16x16x32_bf16 v[24:27], v[164:167], v[220:223], v[24:27]
	v_mfma_f32_16x16x32_bf16 v[12:15], v[132:135], v[232:235], v[12:15]
	v_mfma_f32_16x16x32_bf16 v[8:11], v[164:167], v[232:235], v[8:11]
	s_setprio 0
	s_setprio 1
	v_mfma_f32_16x16x32_bf16 v[52:55], v[168:171], v[200:203], v[52:55]
	v_mfma_f32_16x16x32_bf16 v[48:51], v[176:179], v[200:203], v[48:51]
	v_mfma_f32_16x16x32_bf16 v[36:39], v[168:171], v[208:211], v[36:39]
	v_mfma_f32_16x16x32_bf16 v[32:35], v[176:179], v[208:211], v[32:35]
	v_mfma_f32_16x16x32_bf16 v[20:23], v[168:171], v[216:219], v[20:23]
	v_mfma_f32_16x16x32_bf16 v[16:19], v[176:179], v[216:219], v[16:19]
	v_mfma_f32_16x16x32_bf16 v[4:7], v[168:171], v[224:227], v[4:7]
	v_mfma_f32_16x16x32_bf16 v[0:3], v[176:179], v[224:227], v[0:3]
	v_mfma_f32_16x16x32_bf16 v[52:55], v[172:175], v[204:207], v[52:55]
	v_mfma_f32_16x16x32_bf16 v[48:51], v[196:199], v[204:207], v[48:51]
	v_mfma_f32_16x16x32_bf16 v[36:39], v[172:175], v[212:215], v[36:39]
	v_mfma_f32_16x16x32_bf16 v[32:35], v[196:199], v[212:215], v[32:35]
	v_mfma_f32_16x16x32_bf16 v[20:23], v[172:175], v[220:223], v[20:23]
	v_mfma_f32_16x16x32_bf16 v[16:19], v[196:199], v[220:223], v[16:19]
	v_mfma_f32_16x16x32_bf16 v[4:7], v[172:175], v[232:235], v[4:7]
	v_mfma_f32_16x16x32_bf16 v[0:3], v[196:199], v[232:235], v[0:3]
	s_setprio 0
	s_barrier
	s_sleep 1
	s_add_i32 s79, s79, 2
	s_add_u32 s6, s6, 0x100
	s_addc_u32 s7, s7, 0
	s_add_u32 s77, s77, 0x100
	s_addc_u32 s78, s78, 0
	s_cmp_gt_u32 s79, 13
	s_cbranch_scc0 .LBB0_348
	s_and_b64 vcc, exec, s[24:25]
	s_cbranch_vccz .LBB0_351
	s_barrier

; #define PG8_STAGE(bufoff, gbase, voff) do { _Pragma("unroll") for (int _i = 0; _i < 2; ++_i) \
;         __builtin_amdgcn_global_load_lds((const unsigned*)((const char*)(gbase) + (voff)[_i]), (PG8_LAS unsigned*)(lds + (bufoff) + ldsw + _i * 8192), 16, 0, 0); } while (0)
; #define PG8_LDA(dst, b, h) do { _Pragma("unroll") for (int m = 0; m < 4; ++m) _Pragma("unroll") for (int k = 0; k < 2; ++k) dst[m][k] = *(const PG8_LAS bf16x8*)(lds + PG8_SA(b, h) + aoff + m * 2048 + k * 1024); } while (0)
; #define PG8_LDB(dst, b, h) do { _Pragma("unroll") for (int n = 0; n < 2; ++n) _Pragma("unroll") for (int k = 0; k < 2; ++k) dst[n][k] = *(const PG8_LAS bf16x8*)(lds + PG8_SB(b, h) + boff + n * 2048 + k * 1024); } while (0)
; #define PG8_MMA(ai, bj, At, Bt) do { __builtin_amdgcn_s_setprio(1); _Pragma("unroll") for (int m = 0; m < 4; ++m) _Pragma("unroll") for (int n = 0; n < 2; ++n) _Pragma("unroll") for (int k = 0; k < 2; ++k) \
;         acc[ai][bj][m][n] = __builtin_amdgcn_mfma_f32_16x16x32_bf16(Bt[n][k], At[m][k], acc[ai][bj][m][n], 0, 0, 0); __builtin_amdgcn_s_setprio(0); } while (0)
; #define PG8_WAIT_V(n) asm volatile("s_waitcnt vmcnt(" #n ")" ::: "memory")
; #define PG8_WAIT_L(n) asm volatile("s_waitcnt lgkmcnt(" #n ")" ::: "memory")
; #define PG8_BAR __builtin_amdgcn_s_barrier()
; #define PG8_SCHED __builtin_amdgcn_sched_barrier(0)
; template <class Epi, class Sched, bool ALIGN_EPI = false, bool SP2 = false>
; __device__ __forceinline__ void gemm_phase(PG8_LAS unsigned char* lds, const Gemm g, const Sched& S, const Epi& E) {
;     ...
;             PG8_LDB(B0, 0, 0); PG8_LDB(B1, 0, 1); PG8_SCHED; PG8_LDA(At, 0, 0); PG8_STAGE(PG8_SA(1, 1), a1 + hstep, voffA);
;             PG8_WAIT_V(8); PG8_WAIT_L(0); PG8_BAR; PG8_MMA(0, 0, At, B0); PG8_MMA(0, 1, At, B1); PG8_BAR; PG8_SCHED;
;             PG8_LDA(At, 0, 1); PG8_STAGE(PG8_SB(0, 0), b2, voffB); PG8_STAGE(PG8_SB(0, 1), b2 + hstep, voffB); PG8_STAGE(PG8_SA(0, 0), a2, voffA);
;             PG8_WAIT_V(8); PG8_WAIT_L(0); PG8_BAR; PG8_MMA(1, 0, At, B0); PG8_MMA(1, 1, At, B1); PG8_BAR; PG8_SCHED;
.LBB0_735:
	ds_read_b128 v[144:147], v159
	ds_read_b128 v[162:165], v159 offset:1024
	ds_read_b128 v[166:169], v159 offset:2048
	ds_read_b128 v[170:173], v159 offset:3072
	ds_read_b128 v[174:177], v160
	ds_read_b128 v[178:181], v160 offset:1024
	ds_read_b128 v[182:185], v160 offset:2048
	ds_read_b128 v[186:189], v160 offset:3072
	s_add_u32 s44, s42, 0xfffe0080
	s_addc_u32 s45, s43, -1
	s_cmp_eq_u32 s86, 4
	s_cselect_b32 s47, s27, s45
	s_cselect_b32 s46, s82, s44
	s_cselect_b32 s45, s25, s85
	s_cselect_b32 s44, s83, s84
	v_lshl_add_u64 v[222:223], s[42:43], 0, v[136:137]
	s_add_i32 m0, s41, 0xc000
	ds_read_b128 v[190:193], v161
	ds_read_b128 v[194:197], v161 offset:1024
	ds_read_b128 v[198:201], v161 offset:2048
	ds_read_b128 v[202:205], v161 offset:3072
	ds_read_b128 v[206:209], v161 offset:4096
	ds_read_b128 v[210:213], v161 offset:5120
	ds_read_b128 v[214:217], v161 offset:6144
	ds_read_b128 v[218:221], v161 offset:7168
	global_load_lds_dwordx4 v[222:223], off
	v_lshl_add_u64 v[222:223], s[42:43], 0, v[138:139]
	s_add_i32 m0, s41, 0xe000
	s_nop 0
	global_load_lds_dwordx4 v[222:223], off
	s_waitcnt vmcnt(8)
	s_waitcnt lgkmcnt(0)
	s_barrier
	s_setprio 1
	s_waitcnt lgkmcnt(0)
	v_mfma_f32_16x16x32_bf16 v[124:127], v[144:147], v[190:193], v[124:127]
	v_mfma_f32_16x16x32_bf16 v[120:123], v[166:169], v[190:193], v[120:123]
	v_mfma_f32_16x16x32_bf16 v[112:115], v[144:147], v[198:201], v[112:115]
	v_mfma_f32_16x16x32_bf16 v[104:107], v[166:169], v[198:201], v[104:107]
	v_mfma_f32_16x16x32_bf16 v[92:95], v[144:147], v[206:209], v[92:95]
	v_mfma_f32_16x16x32_bf16 v[88:91], v[166:169], v[206:209], v[88:91]
	v_mfma_f32_16x16x32_bf16 v[84:87], v[144:147], v[214:217], v[84:87]
	v_mfma_f32_16x16x32_bf16 v[80:83], v[166:169], v[214:217], v[80:83]
	v_mfma_f32_16x16x32_bf16 v[124:127], v[162:165], v[194:197], v[124:127]
	v_mfma_f32_16x16x32_bf16 v[120:123], v[170:173], v[194:197], v[120:123]
	v_mfma_f32_16x16x32_bf16 v[112:115], v[162:165], v[202:205], v[112:115]
	v_mfma_f32_16x16x32_bf16 v[104:107], v[170:173], v[202:205], v[104:107]
	v_mfma_f32_16x16x32_bf16 v[92:95], v[162:165], v[210:213], v[92:95]
	v_mfma_f32_16x16x32_bf16 v[88:91], v[170:173], v[210:213], v[88:91]
	v_mfma_f32_16x16x32_bf16 v[84:87], v[162:165], v[218:221], v[84:87]
	v_mfma_f32_16x16x32_bf16 v[80:83], v[170:173], v[218:221], v[80:83]
	s_setprio 0
	s_setprio 1
	v_mfma_f32_16x16x32_bf16 v[116:119], v[174:177], v[190:193], v[116:119]
	v_mfma_f32_16x16x32_bf16 v[108:111], v[182:185], v[190:193], v[108:111]
	v_mfma_f32_16x16x32_bf16 v[100:103], v[174:177], v[198:201], v[100:103]
	v_mfma_f32_16x16x32_bf16 v[96:99], v[182:185], v[198:201], v[96:99]
	v_mfma_f32_16x16x32_bf16 v[76:79], v[174:177], v[206:209], v[76:79]
	v_mfma_f32_16x16x32_bf16 v[72:75], v[182:185], v[206:209], v[72:75]
	v_mfma_f32_16x16x32_bf16 v[68:71], v[174:177], v[214:217], v[68:71]
	v_mfma_f32_16x16x32_bf16 v[64:67], v[182:185], v[214:217], v[64:67]
	v_mfma_f32_16x16x32_bf16 v[116:119], v[178:181], v[194:197], v[116:119]
	v_mfma_f32_16x16x32_bf16 v[108:111], v[186:189], v[194:197], v[108:111]
	v_mfma_f32_16x16x32_bf16 v[100:103], v[178:181], v[202:205], v[100:103]
	v_mfma_f32_16x16x32_bf16 v[96:99], v[186:189], v[202:205], v[96:99]
	v_mfma_f32_16x16x32_bf16 v[76:79], v[178:181], v[210:213], v[76:79]
	v_mfma_f32_16x16x32_bf16 v[72:75], v[186:189], v[210:213], v[72:75]
	v_mfma_f32_16x16x32_bf16 v[68:71], v[178:181], v[218:221], v[68:71]
	v_mfma_f32_16x16x32_bf16 v[64:67], v[186:189], v[218:221], v[64:67]
	s_setprio 0
	s_barrier
	s_sleep 1
	s_add_i32 s87, s75, s49
	v_lshl_add_u64 v[222:223], s[44:45], 0, v[130:131]
	s_mov_b32 m0, s87
	ds_read_b128 v[190:193], v161 offset:16384
	ds_read_b128 v[194:197], v161 offset:17408
	ds_read_b128 v[198:201], v161 offset:18432
	ds_read_b128 v[202:205], v161 offset:19456
	ds_read_b128 v[206:209], v161 offset:20480
	ds_read_b128 v[210:213], v161 offset:21504
	ds_read_b128 v[214:217], v161 offset:22528
	ds_read_b128 v[218:221], v161 offset:23552
	global_load_lds_dwordx4 v[222:223], off
	s_add_i32 m0, s87, 0x2000
	s_add_u32 s88, s44, 0x20000
	v_lshl_add_u64 v[224:225], s[44:45], 0, v[134:135]
	s_addc_u32 s89, s45, 0
	s_add_i32 s87, s76, s49
	global_load_lds_dwordx4 v[224:225], off
	v_lshl_add_u64 v[226:227], s[88:89], 0, v[130:131]
	s_mov_b32 m0, s87
	v_lshl_add_u64 v[228:229], s[46:47], 0, v[132:133]
	global_load_lds_dwordx4 v[226:227], off
	v_lshl_add_u64 v[226:227], s[88:89], 0, v[134:135]
	s_add_i32 m0, s87, 0x2000
	s_nop 0
	global_load_lds_dwordx4 v[226:227], off
	v_lshl_add_u64 v[226:227], s[46:47], 0, v[128:129]
	s_mov_b32 m0, s41
	s_nop 0
	global_load_lds_dwordx4 v[226:227], off
	s_mov_b32 m0, s51
	s_nop 0
	global_load_lds_dwordx4 v[228:229], off
	s_waitcnt vmcnt(8)
	s_waitcnt lgkmcnt(0)
	s_barrier
; #define PG8_STAGE(bufoff, gbase, voff) do { _Pragma("unroll") for (int _i = 0; _i < 2; ++_i) \
;         __builtin_amdgcn_global_load_lds((const unsigned*)((const char*)(gbase) + (voff)[_i]), (PG8_LAS unsigned*)(lds + (bufoff) + ldsw + _i * 8192), 16, 0, 0); } while (0)
; #define PG8_LDA(dst, b, h) do { _Pragma("unroll") for (int m = 0; m < 4; ++m) _Pragma("unroll") for (int k = 0; k < 2; ++k) dst[m][k] = *(const PG8_LAS bf16x8*)(lds + PG8_SA(b, h) + aoff + m * 2048 + k * 1024); } while (0)
; #define PG8_LDB(dst, b, h) do { _Pragma("unroll") for (int n = 0; n < 2; ++n) _Pragma("unroll") for (int k = 0; k < 2; ++k) dst[n][k] = *(const PG8_LAS bf16x8*)(lds + PG8_SB(b, h) + boff + n * 2048 + k * 1024); } while (0)
; #define PG8_MMA(ai, bj, At, Bt) do { __builtin_amdgcn_s_setprio(1); _Pragma("unroll") for (int m = 0; m < 4; ++m) _Pragma("unroll") for (int n = 0; n < 2; ++n) _Pragma("unroll") for (int k = 0; k < 2; ++k) \
;         acc[ai][bj][m][n] = __builtin_amdgcn_mfma_f32_16x16x32_bf16(Bt[n][k], At[m][k], acc[ai][bj][m][n], 0, 0, 0); __builtin_amdgcn_s_setprio(0); } while (0)
; #define PG8_WAIT_V(n) asm volatile("s_waitcnt vmcnt(" #n ")" ::: "memory")
; #define PG8_WAIT_L(n) asm volatile("s_waitcnt lgkmcnt(" #n ")" ::: "memory")
; #define PG8_BAR __builtin_amdgcn_s_barrier()
; #define PG8_SCHED __builtin_amdgcn_sched_barrier(0)
; template <class Epi, class Sched, bool ALIGN_EPI = false, bool SP2 = false>
; __device__ __forceinline__ void gemm_phase(PG8_LAS unsigned char* lds, const Gemm g, const Sched& S, const Epi& E) {
;     ...
;             PG8_WAIT_V(8); PG8_WAIT_L(0); PG8_BAR; PG8_MMA(1, 0, At, B0); PG8_MMA(1, 1, At, B1); PG8_BAR; PG8_SCHED;
;             PG8_LDB(B0, 1, 0); PG8_LDB(B1, 1, 1); PG8_SCHED; PG8_LDA(At, 1, 0); PG8_STAGE(PG8_SA(0, 1), a2 + hstep, voffA);
;             PG8_WAIT_V(8); PG8_WAIT_L(0); PG8_BAR; PG8_MMA(0, 0, At, B0); PG8_MMA(0, 1, At, B1); PG8_BAR; PG8_SCHED;
	s_setprio 1
	s_waitcnt lgkmcnt(0)
	v_mfma_f32_16x16x32_bf16 v[60:63], v[144:147], v[190:193], v[60:63]
	v_mfma_f32_16x16x32_bf16 v[56:59], v[166:169], v[190:193], v[56:59]
	v_mfma_f32_16x16x32_bf16 v[52:55], v[144:147], v[198:201], v[52:55]
	v_mfma_f32_16x16x32_bf16 v[48:51], v[166:169], v[198:201], v[48:51]
	v_mfma_f32_16x16x32_bf16 v[28:31], v[144:147], v[206:209], v[28:31]
	v_mfma_f32_16x16x32_bf16 v[24:27], v[166:169], v[206:209], v[24:27]
	v_mfma_f32_16x16x32_bf16 v[20:23], v[144:147], v[214:217], v[20:23]
	v_mfma_f32_16x16x32_bf16 v[16:19], v[166:169], v[214:217], v[16:19]
	v_mfma_f32_16x16x32_bf16 v[60:63], v[162:165], v[194:197], v[60:63]
	v_mfma_f32_16x16x32_bf16 v[56:59], v[170:173], v[194:197], v[56:59]
	v_mfma_f32_16x16x32_bf16 v[52:55], v[162:165], v[202:205], v[52:55]
	v_mfma_f32_16x16x32_bf16 v[48:51], v[170:173], v[202:205], v[48:51]
	v_mfma_f32_16x16x32_bf16 v[28:31], v[162:165], v[210:213], v[28:31]
	v_mfma_f32_16x16x32_bf16 v[24:27], v[170:173], v[210:213], v[24:27]
	v_mfma_f32_16x16x32_bf16 v[20:23], v[162:165], v[218:221], v[20:23]
	v_mfma_f32_16x16x32_bf16 v[16:19], v[170:173], v[218:221], v[16:19]
	s_setprio 0
	s_setprio 1
	v_mfma_f32_16x16x32_bf16 v[44:47], v[174:177], v[190:193], v[44:47]
	v_mfma_f32_16x16x32_bf16 v[40:43], v[182:185], v[190:193], v[40:43]
	v_mfma_f32_16x16x32_bf16 v[36:39], v[174:177], v[198:201], v[36:39]
	v_mfma_f32_16x16x32_bf16 v[32:35], v[182:185], v[198:201], v[32:35]
	v_mfma_f32_16x16x32_bf16 v[12:15], v[174:177], v[206:209], v[12:15]
	v_mfma_f32_16x16x32_bf16 v[8:11], v[182:185], v[206:209], v[8:11]
	v_mfma_f32_16x16x32_bf16 v[4:7], v[174:177], v[214:217], v[4:7]
	v_mfma_f32_16x16x32_bf16 v[0:3], v[182:185], v[214:217], v[0:3]
	v_mfma_f32_16x16x32_bf16 v[44:47], v[178:181], v[194:197], v[44:47]
	v_mfma_f32_16x16x32_bf16 v[40:43], v[186:189], v[194:197], v[40:43]
	v_mfma_f32_16x16x32_bf16 v[36:39], v[178:181], v[202:205], v[36:39]
	v_mfma_f32_16x16x32_bf16 v[32:35], v[186:189], v[202:205], v[32:35]
	v_mfma_f32_16x16x32_bf16 v[12:15], v[178:181], v[210:213], v[12:15]
	v_mfma_f32_16x16x32_bf16 v[8:11], v[186:189], v[210:213], v[8:11]
	v_mfma_f32_16x16x32_bf16 v[4:7], v[178:181], v[218:221], v[4:7]
	v_mfma_f32_16x16x32_bf16 v[0:3], v[186:189], v[218:221], v[0:3]
	s_setprio 0
	s_barrier
	s_sleep 1
	s_add_i32 s87, 0, 0x18000
	s_add_i32 s88, 0, 0x1c000
	v_add_u32_e32 v170, s87, v157
	v_add_u32_e32 v186, s88, v157
	ds_read_b128 v[144:147], v170
	ds_read_b128 v[162:165], v170 offset:1024
	ds_read_b128 v[166:169], v170 offset:2048
	ds_read_b128 v[170:173], v170 offset:3072
	ds_read_b128 v[174:177], v186
	ds_read_b128 v[178:181], v186 offset:1024
	ds_read_b128 v[182:185], v186 offset:2048
	ds_read_b128 v[186:189], v186 offset:3072
	s_add_u32 s46, s46, 0x20000
	s_addc_u32 s47, s47, 0
	s_mov_b32 m0, s52
	v_lshl_add_u64 v[232:233], s[46:47], 0, v[128:129]
	ds_read_b128 v[190:193], v161 offset:32768
	ds_read_b128 v[194:197], v161 offset:33792
	ds_read_b128 v[198:201], v161 offset:34816
	ds_read_b128 v[202:205], v161 offset:35840
	ds_read_b128 v[206:209], v161 offset:36864
	ds_read_b128 v[210:213], v161 offset:37888
	ds_read_b128 v[214:217], v161 offset:38912
	ds_read_b128 v[218:221], v161 offset:39936
	global_load_lds_dwordx4 v[232:233], off
	v_lshl_add_u64 v[232:233], s[46:47], 0, v[132:133]
	s_mov_b32 m0, s53
	s_nop 0
	global_load_lds_dwordx4 v[232:233], off
	s_waitcnt vmcnt(8)
	s_waitcnt lgkmcnt(0)
	s_barrier
	s_setprio 1
	s_waitcnt lgkmcnt(0)
	v_mfma_f32_16x16x32_bf16 v[124:127], v[144:147], v[190:193], v[124:127]
	v_mfma_f32_16x16x32_bf16 v[120:123], v[166:169], v[190:193], v[120:123]
	v_mfma_f32_16x16x32_bf16 v[112:115], v[144:147], v[198:201], v[112:115]
	v_mfma_f32_16x16x32_bf16 v[104:107], v[166:169], v[198:201], v[104:107]
	v_mfma_f32_16x16x32_bf16 v[92:95], v[144:147], v[206:209], v[92:95]
	v_mfma_f32_16x16x32_bf16 v[88:91], v[166:169], v[206:209], v[88:91]
	v_mfma_f32_16x16x32_bf16 v[84:87], v[144:147], v[214:217], v[84:87]
	v_mfma_f32_16x16x32_bf16 v[80:83], v[166:169], v[214:217], v[80:83]
	v_mfma_f32_16x16x32_bf16 v[124:127], v[162:165], v[194:197], v[124:127]
	v_mfma_f32_16x16x32_bf16 v[120:123], v[170:173], v[194:197], v[120:123]
	v_mfma_f32_16x16x32_bf16 v[112:115], v[162:165], v[202:205], v[112:115]
	v_mfma_f32_16x16x32_bf16 v[104:107], v[170:173], v[202:205], v[104:107]
	v_mfma_f32_16x16x32_bf16 v[92:95], v[162:165], v[210:213], v[92:95]
	v_mfma_f32_16x16x32_bf16 v[88:91], v[170:173], v[210:213], v[88:91]
	v_mfma_f32_16x16x32_bf16 v[84:87], v[162:165], v[218:221], v[84:87]
	v_mfma_f32_16x16x32_bf16 v[80:83], v[170:173], v[218:221], v[80:83]
	s_setprio 0
	s_setprio 1
	v_mfma_f32_16x16x32_bf16 v[116:119], v[174:177], v[190:193], v[116:119]
	v_mfma_f32_16x16x32_bf16 v[108:111], v[182:185], v[190:193], v[108:111]
	v_mfma_f32_16x16x32_bf16 v[100:103], v[174:177], v[198:201], v[100:103]
	v_mfma_f32_16x16x32_bf16 v[96:99], v[182:185], v[198:201], v[96:99]
	v_mfma_f32_16x16x32_bf16 v[76:79], v[174:177], v[206:209], v[76:79]
	v_mfma_f32_16x16x32_bf16 v[72:75], v[182:185], v[206:209], v[72:75]
	v_mfma_f32_16x16x32_bf16 v[68:71], v[174:177], v[214:217], v[68:71]
	v_mfma_f32_16x16x32_bf16 v[64:67], v[182:185], v[214:217], v[64:67]
	v_mfma_f32_16x16x32_bf16 v[116:119], v[178:181], v[194:197], v[116:119]
	v_mfma_f32_16x16x32_bf16 v[108:111], v[186:189], v[194:197], v[108:111]
	v_mfma_f32_16x16x32_bf16 v[100:103], v[178:181], v[202:205], v[100:103]
	v_mfma_f32_16x16x32_bf16 v[96:99], v[186:189], v[202:205], v[96:99]
	v_mfma_f32_16x16x32_bf16 v[76:79], v[178:181], v[210:213], v[76:79]
	v_mfma_f32_16x16x32_bf16 v[72:75], v[186:189], v[210:213], v[72:75]
	v_mfma_f32_16x16x32_bf16 v[68:71], v[178:181], v[218:221], v[68:71]
	v_mfma_f32_16x16x32_bf16 v[64:67], v[186:189], v[218:221], v[64:67]
	s_setprio 0
	s_barrier
; #define PG8_STAGE(bufoff, gbase, voff) do { _Pragma("unroll") for (int _i = 0; _i < 2; ++_i) \
;         __builtin_amdgcn_global_load_lds((const unsigned*)((const char*)(gbase) + (voff)[_i]), (PG8_LAS unsigned*)(lds + (bufoff) + ldsw + _i * 8192), 16, 0, 0); } while (0)
; #define PG8_LDA(dst, b, h) do { _Pragma("unroll") for (int m = 0; m < 4; ++m) _Pragma("unroll") for (int k = 0; k < 2; ++k) dst[m][k] = *(const PG8_LAS bf16x8*)(lds + PG8_SA(b, h) + aoff + m * 2048 + k * 1024); } while (0)
; #define PG8_MMA(ai, bj, At, Bt) do { __builtin_amdgcn_s_setprio(1); _Pragma("unroll") for (int m = 0; m < 4; ++m) _Pragma("unroll") for (int n = 0; n < 2; ++n) _Pragma("unroll") for (int k = 0; k < 2; ++k) \
;         acc[ai][bj][m][n] = __builtin_amdgcn_mfma_f32_16x16x32_bf16(Bt[n][k], At[m][k], acc[ai][bj][m][n], 0, 0, 0); __builtin_amdgcn_s_setprio(0); } while (0)
; #define PG8_WAIT_V(n) asm volatile("s_waitcnt vmcnt(" #n ")" ::: "memory")
; #define PG8_BAR __builtin_amdgcn_s_barrier()
;     __device__ __forceinline__ void operator()(const f32x4 (&acc)[2][2][4][2], const Unit& u, int wr, int wc, int fr, int fq) const {
;         const int row0 = u.pm * BM + wr * 64 + fr, col0 = u.pn * BM + wc * 32 + 8 * fq;
;         const bf16_t* const G = (const bf16_t*)(ws + (ADD ? WS_GB : WS_GA)); bf16_t* const Mg = (bf16_t*)(ws + WS_GA);
; #pragma unroll
;         for (int ai = 0; ai < 2; ++ai)
; #pragma unroll
;         for (int mh = 0; mh < 4; mh += 2) {
;             u32x2 pg[4][2][2], pm_[4][2][2];
; #pragma unroll
;             for (int m = mh; m < mh + 2; ++m)
; #pragma unroll
;                 for (int bj = 0; bj < 2; ++bj)
; #pragma unroll
;                     for (int n = 0; n < 2; ++n) { const size_t off = (size_t)(row0 + ai * HALF + m * 16) * 1024 + col0 + bj * HALF + n * 4;
;                         pg[m][bj][n] = *(const u32x2*)(G + off); if (ADD) pm_[m][bj][n] = *(const u32x2*)(Mg + off); }
; template <class Epi, class Sched, bool ALIGN_EPI = false, bool SP2 = false>
; __device__ __forceinline__ void gemm_phase(PG8_LAS unsigned char* lds, const Gemm g, const Sched& S, const Epi& E) {
;     ...
;             PG8_LDA(At, 1, 1); PG8_STAGE(PG8_SB(1, 0), b3, voffB); PG8_STAGE(PG8_SB(1, 1), b3 + hstep, voffB); PG8_STAGE(PG8_SA(1, 0), a3, voffA);
;             PG8_WAIT_V(8); PG8_WAIT_L(0); PG8_BAR; PG8_MMA(1, 0, At, B0); PG8_MMA(1, 1, At, B1); PG8_BAR; PG8_SCHED;
	s_sleep 1
	s_add_i32 s46, s87, s49
	v_lshl_add_u64 v[222:223], v[222:223], 0, s[6:7]
	s_mov_b32 m0, s46
	ds_read_b128 v[190:193], v161 offset:49152
	ds_read_b128 v[194:197], v161 offset:50176
	ds_read_b128 v[198:201], v161 offset:51200
	ds_read_b128 v[202:205], v161 offset:52224
	ds_read_b128 v[206:209], v161 offset:53248
	ds_read_b128 v[210:213], v161 offset:54272
	ds_read_b128 v[214:217], v161 offset:55296
	ds_read_b128 v[218:221], v161 offset:56320
	global_load_lds_dwordx4 v[222:223], off
	s_add_i32 m0, s46, 0x2000
	s_add_u32 s44, s44, 0x20080
	v_lshl_add_u64 v[222:223], v[224:225], 0, s[6:7]
	s_addc_u32 s45, s45, 0
	s_add_i32 s46, s88, s49
	global_load_lds_dwordx4 v[222:223], off
	v_lshl_add_u64 v[222:223], s[44:45], 0, v[130:131]
	s_mov_b32 m0, s46
	s_nop 0
	global_load_lds_dwordx4 v[222:223], off
	v_lshl_add_u64 v[222:223], s[44:45], 0, v[134:135]
	s_add_i32 m0, s46, 0x2000
	s_nop 0
	global_load_lds_dwordx4 v[222:223], off
	v_lshl_add_u64 v[222:223], v[226:227], 0, s[6:7]
	s_mov_b32 m0, s61
	s_nop 0
	global_load_lds_dwordx4 v[222:223], off
	v_lshl_add_u64 v[222:223], v[228:229], 0, s[6:7]
	s_mov_b32 m0, s72
	s_nop 0
	global_load_lds_dwordx4 v[222:223], off
	s_waitcnt vmcnt(8)
	s_waitcnt lgkmcnt(0)
	s_barrier
	s_setprio 1
	s_waitcnt lgkmcnt(0)
	v_mfma_f32_16x16x32_bf16 v[60:63], v[144:147], v[190:193], v[60:63]
	v_mfma_f32_16x16x32_bf16 v[56:59], v[166:169], v[190:193], v[56:59]
	v_mfma_f32_16x16x32_bf16 v[52:55], v[144:147], v[198:201], v[52:55]
	v_mfma_f32_16x16x32_bf16 v[48:51], v[166:169], v[198:201], v[48:51]
	v_mfma_f32_16x16x32_bf16 v[28:31], v[144:147], v[206:209], v[28:31]
	v_mfma_f32_16x16x32_bf16 v[24:27], v[166:169], v[206:209], v[24:27]
	v_mfma_f32_16x16x32_bf16 v[20:23], v[144:147], v[214:217], v[20:23]
	v_mfma_f32_16x16x32_bf16 v[16:19], v[166:169], v[214:217], v[16:19]
	v_mfma_f32_16x16x32_bf16 v[60:63], v[162:165], v[194:197], v[60:63]
	v_mfma_f32_16x16x32_bf16 v[56:59], v[170:173], v[194:197], v[56:59]
	v_mfma_f32_16x16x32_bf16 v[52:55], v[162:165], v[202:205], v[52:55]
	v_mfma_f32_16x16x32_bf16 v[48:51], v[170:173], v[202:205], v[48:51]
	v_mfma_f32_16x16x32_bf16 v[28:31], v[162:165], v[210:213], v[28:31]
	v_mfma_f32_16x16x32_bf16 v[24:27], v[170:173], v[210:213], v[24:27]
	v_mfma_f32_16x16x32_bf16 v[20:23], v[162:165], v[218:221], v[20:23]
	v_mfma_f32_16x16x32_bf16 v[16:19], v[170:173], v[218:221], v[16:19]
	s_setprio 0
	s_setprio 1
	v_mfma_f32_16x16x32_bf16 v[44:47], v[174:177], v[190:193], v[44:47]
	v_mfma_f32_16x16x32_bf16 v[40:43], v[182:185], v[190:193], v[40:43]
	v_mfma_f32_16x16x32_bf16 v[36:39], v[174:177], v[198:201], v[36:39]
	v_mfma_f32_16x16x32_bf16 v[32:35], v[182:185], v[198:201], v[32:35]
	v_mfma_f32_16x16x32_bf16 v[12:15], v[174:177], v[206:209], v[12:15]
	v_mfma_f32_16x16x32_bf16 v[8:11], v[182:185], v[206:209], v[8:11]
	v_mfma_f32_16x16x32_bf16 v[4:7], v[174:177], v[214:217], v[4:7]
	v_mfma_f32_16x16x32_bf16 v[0:3], v[182:185], v[214:217], v[0:3]
	v_mfma_f32_16x16x32_bf16 v[44:47], v[178:181], v[194:197], v[44:47]
	v_mfma_f32_16x16x32_bf16 v[40:43], v[186:189], v[194:197], v[40:43]
	v_mfma_f32_16x16x32_bf16 v[36:39], v[178:181], v[202:205], v[36:39]
	v_mfma_f32_16x16x32_bf16 v[32:35], v[186:189], v[202:205], v[32:35]
	v_mfma_f32_16x16x32_bf16 v[12:15], v[178:181], v[210:213], v[12:15]
	v_mfma_f32_16x16x32_bf16 v[8:11], v[186:189], v[210:213], v[8:11]
	v_mfma_f32_16x16x32_bf16 v[4:7], v[178:181], v[218:221], v[4:7]
	v_mfma_f32_16x16x32_bf16 v[0:3], v[186:189], v[218:221], v[0:3]
	s_setprio 0
	s_barrier
	s_sleep 1
	s_add_i32 s86, s86, 2
	s_add_u32 s42, s42, 0x100
	s_addc_u32 s43, s43, 0
	s_add_u32 s84, s84, 0x100
	s_addc_u32 s85, s85, 0
	s_cmp_gt_u32 s86, 5
	s_cbranch_scc0 .LBB0_735
	v_lshl_add_u32 v178, s40, 8, v156
	v_lshl_or_b32 v144, s81, 8, v158
	v_ashrrev_i32_e32 v145, 31, v144
	v_ashrrev_i32_e32 v179, 31, v178
	v_lshl_add_u64 v[180:181], v[144:145], 1, s[0:1]
	v_lshlrev_b64 v[144:145], 11, v[178:179]
	v_or_b32_e32 v146, 16, v178
	v_lshl_add_u64 v[144:145], v[180:181], 0, v[144:145]
	v_ashrrev_i32_e32 v147, 31, v146
	global_load_dwordx4 v[162:165], v[144:145], off
	global_load_dwordx4 v[166:169], v[144:145], off offset:256
	v_lshlrev_b64 v[146:147], 11, v[146:147]
	v_lshl_add_u64 v[182:183], v[180:181], 0, v[146:147]
	global_load_dwordx4 v[170:173], v[182:183], off
	global_load_dwordx4 v[174:177], v[182:183], off offset:256
	v_or_b32_e32 v146, 32, v178
	v_ashrrev_i32_e32 v147, 31, v146
	v_lshlrev_b64 v[146:147], 11, v[146:147]
	v_lshl_add_u64 v[146:147], v[180:181], 0, v[146:147]
	s_mov_b32 s81, s24
	s_mov_b32 s40, s26
	s_mov_b64 s[44:45], s[38:39]
	s_mov_b64 s[42:43], s[36:37]
	s_waitcnt vmcnt(0)
; __device__ __forceinline__ u32x2 pack4(f32x4 v) { u32x2 w; w.x = cvt_pk_bf16(v[0], v[1]); w.y = cvt_pk_bf16(v[2], v[3]); return w; }
; __device__ __forceinline__ f32x4 unpack4(u32x2 w) { f32x4 v; v[0] = __uint_as_float(w.x << 16); v[1] = __uint_as_float(w.x & 0xffff0000u); v[2] = __uint_as_float(w.y << 16); v[3] = __uint_as_float(w.y & 0xffff0000u); return v; }
;     __device__ __forceinline__ void operator()(const f32x4 (&acc)[2][2][4][2], const Unit& u, int wr, int wc, int fr, int fq) const {
;     ...
;                     for (int n = 0; n < 2; ++n) { const size_t off = (size_t)(row0 + ai * HALF + m * 16) * 1024 + col0 + bj * HALF + n * 4;
;                         pg[m][bj][n] = *(const u32x2*)(G + off); if (ADD) pm_[m][bj][n] = *(const u32x2*)(Mg + off); }
;             asm volatile("" ::: "memory");
; #pragma unroll
;             for (int m = mh; m < mh + 2; ++m)
; #pragma unroll
;                 for (int bj = 0; bj < 2; ++bj)
; #pragma unroll
;                     for (int n = 0; n < 2; ++n) { const size_t off = (size_t)(row0 + ai * HALF + m * 16) * 1024 + col0 + bj * HALF + n * 4;
;                         f32x4 o = unpack4(pg[m][bj][n]) * acc[ai][bj][m][n]; if (ADD) o = o + unpack4(pm_[m][bj][n]);
;                         *(u32x2*)(Mg + off) = pack4(o); }
	v_lshlrev_b32_e32 v184, 16, v162
	v_and_b32_e32 v185, 0xffff0000, v162
	v_lshlrev_b32_e32 v162, 16, v163
	v_and_b32_e32 v163, 0xffff0000, v163
	v_lshlrev_b32_e32 v188, 16, v166
	v_and_b32_e32 v189, 0xffff0000, v166
	v_lshlrev_b32_e32 v166, 16, v167
	v_and_b32_e32 v167, 0xffff0000, v167
	v_lshlrev_b32_e32 v190, 16, v168
	v_and_b32_e32 v191, 0xffff0000, v168
	v_lshlrev_b32_e32 v168, 16, v169
	v_and_b32_e32 v169, 0xffff0000, v169
	v_lshlrev_b32_e32 v186, 16, v164
	v_and_b32_e32 v187, 0xffff0000, v164
	v_lshlrev_b32_e32 v164, 16, v165
	v_and_b32_e32 v165, 0xffff0000, v165
	v_pk_mul_f32 v[126:127], v[126:127], v[162:163]
	v_pk_mul_f32 v[118:119], v[118:119], v[166:167]
	v_pk_mul_f32 v[162:163], v[110:111], v[168:169]
	v_lshlrev_b32_e32 v166, 16, v170
	v_and_b32_e32 v167, 0xffff0000, v170
	v_lshlrev_b32_e32 v168, 16, v171
	v_and_b32_e32 v169, 0xffff0000, v171
	v_lshlrev_b32_e32 v170, 16, v172
	v_and_b32_e32 v171, 0xffff0000, v172
	v_lshlrev_b32_e32 v172, 16, v173
	v_and_b32_e32 v173, 0xffff0000, v173
	v_pk_mul_f32 v[124:125], v[124:125], v[184:185]
	v_pk_mul_f32 v[122:123], v[122:123], v[164:165]
	v_pk_mul_f32 v[120:121], v[120:121], v[186:187]
	v_lshlrev_b32_e32 v184, 16, v174
	v_and_b32_e32 v185, 0xffff0000, v174
	v_lshlrev_b32_e32 v174, 16, v175
	v_and_b32_e32 v175, 0xffff0000, v175
	v_lshlrev_b32_e32 v186, 16, v176
	v_and_b32_e32 v187, 0xffff0000, v176
	v_lshlrev_b32_e32 v176, 16, v177
	v_and_b32_e32 v177, 0xffff0000, v177
	v_pk_mul_f32 v[114:115], v[114:115], v[168:169]
	v_pk_mul_f32 v[112:113], v[112:113], v[166:167]
	v_pk_mul_f32 v[106:107], v[106:107], v[172:173]
	v_pk_mul_f32 v[104:105], v[104:105], v[170:171]
	v_pk_mul_f32 v[116:117], v[116:117], v[188:189]
	v_pk_mul_f32 v[164:165], v[108:109], v[190:191]
	v_cvt_pk_bf16_f32 v108, v124, v125
	v_cvt_pk_bf16_f32 v109, v126, v127
	v_cvt_pk_bf16_f32 v110, v120, v121
	v_cvt_pk_bf16_f32 v111, v122, v123
	v_pk_mul_f32 v[102:103], v[102:103], v[174:175]
	v_pk_mul_f32 v[100:101], v[100:101], v[184:185]
	v_pk_mul_f32 v[120:121], v[98:99], v[176:177]
	v_pk_mul_f32 v[122:123], v[96:97], v[186:187]
	v_cvt_pk_bf16_f32 v96, v112, v113
	v_cvt_pk_bf16_f32 v97, v114, v115
	v_cvt_pk_bf16_f32 v98, v104, v105
	v_cvt_pk_bf16_f32 v99, v106, v107
	v_cvt_pk_bf16_f32 v116, v116, v117
	v_cvt_pk_bf16_f32 v117, v118, v119
	v_cvt_pk_bf16_f32 v118, v164, v165
	v_cvt_pk_bf16_f32 v119, v162, v163
	global_store_dwordx4 v[144:145], v[108:111], off
	global_store_dwordx4 v[144:145], v[116:119], off offset:256
	v_cvt_pk_bf16_f32 v100, v100, v101
	v_cvt_pk_bf16_f32 v101, v102, v103
	v_cvt_pk_bf16_f32 v102, v122, v123
	v_cvt_pk_bf16_f32 v103, v120, v121
	global_store_dwordx4 v[182:183], v[96:99], off
	global_store_dwordx4 v[182:183], v[100:103], off offset:256
	global_load_dwordx4 v[98:101], v[146:147], off
	global_load_dwordx4 v[102:105], v[146:147], off offset:256
	v_or_b32_e32 v96, 48, v178
	v_ashrrev_i32_e32 v97, 31, v96
	v_lshlrev_b64 v[96:97], 11, v[96:97]
	v_lshl_add_u64 v[114:115], v[180:181], 0, v[96:97]
	global_load_dwordx4 v[106:109], v[114:115], off
	global_load_dwordx4 v[110:113], v[114:115], off offset:256
	v_add_co_u32_e32 v96, vcc, s77, v144
	s_waitcnt vmcnt(3)
	v_lshlrev_b32_e32 v116, 16, v98
	v_and_b32_e32 v117, 0xffff0000, v98
	v_lshlrev_b32_e32 v98, 16, v99
	v_and_b32_e32 v99, 0xffff0000, v99
	v_lshlrev_b32_e32 v118, 16, v100
	v_and_b32_e32 v119, 0xffff0000, v100
	v_lshlrev_b32_e32 v100, 16, v101
	v_and_b32_e32 v101, 0xffff0000, v101
	s_waitcnt vmcnt(2)
	v_lshlrev_b32_e32 v120, 16, v102
	v_and_b32_e32 v121, 0xffff0000, v102
	v_lshlrev_b32_e32 v102, 16, v103
	v_and_b32_e32 v103, 0xffff0000, v103
	v_lshlrev_b32_e32 v122, 16, v104
	v_and_b32_e32 v123, 0xffff0000, v104
	v_lshlrev_b32_e32 v104, 16, v105
	v_and_b32_e32 v105, 0xffff0000, v105
	s_waitcnt vmcnt(1)
	v_lshlrev_b32_e32 v124, 16, v106
	v_and_b32_e32 v125, 0xffff0000, v106
	v_lshlrev_b32_e32 v106, 16, v107
	v_and_b32_e32 v107, 0xffff0000, v107
	v_lshlrev_b32_e32 v126, 16, v108
	v_and_b32_e32 v127, 0xffff0000, v108
	v_lshlrev_b32_e32 v108, 16, v109
	v_and_b32_e32 v109, 0xffff0000, v109
	s_waitcnt vmcnt(0)
	v_lshlrev_b32_e32 v162, 16, v110
	v_and_b32_e32 v163, 0xffff0000, v110
	v_lshlrev_b32_e32 v110, 16, v111
	v_and_b32_e32 v111, 0xffff0000, v111
	v_lshlrev_b32_e32 v164, 16, v112
	v_and_b32_e32 v165, 0xffff0000, v112
	v_lshlrev_b32_e32 v112, 16, v113
	v_and_b32_e32 v113, 0xffff0000, v113
	v_pk_mul_f32 v[94:95], v[94:95], v[98:99]
	v_pk_mul_f32 v[92:93], v[92:93], v[116:117]
	v_pk_mul_f32 v[90:91], v[90:91], v[100:101]
	v_pk_mul_f32 v[88:89], v[88:89], v[118:119]
	v_pk_mul_f32 v[78:79], v[78:79], v[102:103]
	v_pk_mul_f32 v[76:77], v[76:77], v[120:121]
	v_pk_mul_f32 v[74:75], v[74:75], v[104:105]
	v_pk_mul_f32 v[72:73], v[72:73], v[122:123]
	v_pk_mul_f32 v[86:87], v[86:87], v[106:107]
	v_pk_mul_f32 v[84:85], v[84:85], v[124:125]
	v_pk_mul_f32 v[82:83], v[82:83], v[108:109]
	v_pk_mul_f32 v[80:81], v[80:81], v[126:127]
	v_pk_mul_f32 v[98:99], v[70:71], v[110:111]
	v_pk_mul_f32 v[100:101], v[68:69], v[162:163]
	v_pk_mul_f32 v[102:103], v[66:67], v[112:113]
	v_pk_mul_f32 v[104:105], v[64:65], v[164:165]
	v_cvt_pk_bf16_f32 v64, v92, v93
	v_cvt_pk_bf16_f32 v65, v94, v95
	v_cvt_pk_bf16_f32 v66, v88, v89
	v_cvt_pk_bf16_f32 v67, v90, v91
	v_addc_co_u32_e32 v97, vcc, 0, v145, vcc
	v_cvt_pk_bf16_f32 v68, v76, v77
	v_cvt_pk_bf16_f32 v69, v78, v79
	v_cvt_pk_bf16_f32 v70, v72, v73
	v_cvt_pk_bf16_f32 v71, v74, v75
	v_cvt_pk_bf16_f32 v72, v84, v85
	v_cvt_pk_bf16_f32 v73, v86, v87
	v_cvt_pk_bf16_f32 v74, v80, v81
	v_cvt_pk_bf16_f32 v75, v82, v83
	v_cvt_pk_bf16_f32 v76, v100, v101
	v_cvt_pk_bf16_f32 v77, v98, v99
	v_cvt_pk_bf16_f32 v78, v104, v105
	v_cvt_pk_bf16_f32 v79, v102, v103
	global_store_dwordx4 v[146:147], v[64:67], off
	global_store_dwordx4 v[146:147], v[68:71], off offset:256
	global_store_dwordx4 v[114:115], v[72:75], off
	global_store_dwordx4 v[114:115], v[76:79], off offset:256
	v_add_co_u32_e32 v84, vcc, s78, v144
	global_load_dwordx4 v[66:69], v[96:97], off
	v_lshl_add_u64 v[82:83], v[144:145], 0, s[12:13]
	v_addc_co_u32_e32 v85, vcc, 0, v145, vcc
	v_lshl_add_u64 v[86:87], v[144:145], 0, s[14:15]
	global_load_dwordx4 v[70:73], v[82:83], off offset:256
	global_load_dwordx4 v[74:77], v[84:85], off
	global_load_dwordx4 v[78:81], v[86:87], off offset:256
	v_add_co_u32_e32 v64, vcc, s79, v144
	s_waitcnt vmcnt(3)
; __device__ __forceinline__ u32x2 pack4(f32x4 v) { u32x2 w; w.x = cvt_pk_bf16(v[0], v[1]); w.y = cvt_pk_bf16(v[2], v[3]); return w; }
; __device__ __forceinline__ f32x4 unpack4(u32x2 w) { f32x4 v; v[0] = __uint_as_float(w.x << 16); v[1] = __uint_as_float(w.x & 0xffff0000u); v[2] = __uint_as_float(w.y << 16); v[3] = __uint_as_float(w.y & 0xffff0000u); return v; }
; #define PG8_WAIT_V(n) asm volatile("s_waitcnt vmcnt(" #n ")" ::: "memory")
; #define PG8_BAR __builtin_amdgcn_s_barrier()
;     __device__ __forceinline__ void operator()(const f32x4 (&acc)[2][2][4][2], const Unit& u, int wr, int wc, int fr, int fq) const {
;     ...
;             for (int m = mh; m < mh + 2; ++m)
; #pragma unroll
;                 for (int bj = 0; bj < 2; ++bj)
; #pragma unroll
;                     for (int n = 0; n < 2; ++n) { const size_t off = (size_t)(row0 + ai * HALF + m * 16) * 1024 + col0 + bj * HALF + n * 4;
;                         f32x4 o = unpack4(pg[m][bj][n]) * acc[ai][bj][m][n]; if (ADD) o = o + unpack4(pm_[m][bj][n]);
;                         *(u32x2*)(Mg + off) = pack4(o); }
; template <class Epi, class Sched, bool ALIGN_EPI = false, bool SP2 = false>
; __device__ __forceinline__ void gemm_phase(PG8_LAS unsigned char* lds, const Gemm g, const Sched& S, const Epi& E) {
;     ...
;     PG8_WAIT_V(0);
;     if constexpr (!ALIGN_EPI) { if (wr == 0) PG8_BAR; }
;     PG8_BAR;
	v_lshlrev_b32_e32 v88, 16, v66
	v_and_b32_e32 v89, 0xffff0000, v66
	v_lshlrev_b32_e32 v66, 16, v67
	v_and_b32_e32 v67, 0xffff0000, v67
	v_lshlrev_b32_e32 v90, 16, v68
	v_and_b32_e32 v91, 0xffff0000, v68
	v_lshlrev_b32_e32 v68, 16, v69
	v_and_b32_e32 v69, 0xffff0000, v69
	s_waitcnt vmcnt(2)
	v_lshlrev_b32_e32 v92, 16, v70
	v_and_b32_e32 v93, 0xffff0000, v70
	v_lshlrev_b32_e32 v70, 16, v71
	v_and_b32_e32 v71, 0xffff0000, v71
	v_lshlrev_b32_e32 v94, 16, v72
	v_and_b32_e32 v95, 0xffff0000, v72
	v_lshlrev_b32_e32 v72, 16, v73
	v_and_b32_e32 v73, 0xffff0000, v73
	s_waitcnt vmcnt(1)
	v_lshlrev_b32_e32 v98, 16, v74
	v_and_b32_e32 v99, 0xffff0000, v74
	v_lshlrev_b32_e32 v74, 16, v75
	v_and_b32_e32 v75, 0xffff0000, v75
	v_lshlrev_b32_e32 v100, 16, v76
	v_and_b32_e32 v101, 0xffff0000, v76
	v_lshlrev_b32_e32 v76, 16, v77
	v_and_b32_e32 v77, 0xffff0000, v77
	s_waitcnt vmcnt(0)
	v_lshlrev_b32_e32 v102, 16, v78
	v_and_b32_e32 v103, 0xffff0000, v78
	v_lshlrev_b32_e32 v78, 16, v79
	v_and_b32_e32 v79, 0xffff0000, v79
	v_lshlrev_b32_e32 v104, 16, v80
	v_and_b32_e32 v105, 0xffff0000, v80
	v_lshlrev_b32_e32 v80, 16, v81
	v_and_b32_e32 v81, 0xffff0000, v81
	v_pk_mul_f32 v[62:63], v[62:63], v[66:67]
	v_pk_mul_f32 v[60:61], v[60:61], v[88:89]
	v_pk_mul_f32 v[58:59], v[58:59], v[68:69]
	v_pk_mul_f32 v[56:57], v[56:57], v[90:91]
	v_pk_mul_f32 v[46:47], v[46:47], v[70:71]
	v_pk_mul_f32 v[44:45], v[44:45], v[92:93]
	v_pk_mul_f32 v[42:43], v[42:43], v[72:73]
	v_pk_mul_f32 v[40:41], v[40:41], v[94:95]
	v_pk_mul_f32 v[54:55], v[54:55], v[74:75]
	v_pk_mul_f32 v[52:53], v[52:53], v[98:99]
	v_pk_mul_f32 v[50:51], v[50:51], v[76:77]
	v_pk_mul_f32 v[48:49], v[48:49], v[100:101]
	v_pk_mul_f32 v[66:67], v[38:39], v[78:79]
	v_pk_mul_f32 v[68:69], v[36:37], v[102:103]
	v_pk_mul_f32 v[70:71], v[34:35], v[80:81]
	v_pk_mul_f32 v[72:73], v[32:33], v[104:105]
	v_cvt_pk_bf16_f32 v32, v60, v61
	v_cvt_pk_bf16_f32 v33, v62, v63
	v_cvt_pk_bf16_f32 v34, v56, v57
	v_cvt_pk_bf16_f32 v35, v58, v59
	v_addc_co_u32_e32 v65, vcc, 0, v145, vcc
	v_cvt_pk_bf16_f32 v36, v44, v45
	v_cvt_pk_bf16_f32 v37, v46, v47
	v_cvt_pk_bf16_f32 v38, v40, v41
	v_cvt_pk_bf16_f32 v39, v42, v43
	v_cvt_pk_bf16_f32 v40, v52, v53
	v_cvt_pk_bf16_f32 v41, v54, v55
	v_cvt_pk_bf16_f32 v42, v48, v49
	v_cvt_pk_bf16_f32 v43, v50, v51
	v_cvt_pk_bf16_f32 v44, v68, v69
	v_cvt_pk_bf16_f32 v45, v66, v67
	v_cvt_pk_bf16_f32 v46, v72, v73
	v_cvt_pk_bf16_f32 v47, v70, v71
	global_store_dwordx4 v[96:97], v[32:35], off
	global_store_dwordx4 v[82:83], v[36:39], off offset:256
	global_store_dwordx4 v[84:85], v[40:43], off
	global_store_dwordx4 v[86:87], v[44:47], off offset:256
	v_add_co_u32_e32 v50, vcc, s80, v144
	global_load_dwordx4 v[32:35], v[64:65], off
	v_lshl_add_u64 v[48:49], v[144:145], 0, s[20:21]
	v_addc_co_u32_e32 v51, vcc, 0, v145, vcc
	v_lshl_add_u64 v[52:53], v[144:145], 0, s[22:23]
	global_load_dwordx4 v[36:39], v[48:49], off offset:256
	global_load_dwordx4 v[40:43], v[50:51], off
	global_load_dwordx4 v[44:47], v[52:53], off offset:256
	s_and_b64 vcc, exec, s[2:3]
	s_waitcnt vmcnt(3)
	v_lshlrev_b32_e32 v54, 16, v32
	v_and_b32_e32 v55, 0xffff0000, v32
	v_lshlrev_b32_e32 v32, 16, v33
	v_and_b32_e32 v33, 0xffff0000, v33
	v_lshlrev_b32_e32 v56, 16, v34
	v_and_b32_e32 v57, 0xffff0000, v34
	v_lshlrev_b32_e32 v34, 16, v35
	v_and_b32_e32 v35, 0xffff0000, v35
	s_waitcnt vmcnt(2)
	v_lshlrev_b32_e32 v58, 16, v36
	v_and_b32_e32 v59, 0xffff0000, v36
	v_lshlrev_b32_e32 v36, 16, v37
	v_and_b32_e32 v37, 0xffff0000, v37
	v_lshlrev_b32_e32 v60, 16, v38
	v_and_b32_e32 v61, 0xffff0000, v38
	v_lshlrev_b32_e32 v38, 16, v39
	v_and_b32_e32 v39, 0xffff0000, v39
	s_waitcnt vmcnt(1)
	v_lshlrev_b32_e32 v62, 16, v40
	v_and_b32_e32 v63, 0xffff0000, v40
	v_lshlrev_b32_e32 v40, 16, v41
	v_and_b32_e32 v41, 0xffff0000, v41
	v_lshlrev_b32_e32 v66, 16, v42
	v_and_b32_e32 v67, 0xffff0000, v42
	v_lshlrev_b32_e32 v42, 16, v43
	v_and_b32_e32 v43, 0xffff0000, v43
	s_waitcnt vmcnt(0)
	v_lshlrev_b32_e32 v68, 16, v44
	v_and_b32_e32 v69, 0xffff0000, v44
	v_lshlrev_b32_e32 v44, 16, v45
	v_and_b32_e32 v45, 0xffff0000, v45
	v_lshlrev_b32_e32 v70, 16, v46
	v_and_b32_e32 v71, 0xffff0000, v46
	v_lshlrev_b32_e32 v46, 16, v47
	v_and_b32_e32 v47, 0xffff0000, v47
	v_pk_mul_f32 v[30:31], v[30:31], v[32:33]
	v_pk_mul_f32 v[28:29], v[28:29], v[54:55]
	v_pk_mul_f32 v[26:27], v[26:27], v[34:35]
	v_pk_mul_f32 v[24:25], v[24:25], v[56:57]
	v_pk_mul_f32 v[14:15], v[14:15], v[36:37]
	v_pk_mul_f32 v[12:13], v[12:13], v[58:59]
	v_pk_mul_f32 v[10:11], v[10:11], v[38:39]
	v_pk_mul_f32 v[8:9], v[8:9], v[60:61]
	v_pk_mul_f32 v[22:23], v[22:23], v[40:41]
	v_pk_mul_f32 v[20:21], v[20:21], v[62:63]
	v_pk_mul_f32 v[18:19], v[18:19], v[42:43]
	v_pk_mul_f32 v[16:17], v[16:17], v[66:67]
	v_pk_mul_f32 v[32:33], v[6:7], v[44:45]
	v_pk_mul_f32 v[34:35], v[4:5], v[68:69]
	v_pk_mul_f32 v[36:37], v[2:3], v[46:47]
	v_pk_mul_f32 v[38:39], v[0:1], v[70:71]
	v_cvt_pk_bf16_f32 v0, v28, v29
	v_cvt_pk_bf16_f32 v1, v30, v31
	v_cvt_pk_bf16_f32 v2, v24, v25
	v_cvt_pk_bf16_f32 v3, v26, v27
	v_cvt_pk_bf16_f32 v4, v12, v13
	v_cvt_pk_bf16_f32 v5, v14, v15
	v_cvt_pk_bf16_f32 v6, v8, v9
	v_cvt_pk_bf16_f32 v7, v10, v11
	v_cvt_pk_bf16_f32 v8, v20, v21
	v_cvt_pk_bf16_f32 v9, v22, v23
	v_cvt_pk_bf16_f32 v10, v16, v17
	v_cvt_pk_bf16_f32 v11, v18, v19
	v_cvt_pk_bf16_f32 v12, v34, v35
	v_cvt_pk_bf16_f32 v13, v32, v33
	v_cvt_pk_bf16_f32 v14, v38, v39
	v_cvt_pk_bf16_f32 v15, v36, v37
	global_store_dwordx4 v[64:65], v[0:3], off
	global_store_dwordx4 v[48:49], v[4:7], off offset:256
	global_store_dwordx4 v[50:51], v[8:11], off
	global_store_dwordx4 v[52:53], v[12:15], off offset:256
	s_cbranch_vccz .LBB0_732
	s_waitcnt vmcnt(0)
	s_cmpk_gt_u32 s48, 0xff
	s_cbranch_scc1 .LBB0_739
	s_barrier

; #define PG8_STAGE(bufoff, gbase, voff) do { _Pragma("unroll") for (int _i = 0; _i < 2; ++_i) \
;         __builtin_amdgcn_global_load_lds((const unsigned*)((const char*)(gbase) + (voff)[_i]), (PG8_LAS unsigned*)(lds + (bufoff) + ldsw + _i * 8192), 16, 0, 0); } while (0)
; #define PG8_LDA(dst, b, h) do { _Pragma("unroll") for (int m = 0; m < 4; ++m) _Pragma("unroll") for (int k = 0; k < 2; ++k) dst[m][k] = *(const PG8_LAS bf16x8*)(lds + PG8_SA(b, h) + aoff + m * 2048 + k * 1024); } while (0)
; #define PG8_LDB(dst, b, h) do { _Pragma("unroll") for (int n = 0; n < 2; ++n) _Pragma("unroll") for (int k = 0; k < 2; ++k) dst[n][k] = *(const PG8_LAS bf16x8*)(lds + PG8_SB(b, h) + boff + n * 2048 + k * 1024); } while (0)
; #define PG8_MMA(ai, bj, At, Bt) do { __builtin_amdgcn_s_setprio(1); _Pragma("unroll") for (int m = 0; m < 4; ++m) _Pragma("unroll") for (int n = 0; n < 2; ++n) _Pragma("unroll") for (int k = 0; k < 2; ++k) \
;         acc[ai][bj][m][n] = __builtin_amdgcn_mfma_f32_16x16x32_bf16(Bt[n][k], At[m][k], acc[ai][bj][m][n], 0, 0, 0); __builtin_amdgcn_s_setprio(0); } while (0)
; #define PG8_WAIT_V(n) asm volatile("s_waitcnt vmcnt(" #n ")" ::: "memory")
; #define PG8_WAIT_L(n) asm volatile("s_waitcnt lgkmcnt(" #n ")" ::: "memory")
; #define PG8_BAR __builtin_amdgcn_s_barrier()
; #define PG8_SCHED __builtin_amdgcn_sched_barrier(0)
; template <class Epi, class Sched, bool ALIGN_EPI = false, bool SP2 = false>
; __device__ __forceinline__ void gemm_phase(PG8_LAS unsigned char* lds, const Gemm g, const Sched& S, const Epi& E) {
;     ...
;             PG8_LDB(B0, 0, 0); PG8_LDB(B1, 0, 1); PG8_SCHED; PG8_LDA(At, 0, 0); PG8_STAGE(PG8_SA(1, 1), a1 + hstep, voffA);
;             PG8_WAIT_V(8); PG8_WAIT_L(0); PG8_BAR; PG8_MMA(0, 0, At, B0); PG8_MMA(0, 1, At, B1); PG8_BAR; PG8_SCHED;
;             PG8_LDA(At, 0, 1); PG8_STAGE(PG8_SB(0, 0), b2, voffB); PG8_STAGE(PG8_SB(0, 1), b2 + hstep, voffB); PG8_STAGE(PG8_SA(0, 0), a2, voffA);
;             PG8_WAIT_V(8); PG8_WAIT_L(0); PG8_BAR; PG8_MMA(1, 0, At, B0); PG8_MMA(1, 1, At, B1); PG8_BAR; PG8_SCHED;
.LBB0_747:
	ds_read_b128 v[144:147], v150
	ds_read_b128 v[158:161], v150 offset:1024
	ds_read_b128 v[162:165], v150 offset:2048
	ds_read_b128 v[166:169], v150 offset:3072
	ds_read_b128 v[170:173], v152
	ds_read_b128 v[174:177], v152 offset:1024
	ds_read_b128 v[178:181], v152 offset:2048
	ds_read_b128 v[182:185], v152 offset:3072
	s_add_u32 s36, s26, 0xfffe0080
	s_addc_u32 s37, s27, -1
	s_cmp_eq_u32 s72, 4
	s_cselect_b32 s39, s15, s37
	s_cselect_b32 s38, s60, s36
	s_cselect_b32 s37, s13, s71
	s_cselect_b32 s36, s61, s70
	v_lshl_add_u64 v[148:149], s[26:27], 0, v[136:137]
	s_add_i32 m0, s25, 0xc000
	ds_read_b128 v[186:189], v154
	ds_read_b128 v[190:193], v154 offset:1024
	ds_read_b128 v[194:197], v154 offset:2048
	ds_read_b128 v[198:201], v154 offset:3072
	ds_read_b128 v[202:205], v154 offset:4096
	ds_read_b128 v[206:209], v154 offset:5120
	ds_read_b128 v[210:213], v154 offset:6144
	ds_read_b128 v[214:217], v154 offset:7168
	global_load_lds_dwordx4 v[148:149], off
	v_lshl_add_u64 v[148:149], s[26:27], 0, v[138:139]
	s_add_i32 m0, s25, 0xe000
	s_nop 0
	global_load_lds_dwordx4 v[148:149], off
	s_waitcnt vmcnt(8)
	s_waitcnt lgkmcnt(0)
	s_barrier
	s_setprio 1
	s_waitcnt lgkmcnt(0)
	v_mfma_f32_16x16x32_bf16 v[124:127], v[144:147], v[186:189], v[124:127]
	v_mfma_f32_16x16x32_bf16 v[120:123], v[162:165], v[186:189], v[120:123]
	v_mfma_f32_16x16x32_bf16 v[116:119], v[144:147], v[194:197], v[116:119]
	v_mfma_f32_16x16x32_bf16 v[104:107], v[162:165], v[194:197], v[104:107]
	v_mfma_f32_16x16x32_bf16 v[92:95], v[144:147], v[202:205], v[92:95]
	v_mfma_f32_16x16x32_bf16 v[88:91], v[162:165], v[202:205], v[88:91]
	v_mfma_f32_16x16x32_bf16 v[80:83], v[144:147], v[210:213], v[80:83]
	v_mfma_f32_16x16x32_bf16 v[72:75], v[162:165], v[210:213], v[72:75]
	v_mfma_f32_16x16x32_bf16 v[124:127], v[158:161], v[190:193], v[124:127]
	v_mfma_f32_16x16x32_bf16 v[120:123], v[166:169], v[190:193], v[120:123]
	v_mfma_f32_16x16x32_bf16 v[116:119], v[158:161], v[198:201], v[116:119]
	v_mfma_f32_16x16x32_bf16 v[104:107], v[166:169], v[198:201], v[104:107]
	v_mfma_f32_16x16x32_bf16 v[92:95], v[158:161], v[206:209], v[92:95]
	v_mfma_f32_16x16x32_bf16 v[88:91], v[166:169], v[206:209], v[88:91]
	v_mfma_f32_16x16x32_bf16 v[80:83], v[158:161], v[214:217], v[80:83]
	v_mfma_f32_16x16x32_bf16 v[72:75], v[166:169], v[214:217], v[72:75]
	s_setprio 0
	s_setprio 1
	v_mfma_f32_16x16x32_bf16 v[112:115], v[170:173], v[186:189], v[112:115]
	v_mfma_f32_16x16x32_bf16 v[108:111], v[178:181], v[186:189], v[108:111]
	v_mfma_f32_16x16x32_bf16 v[100:103], v[170:173], v[194:197], v[100:103]
	v_mfma_f32_16x16x32_bf16 v[96:99], v[178:181], v[194:197], v[96:99]
	v_mfma_f32_16x16x32_bf16 v[84:87], v[170:173], v[202:205], v[84:87]
	v_mfma_f32_16x16x32_bf16 v[76:79], v[178:181], v[202:205], v[76:79]
	v_mfma_f32_16x16x32_bf16 v[68:71], v[170:173], v[210:213], v[68:71]
	v_mfma_f32_16x16x32_bf16 v[64:67], v[178:181], v[210:213], v[64:67]
	v_mfma_f32_16x16x32_bf16 v[112:115], v[174:177], v[190:193], v[112:115]
	v_mfma_f32_16x16x32_bf16 v[108:111], v[182:185], v[190:193], v[108:111]
	v_mfma_f32_16x16x32_bf16 v[100:103], v[174:177], v[198:201], v[100:103]
	v_mfma_f32_16x16x32_bf16 v[96:99], v[182:185], v[198:201], v[96:99]
	v_mfma_f32_16x16x32_bf16 v[84:87], v[174:177], v[206:209], v[84:87]
	v_mfma_f32_16x16x32_bf16 v[76:79], v[182:185], v[206:209], v[76:79]
	v_mfma_f32_16x16x32_bf16 v[68:71], v[174:177], v[214:217], v[68:71]
	v_mfma_f32_16x16x32_bf16 v[64:67], v[182:185], v[214:217], v[64:67]
	s_setprio 0
	s_barrier
	s_sleep 1
	s_add_i32 s73, s51, s41
	v_lshl_add_u64 v[148:149], s[36:37], 0, v[130:131]
	s_mov_b32 m0, s73
	ds_read_b128 v[186:189], v154 offset:16384
	ds_read_b128 v[190:193], v154 offset:17408
	ds_read_b128 v[194:197], v154 offset:18432
	ds_read_b128 v[198:201], v154 offset:19456
	ds_read_b128 v[202:205], v154 offset:20480
	ds_read_b128 v[206:209], v154 offset:21504
	ds_read_b128 v[210:213], v154 offset:22528
	ds_read_b128 v[214:217], v154 offset:23552
	global_load_lds_dwordx4 v[148:149], off
	s_add_i32 m0, s73, 0x2000
	s_add_u32 s74, s36, 0x20000
	v_lshl_add_u64 v[218:219], s[36:37], 0, v[134:135]
	s_addc_u32 s75, s37, 0
	s_add_i32 s73, s52, s41
	global_load_lds_dwordx4 v[218:219], off
	v_lshl_add_u64 v[220:221], s[74:75], 0, v[130:131]
	s_mov_b32 m0, s73
	v_lshl_add_u64 v[222:223], s[38:39], 0, v[132:133]
	global_load_lds_dwordx4 v[220:221], off
	v_lshl_add_u64 v[220:221], s[74:75], 0, v[134:135]
	s_add_i32 m0, s73, 0x2000
	s_nop 0
	global_load_lds_dwordx4 v[220:221], off
	v_lshl_add_u64 v[220:221], s[38:39], 0, v[128:129]
	s_mov_b32 m0, s25
	s_nop 0
	global_load_lds_dwordx4 v[220:221], off
	s_mov_b32 m0, s44
	s_nop 0
	global_load_lds_dwordx4 v[222:223], off
	s_waitcnt vmcnt(8)
	s_waitcnt lgkmcnt(0)
	s_barrier
; #define PG8_STAGE(bufoff, gbase, voff) do { _Pragma("unroll") for (int _i = 0; _i < 2; ++_i) \
;         __builtin_amdgcn_global_load_lds((const unsigned*)((const char*)(gbase) + (voff)[_i]), (PG8_LAS unsigned*)(lds + (bufoff) + ldsw + _i * 8192), 16, 0, 0); } while (0)
; #define PG8_LDA(dst, b, h) do { _Pragma("unroll") for (int m = 0; m < 4; ++m) _Pragma("unroll") for (int k = 0; k < 2; ++k) dst[m][k] = *(const PG8_LAS bf16x8*)(lds + PG8_SA(b, h) + aoff + m * 2048 + k * 1024); } while (0)
; #define PG8_LDB(dst, b, h) do { _Pragma("unroll") for (int n = 0; n < 2; ++n) _Pragma("unroll") for (int k = 0; k < 2; ++k) dst[n][k] = *(const PG8_LAS bf16x8*)(lds + PG8_SB(b, h) + boff + n * 2048 + k * 1024); } while (0)
; #define PG8_MMA(ai, bj, At, Bt) do { __builtin_amdgcn_s_setprio(1); _Pragma("unroll") for (int m = 0; m < 4; ++m) _Pragma("unroll") for (int n = 0; n < 2; ++n) _Pragma("unroll") for (int k = 0; k < 2; ++k) \
;         acc[ai][bj][m][n] = __builtin_amdgcn_mfma_f32_16x16x32_bf16(Bt[n][k], At[m][k], acc[ai][bj][m][n], 0, 0, 0); __builtin_amdgcn_s_setprio(0); } while (0)
; #define PG8_WAIT_V(n) asm volatile("s_waitcnt vmcnt(" #n ")" ::: "memory")
; #define PG8_WAIT_L(n) asm volatile("s_waitcnt lgkmcnt(" #n ")" ::: "memory")
; #define PG8_BAR __builtin_amdgcn_s_barrier()
; #define PG8_SCHED __builtin_amdgcn_sched_barrier(0)
; template <class Epi, class Sched, bool ALIGN_EPI = false, bool SP2 = false>
; __device__ __forceinline__ void gemm_phase(PG8_LAS unsigned char* lds, const Gemm g, const Sched& S, const Epi& E) {
;     ...
;             PG8_WAIT_V(8); PG8_WAIT_L(0); PG8_BAR; PG8_MMA(1, 0, At, B0); PG8_MMA(1, 1, At, B1); PG8_BAR; PG8_SCHED;
;             PG8_LDB(B0, 1, 0); PG8_LDB(B1, 1, 1); PG8_SCHED; PG8_LDA(At, 1, 0); PG8_STAGE(PG8_SA(0, 1), a2 + hstep, voffA);
;             PG8_WAIT_V(8); PG8_WAIT_L(0); PG8_BAR; PG8_MMA(0, 0, At, B0); PG8_MMA(0, 1, At, B1); PG8_BAR; PG8_SCHED;
	s_setprio 1
	s_waitcnt lgkmcnt(0)
	v_mfma_f32_16x16x32_bf16 v[60:63], v[144:147], v[186:189], v[60:63]
	v_mfma_f32_16x16x32_bf16 v[56:59], v[162:165], v[186:189], v[56:59]
	v_mfma_f32_16x16x32_bf16 v[48:51], v[144:147], v[194:197], v[48:51]
	v_mfma_f32_16x16x32_bf16 v[40:43], v[162:165], v[194:197], v[40:43]
	v_mfma_f32_16x16x32_bf16 v[28:31], v[144:147], v[202:205], v[28:31]
	v_mfma_f32_16x16x32_bf16 v[24:27], v[162:165], v[202:205], v[24:27]
	v_mfma_f32_16x16x32_bf16 v[16:19], v[144:147], v[210:213], v[16:19]
	v_mfma_f32_16x16x32_bf16 v[8:11], v[162:165], v[210:213], v[8:11]
	v_mfma_f32_16x16x32_bf16 v[60:63], v[158:161], v[190:193], v[60:63]
	v_mfma_f32_16x16x32_bf16 v[56:59], v[166:169], v[190:193], v[56:59]
	v_mfma_f32_16x16x32_bf16 v[48:51], v[158:161], v[198:201], v[48:51]
	v_mfma_f32_16x16x32_bf16 v[40:43], v[166:169], v[198:201], v[40:43]
	v_mfma_f32_16x16x32_bf16 v[28:31], v[158:161], v[206:209], v[28:31]
	v_mfma_f32_16x16x32_bf16 v[24:27], v[166:169], v[206:209], v[24:27]
	v_mfma_f32_16x16x32_bf16 v[16:19], v[158:161], v[214:217], v[16:19]
	v_mfma_f32_16x16x32_bf16 v[8:11], v[166:169], v[214:217], v[8:11]
	s_setprio 0
	s_setprio 1
	v_mfma_f32_16x16x32_bf16 v[52:55], v[170:173], v[186:189], v[52:55]
	v_mfma_f32_16x16x32_bf16 v[44:47], v[178:181], v[186:189], v[44:47]
	v_mfma_f32_16x16x32_bf16 v[36:39], v[170:173], v[194:197], v[36:39]
	v_mfma_f32_16x16x32_bf16 v[32:35], v[178:181], v[194:197], v[32:35]
	v_mfma_f32_16x16x32_bf16 v[20:23], v[170:173], v[202:205], v[20:23]
	v_mfma_f32_16x16x32_bf16 v[12:15], v[178:181], v[202:205], v[12:15]
	v_mfma_f32_16x16x32_bf16 v[4:7], v[170:173], v[210:213], v[4:7]
	v_mfma_f32_16x16x32_bf16 v[0:3], v[178:181], v[210:213], v[0:3]
	v_mfma_f32_16x16x32_bf16 v[52:55], v[174:177], v[190:193], v[52:55]
	v_mfma_f32_16x16x32_bf16 v[44:47], v[182:185], v[190:193], v[44:47]
	v_mfma_f32_16x16x32_bf16 v[36:39], v[174:177], v[198:201], v[36:39]
	v_mfma_f32_16x16x32_bf16 v[32:35], v[182:185], v[198:201], v[32:35]
	v_mfma_f32_16x16x32_bf16 v[20:23], v[174:177], v[206:209], v[20:23]
	v_mfma_f32_16x16x32_bf16 v[12:15], v[182:185], v[206:209], v[12:15]
	v_mfma_f32_16x16x32_bf16 v[4:7], v[174:177], v[214:217], v[4:7]
	v_mfma_f32_16x16x32_bf16 v[0:3], v[182:185], v[214:217], v[0:3]
	s_setprio 0
	s_barrier
	s_sleep 1
	s_add_i32 s73, 0, 0x18000
	v_add_u32_e32 v155, s73, v153
	s_add_i32 s74, 0, 0x1c000
	ds_read_b128 v[144:147], v155
	ds_read_b128 v[158:161], v155 offset:1024
	ds_read_b128 v[162:165], v155 offset:2048
	ds_read_b128 v[166:169], v155 offset:3072
	v_add_u32_e32 v155, s74, v153
	ds_read_b128 v[170:173], v155
	ds_read_b128 v[174:177], v155 offset:1024
	ds_read_b128 v[178:181], v155 offset:2048
	ds_read_b128 v[182:185], v155 offset:3072
	s_add_u32 s38, s38, 0x20000
	s_addc_u32 s39, s39, 0
	s_mov_b32 m0, s45
	v_lshl_add_u64 v[224:225], s[38:39], 0, v[128:129]
	ds_read_b128 v[186:189], v154 offset:32768
	ds_read_b128 v[190:193], v154 offset:33792
	ds_read_b128 v[194:197], v154 offset:34816
	ds_read_b128 v[198:201], v154 offset:35840
	ds_read_b128 v[202:205], v154 offset:36864
	ds_read_b128 v[206:209], v154 offset:37888
	ds_read_b128 v[210:213], v154 offset:38912
	ds_read_b128 v[214:217], v154 offset:39936
	global_load_lds_dwordx4 v[224:225], off
	v_lshl_add_u64 v[224:225], s[38:39], 0, v[132:133]
	s_mov_b32 m0, s46
	s_nop 0
	global_load_lds_dwordx4 v[224:225], off
	s_waitcnt vmcnt(8)
	s_waitcnt lgkmcnt(0)
	s_barrier
	s_setprio 1
	s_waitcnt lgkmcnt(0)
	v_mfma_f32_16x16x32_bf16 v[124:127], v[144:147], v[186:189], v[124:127]
	v_mfma_f32_16x16x32_bf16 v[120:123], v[162:165], v[186:189], v[120:123]
	v_mfma_f32_16x16x32_bf16 v[116:119], v[144:147], v[194:197], v[116:119]
	v_mfma_f32_16x16x32_bf16 v[104:107], v[162:165], v[194:197], v[104:107]
	v_mfma_f32_16x16x32_bf16 v[92:95], v[144:147], v[202:205], v[92:95]
	v_mfma_f32_16x16x32_bf16 v[88:91], v[162:165], v[202:205], v[88:91]
	v_mfma_f32_16x16x32_bf16 v[80:83], v[144:147], v[210:213], v[80:83]
	v_mfma_f32_16x16x32_bf16 v[72:75], v[162:165], v[210:213], v[72:75]
	v_mfma_f32_16x16x32_bf16 v[124:127], v[158:161], v[190:193], v[124:127]
	v_mfma_f32_16x16x32_bf16 v[120:123], v[166:169], v[190:193], v[120:123]
	v_mfma_f32_16x16x32_bf16 v[116:119], v[158:161], v[198:201], v[116:119]
	v_mfma_f32_16x16x32_bf16 v[104:107], v[166:169], v[198:201], v[104:107]
	v_mfma_f32_16x16x32_bf16 v[92:95], v[158:161], v[206:209], v[92:95]
	v_mfma_f32_16x16x32_bf16 v[88:91], v[166:169], v[206:209], v[88:91]
	v_mfma_f32_16x16x32_bf16 v[80:83], v[158:161], v[214:217], v[80:83]
	v_mfma_f32_16x16x32_bf16 v[72:75], v[166:169], v[214:217], v[72:75]
	s_setprio 0
	s_setprio 1
	v_mfma_f32_16x16x32_bf16 v[112:115], v[170:173], v[186:189], v[112:115]
	v_mfma_f32_16x16x32_bf16 v[108:111], v[178:181], v[186:189], v[108:111]
	v_mfma_f32_16x16x32_bf16 v[100:103], v[170:173], v[194:197], v[100:103]
	v_mfma_f32_16x16x32_bf16 v[96:99], v[178:181], v[194:197], v[96:99]
	v_mfma_f32_16x16x32_bf16 v[84:87], v[170:173], v[202:205], v[84:87]
	v_mfma_f32_16x16x32_bf16 v[76:79], v[178:181], v[202:205], v[76:79]
	v_mfma_f32_16x16x32_bf16 v[68:71], v[170:173], v[210:213], v[68:71]
	v_mfma_f32_16x16x32_bf16 v[64:67], v[178:181], v[210:213], v[64:67]
	v_mfma_f32_16x16x32_bf16 v[112:115], v[174:177], v[190:193], v[112:115]
	v_mfma_f32_16x16x32_bf16 v[108:111], v[182:185], v[190:193], v[108:111]
	v_mfma_f32_16x16x32_bf16 v[100:103], v[174:177], v[198:201], v[100:103]
	v_mfma_f32_16x16x32_bf16 v[96:99], v[182:185], v[198:201], v[96:99]
	v_mfma_f32_16x16x32_bf16 v[84:87], v[174:177], v[206:209], v[84:87]
	v_mfma_f32_16x16x32_bf16 v[76:79], v[182:185], v[206:209], v[76:79]
	v_mfma_f32_16x16x32_bf16 v[68:71], v[174:177], v[214:217], v[68:71]
	v_mfma_f32_16x16x32_bf16 v[64:67], v[182:185], v[214:217], v[64:67]
	s_setprio 0
	s_barrier
; #define PG8_STAGE(bufoff, gbase, voff) do { _Pragma("unroll") for (int _i = 0; _i < 2; ++_i) \
;         __builtin_amdgcn_global_load_lds((const unsigned*)((const char*)(gbase) + (voff)[_i]), (PG8_LAS unsigned*)(lds + (bufoff) + ldsw + _i * 8192), 16, 0, 0); } while (0)
; #define PG8_LDA(dst, b, h) do { _Pragma("unroll") for (int m = 0; m < 4; ++m) _Pragma("unroll") for (int k = 0; k < 2; ++k) dst[m][k] = *(const PG8_LAS bf16x8*)(lds + PG8_SA(b, h) + aoff + m * 2048 + k * 1024); } while (0)
; #define PG8_MMA(ai, bj, At, Bt) do { __builtin_amdgcn_s_setprio(1); _Pragma("unroll") for (int m = 0; m < 4; ++m) _Pragma("unroll") for (int n = 0; n < 2; ++n) _Pragma("unroll") for (int k = 0; k < 2; ++k) \
;         acc[ai][bj][m][n] = __builtin_amdgcn_mfma_f32_16x16x32_bf16(Bt[n][k], At[m][k], acc[ai][bj][m][n], 0, 0, 0); __builtin_amdgcn_s_setprio(0); } while (0)
; #define PG8_WAIT_V(n) asm volatile("s_waitcnt vmcnt(" #n ")" ::: "memory")
; #define PG8_WAIT_L(n) asm volatile("s_waitcnt lgkmcnt(" #n ")" ::: "memory")
; #define PG8_BAR __builtin_amdgcn_s_barrier()
; #define PG8_SCHED __builtin_amdgcn_sched_barrier(0)
;     __device__ __forceinline__ void operator()(const f32x4 (&acc)[2][2][4][2], const Unit& u, int wr, int wc, int fr, int fq) const {
;     ...
;             for (int m = mh; m < mh + 2; ++m)
; #pragma unroll
;                 for (int bj = 0; bj < 2; ++bj)
; #pragma unroll
;                     for (int n = 0; n < 2; ++n) { const size_t off = (size_t)(row0 + ai * HALF + m * 16) * 1024 + col0 + bj * HALF + n * 4;
;                         pg[m][bj][n] = *(const u32x2*)(G + off); if (ADD) pm_[m][bj][n] = *(const u32x2*)(Mg + off); }
; template <class Epi, class Sched, bool ALIGN_EPI = false, bool SP2 = false>
; __device__ __forceinline__ void gemm_phase(PG8_LAS unsigned char* lds, const Gemm g, const Sched& S, const Epi& E) {
;     ...
;             PG8_LDA(At, 1, 1); PG8_STAGE(PG8_SB(1, 0), b3, voffB); PG8_STAGE(PG8_SB(1, 1), b3 + hstep, voffB); PG8_STAGE(PG8_SA(1, 0), a3, voffA);
;             PG8_WAIT_V(8); PG8_WAIT_L(0); PG8_BAR; PG8_MMA(1, 0, At, B0); PG8_MMA(1, 1, At, B1); PG8_BAR; PG8_SCHED;
	s_sleep 1
	s_add_i32 s38, s73, s41
	v_lshl_add_u64 v[148:149], v[148:149], 0, s[4:5]
	s_mov_b32 m0, s38
	ds_read_b128 v[186:189], v154 offset:49152
	ds_read_b128 v[190:193], v154 offset:50176
	ds_read_b128 v[194:197], v154 offset:51200
	ds_read_b128 v[198:201], v154 offset:52224
	ds_read_b128 v[202:205], v154 offset:53248
	ds_read_b128 v[206:209], v154 offset:54272
	ds_read_b128 v[210:213], v154 offset:55296
	ds_read_b128 v[214:217], v154 offset:56320
	global_load_lds_dwordx4 v[148:149], off
	s_add_i32 m0, s38, 0x2000
	s_add_u32 s36, s36, 0x20080
	v_lshl_add_u64 v[148:149], v[218:219], 0, s[4:5]
	s_addc_u32 s37, s37, 0
	s_add_i32 s38, s74, s41
	global_load_lds_dwordx4 v[148:149], off
	v_lshl_add_u64 v[148:149], s[36:37], 0, v[130:131]
	s_mov_b32 m0, s38
	s_nop 0
	global_load_lds_dwordx4 v[148:149], off
	v_lshl_add_u64 v[148:149], s[36:37], 0, v[134:135]
	s_add_i32 m0, s38, 0x2000
	s_nop 0
	global_load_lds_dwordx4 v[148:149], off
	v_lshl_add_u64 v[148:149], v[220:221], 0, s[4:5]
	s_mov_b32 m0, s48
	s_nop 0
	global_load_lds_dwordx4 v[148:149], off
	v_lshl_add_u64 v[148:149], v[222:223], 0, s[4:5]
	s_mov_b32 m0, s49
	s_nop 0
	global_load_lds_dwordx4 v[148:149], off
	s_waitcnt vmcnt(8)
	s_waitcnt lgkmcnt(0)
	s_barrier
	s_setprio 1
	s_waitcnt lgkmcnt(0)
	v_mfma_f32_16x16x32_bf16 v[60:63], v[144:147], v[186:189], v[60:63]
	v_mfma_f32_16x16x32_bf16 v[56:59], v[162:165], v[186:189], v[56:59]
	v_mfma_f32_16x16x32_bf16 v[48:51], v[144:147], v[194:197], v[48:51]
	v_mfma_f32_16x16x32_bf16 v[40:43], v[162:165], v[194:197], v[40:43]
	v_mfma_f32_16x16x32_bf16 v[28:31], v[144:147], v[202:205], v[28:31]
	v_mfma_f32_16x16x32_bf16 v[24:27], v[162:165], v[202:205], v[24:27]
	v_mfma_f32_16x16x32_bf16 v[16:19], v[144:147], v[210:213], v[16:19]
	v_mfma_f32_16x16x32_bf16 v[8:11], v[162:165], v[210:213], v[8:11]
	v_mfma_f32_16x16x32_bf16 v[60:63], v[158:161], v[190:193], v[60:63]
	v_mfma_f32_16x16x32_bf16 v[56:59], v[166:169], v[190:193], v[56:59]
	v_mfma_f32_16x16x32_bf16 v[48:51], v[158:161], v[198:201], v[48:51]
	v_mfma_f32_16x16x32_bf16 v[40:43], v[166:169], v[198:201], v[40:43]
	v_mfma_f32_16x16x32_bf16 v[28:31], v[158:161], v[206:209], v[28:31]
	v_mfma_f32_16x16x32_bf16 v[24:27], v[166:169], v[206:209], v[24:27]
	v_mfma_f32_16x16x32_bf16 v[16:19], v[158:161], v[214:217], v[16:19]
	v_mfma_f32_16x16x32_bf16 v[8:11], v[166:169], v[214:217], v[8:11]
	s_setprio 0
	s_setprio 1
	v_mfma_f32_16x16x32_bf16 v[52:55], v[170:173], v[186:189], v[52:55]
	v_mfma_f32_16x16x32_bf16 v[44:47], v[178:181], v[186:189], v[44:47]
	v_mfma_f32_16x16x32_bf16 v[36:39], v[170:173], v[194:197], v[36:39]
	v_mfma_f32_16x16x32_bf16 v[32:35], v[178:181], v[194:197], v[32:35]
	v_mfma_f32_16x16x32_bf16 v[20:23], v[170:173], v[202:205], v[20:23]
	v_mfma_f32_16x16x32_bf16 v[12:15], v[178:181], v[202:205], v[12:15]
	v_mfma_f32_16x16x32_bf16 v[4:7], v[170:173], v[210:213], v[4:7]
	v_mfma_f32_16x16x32_bf16 v[0:3], v[178:181], v[210:213], v[0:3]
	v_mfma_f32_16x16x32_bf16 v[52:55], v[174:177], v[190:193], v[52:55]
	v_mfma_f32_16x16x32_bf16 v[44:47], v[182:185], v[190:193], v[44:47]
	v_mfma_f32_16x16x32_bf16 v[36:39], v[174:177], v[198:201], v[36:39]
	v_mfma_f32_16x16x32_bf16 v[32:35], v[182:185], v[198:201], v[32:35]
	v_mfma_f32_16x16x32_bf16 v[20:23], v[174:177], v[206:209], v[20:23]
	v_mfma_f32_16x16x32_bf16 v[12:15], v[182:185], v[206:209], v[12:15]
	v_mfma_f32_16x16x32_bf16 v[4:7], v[174:177], v[214:217], v[4:7]
	v_mfma_f32_16x16x32_bf16 v[0:3], v[182:185], v[214:217], v[0:3]
	s_setprio 0
	s_barrier
	s_sleep 1
	s_add_i32 s72, s72, 2
	s_add_u32 s26, s26, 0x100
	s_addc_u32 s27, s27, 0
	s_add_u32 s70, s70, 0x100
	s_addc_u32 s71, s71, 0
	s_cmp_gt_u32 s72, 5
	s_cbranch_scc0 .LBB0_747
	v_lshl_add_u32 v146, s24, 8, v156
	v_lshl_or_b32 v144, s53, 8, v151
	v_ashrrev_i32_e32 v147, 31, v146
	v_ashrrev_i32_e32 v145, 31, v144
	v_lshlrev_b64 v[148:149], 10, v[146:147]
	v_lshl_add_u64 v[148:149], v[148:149], 0, v[144:145]
	v_lshlrev_b64 v[170:171], 1, v[148:149]
	v_lshl_add_u64 v[148:149], s[6:7], 0, v[170:171]
	v_or_b32_e32 v170, 0x100, v170
	v_lshl_add_u64 v[166:167], s[6:7], 0, v[170:171]
	v_or_b32_e32 v178, 16, v146
	global_load_dwordx4 v[158:161], v[148:149], off
	v_lshlrev_b64 v[162:163], 11, v[146:147]
	global_load_dwordx4 v[166:169], v[166:167], off
	v_lshl_add_u64 v[148:149], v[144:145], 1, s[0:1]
	v_ashrrev_i32_e32 v179, 31, v178
	v_lshl_add_u64 v[190:191], v[148:149], 0, v[162:163]
	v_lshlrev_b64 v[174:175], 10, v[178:179]
	global_load_dwordx4 v[162:165], v[190:191], off
	v_lshl_add_u64 v[170:171], s[0:1], 0, v[170:171]
	v_lshl_add_u64 v[174:175], v[174:175], 0, v[144:145]
	global_load_dwordx4 v[170:173], v[170:171], off
	v_lshlrev_b64 v[186:187], 1, v[174:175]
	v_lshlrev_b64 v[178:179], 11, v[178:179]
	v_lshl_add_u64 v[174:175], s[6:7], 0, v[186:187]
	v_lshl_add_u64 v[192:193], v[148:149], 0, v[178:179]
	global_load_dwordx4 v[174:177], v[174:175], off
	v_or_b32_e32 v186, 0x100, v186
	global_load_dwordx4 v[178:181], v[192:193], off
	v_lshl_add_u64 v[182:183], s[6:7], 0, v[186:187]
	v_lshl_add_u64 v[186:187], s[0:1], 0, v[186:187]
	global_load_dwordx4 v[182:185], v[182:183], off
	s_and_b64 vcc, exec, s[2:3]
	global_load_dwordx4 v[186:189], v[186:187], off
	s_mov_b32 s53, s12
	s_mov_b32 s24, s14
	s_mov_b64 s[36:37], s[22:23]
	s_mov_b64 s[26:27], s[20:21]
	s_waitcnt vmcnt(0)
; __device__ __forceinline__ u32x2 pack4(f32x4 v) { u32x2 w; w.x = cvt_pk_bf16(v[0], v[1]); w.y = cvt_pk_bf16(v[2], v[3]); return w; }
; __device__ __forceinline__ f32x4 unpack4(u32x2 w) { f32x4 v; v[0] = __uint_as_float(w.x << 16); v[1] = __uint_as_float(w.x & 0xffff0000u); v[2] = __uint_as_float(w.y << 16); v[3] = __uint_as_float(w.y & 0xffff0000u); return v; }
;     __device__ __forceinline__ void operator()(const f32x4 (&acc)[2][2][4][2], const Unit& u, int wr, int wc, int fr, int fq) const {
;     ...
;             for (int m = mh; m < mh + 2; ++m)
; #pragma unroll
;                 for (int bj = 0; bj < 2; ++bj)
; #pragma unroll
;                     for (int n = 0; n < 2; ++n) { const size_t off = (size_t)(row0 + ai * HALF + m * 16) * 1024 + col0 + bj * HALF + n * 4;
;                         pg[m][bj][n] = *(const u32x2*)(G + off); if (ADD) pm_[m][bj][n] = *(const u32x2*)(Mg + off); }
;             asm volatile("" ::: "memory");
; #pragma unroll
;             for (int m = mh; m < mh + 2; ++m)
; #pragma unroll
;                 for (int bj = 0; bj < 2; ++bj)
; #pragma unroll
;                     for (int n = 0; n < 2; ++n) { const size_t off = (size_t)(row0 + ai * HALF + m * 16) * 1024 + col0 + bj * HALF + n * 4;
;                         f32x4 o = unpack4(pg[m][bj][n]) * acc[ai][bj][m][n]; if (ADD) o = o + unpack4(pm_[m][bj][n]);
;                         *(u32x2*)(Mg + off) = pack4(o); }
	v_lshlrev_b32_e32 v194, 16, v158
	v_and_b32_e32 v195, 0xffff0000, v158
	v_lshlrev_b32_e32 v158, 16, v159
	v_and_b32_e32 v159, 0xffff0000, v159
	v_lshlrev_b32_e32 v198, 16, v160
	v_and_b32_e32 v199, 0xffff0000, v160
	v_lshlrev_b32_e32 v160, 16, v161
	v_lshlrev_b32_e32 v196, 16, v162
	v_and_b32_e32 v197, 0xffff0000, v162
	v_lshlrev_b32_e32 v162, 16, v163
	v_and_b32_e32 v163, 0xffff0000, v163
	v_and_b32_e32 v161, 0xffff0000, v161
	v_lshlrev_b32_e32 v200, 16, v164
	v_and_b32_e32 v201, 0xffff0000, v164
	v_lshlrev_b32_e32 v164, 16, v165
	v_and_b32_e32 v165, 0xffff0000, v165
	v_pk_fma_f32 v[126:127], v[126:127], v[158:159], v[162:163]
	v_pk_fma_f32 v[124:125], v[124:125], v[194:195], v[196:197]
	v_pk_fma_f32 v[158:159], v[122:123], v[160:161], v[164:165]
	v_lshlrev_b32_e32 v160, 16, v166
	v_and_b32_e32 v161, 0xffff0000, v166
	v_lshlrev_b32_e32 v162, 16, v167
	v_and_b32_e32 v163, 0xffff0000, v167
	v_lshlrev_b32_e32 v164, 16, v170
	v_and_b32_e32 v165, 0xffff0000, v170
	v_lshlrev_b32_e32 v166, 16, v171
	v_and_b32_e32 v167, 0xffff0000, v171
	v_lshlrev_b32_e32 v170, 16, v168
	v_and_b32_e32 v171, 0xffff0000, v168
	v_lshlrev_b32_e32 v168, 16, v169
	v_and_b32_e32 v169, 0xffff0000, v169
	v_lshlrev_b32_e32 v194, 16, v172
	v_and_b32_e32 v195, 0xffff0000, v172
	v_lshlrev_b32_e32 v172, 16, v173
	v_and_b32_e32 v173, 0xffff0000, v173
	v_pk_fma_f32 v[122:123], v[120:121], v[198:199], v[200:201]
	v_cvt_pk_bf16_f32 v120, v124, v125
	v_pk_fma_f32 v[114:115], v[114:115], v[162:163], v[166:167]
	v_pk_fma_f32 v[112:113], v[112:113], v[160:161], v[164:165]
	v_pk_fma_f32 v[124:125], v[110:111], v[168:169], v[172:173]
	v_pk_fma_f32 v[110:111], v[108:109], v[170:171], v[194:195]
	v_lshlrev_b32_e32 v196, 16, v174
	v_and_b32_e32 v197, 0xffff0000, v174
	v_lshlrev_b32_e32 v174, 16, v175
	v_and_b32_e32 v175, 0xffff0000, v175
	v_lshlrev_b32_e32 v198, 16, v178
	v_and_b32_e32 v199, 0xffff0000, v178
	v_lshlrev_b32_e32 v178, 16, v179
	v_cvt_pk_bf16_f32 v108, v112, v113
	v_cvt_pk_bf16_f32 v109, v114, v115
	v_cvt_pk_bf16_f32 v110, v110, v111
	v_cvt_pk_bf16_f32 v111, v124, v125
	v_and_b32_e32 v179, 0xffff0000, v179
	global_store_dwordx4 v[190:191], v[108:111], off offset:256
	v_lshlrev_b32_e32 v112, 16, v177
	v_and_b32_e32 v113, 0xffff0000, v177
	v_pk_fma_f32 v[110:111], v[118:119], v[174:175], v[178:179]
	v_pk_fma_f32 v[108:109], v[116:117], v[196:197], v[198:199]
	v_lshlrev_b32_e32 v114, 16, v180
	v_cvt_pk_bf16_f32 v108, v108, v109
	v_cvt_pk_bf16_f32 v109, v110, v111
	v_lshlrev_b32_e32 v110, 16, v176
	v_and_b32_e32 v111, 0xffff0000, v176
	v_and_b32_e32 v115, 0xffff0000, v180
	v_lshlrev_b32_e32 v116, 16, v181
	v_and_b32_e32 v117, 0xffff0000, v181
	v_pk_fma_f32 v[106:107], v[106:107], v[112:113], v[116:117]
	v_pk_fma_f32 v[104:105], v[104:105], v[110:111], v[114:115]
	v_cvt_pk_bf16_f32 v111, v106, v107
	v_cvt_pk_bf16_f32 v110, v104, v105
	global_store_dwordx4 v[192:193], v[108:111], off
	v_lshlrev_b32_e32 v104, 16, v182
	v_and_b32_e32 v105, 0xffff0000, v182
	v_lshlrev_b32_e32 v106, 16, v183
	v_and_b32_e32 v107, 0xffff0000, v183
	v_lshlrev_b32_e32 v108, 16, v186
	v_and_b32_e32 v109, 0xffff0000, v186
	v_lshlrev_b32_e32 v110, 16, v187
	v_and_b32_e32 v111, 0xffff0000, v187
	v_pk_fma_f32 v[102:103], v[102:103], v[106:107], v[110:111]
	v_pk_fma_f32 v[100:101], v[100:101], v[104:105], v[108:109]
	v_lshlrev_b32_e32 v104, 16, v185
	v_cvt_pk_bf16_f32 v100, v100, v101
	v_cvt_pk_bf16_f32 v101, v102, v103
	v_lshlrev_b32_e32 v102, 16, v184
	v_and_b32_e32 v103, 0xffff0000, v184
	v_and_b32_e32 v105, 0xffff0000, v185
	v_lshlrev_b32_e32 v106, 16, v188
	v_and_b32_e32 v107, 0xffff0000, v188
	v_lshlrev_b32_e32 v108, 16, v189
	v_and_b32_e32 v109, 0xffff0000, v189
	v_pk_fma_f32 v[98:99], v[98:99], v[104:105], v[108:109]
	v_pk_fma_f32 v[96:97], v[96:97], v[102:103], v[106:107]
	v_cvt_pk_bf16_f32 v103, v98, v99
	v_cvt_pk_bf16_f32 v102, v96, v97
	global_store_dwordx4 v[192:193], v[100:103], off offset:256
	v_cvt_pk_bf16_f32 v121, v126, v127
	v_cvt_pk_bf16_f32 v122, v122, v123
	v_or_b32_e32 v100, 32, v146
	v_ashrrev_i32_e32 v101, 31, v100
	v_lshlrev_b64 v[96:97], 10, v[100:101]
	v_cvt_pk_bf16_f32 v123, v158, v159
	v_lshl_add_u64 v[96:97], v[96:97], 0, v[144:145]
	global_store_dwordx4 v[190:191], v[120:123], off
	v_lshlrev_b64 v[108:109], 1, v[96:97]
	v_lshlrev_b64 v[100:101], 11, v[100:101]
	v_lshl_add_u64 v[96:97], s[6:7], 0, v[108:109]
	v_lshl_add_u64 v[158:159], v[148:149], 0, v[100:101]
	global_load_dwordx4 v[96:99], v[96:97], off
	v_or_b32_e32 v108, 0x100, v108
	global_load_dwordx4 v[100:103], v[158:159], off
	v_lshl_add_u64 v[104:105], s[6:7], 0, v[108:109]
	v_lshl_add_u64 v[108:109], s[0:1], 0, v[108:109]
	v_or_b32_e32 v116, 48, v146
	global_load_dwordx4 v[104:107], v[104:105], off
	v_ashrrev_i32_e32 v117, 31, v116
	global_load_dwordx4 v[108:111], v[108:109], off
	v_lshlrev_b64 v[112:113], 10, v[116:117]
	v_lshl_add_u64 v[112:113], v[112:113], 0, v[144:145]
	v_lshlrev_b64 v[124:125], 1, v[112:113]
	v_lshlrev_b64 v[116:117], 11, v[116:117]
	v_lshl_add_u64 v[112:113], s[6:7], 0, v[124:125]
	v_lshl_add_u64 v[160:161], v[148:149], 0, v[116:117]
	global_load_dwordx4 v[112:115], v[112:113], off
	v_or_b32_e32 v124, 0x100, v124
	global_load_dwordx4 v[116:119], v[160:161], off
	v_lshl_add_u64 v[120:121], s[6:7], 0, v[124:125]
	v_lshl_add_u64 v[124:125], s[0:1], 0, v[124:125]
	global_load_dwordx4 v[120:123], v[120:121], off
	s_waitcnt vmcnt(6)
	v_lshlrev_b32_e32 v162, 16, v96
	global_load_dwordx4 v[124:127], v[124:125], off
	v_and_b32_e32 v163, 0xffff0000, v96
	v_lshlrev_b32_e32 v96, 16, v97
	v_and_b32_e32 v97, 0xffff0000, v97
	s_waitcnt vmcnt(6)
; __device__ __forceinline__ u32x2 pack4(f32x4 v) { u32x2 w; w.x = cvt_pk_bf16(v[0], v[1]); w.y = cvt_pk_bf16(v[2], v[3]); return w; }
; __device__ __forceinline__ f32x4 unpack4(u32x2 w) { f32x4 v; v[0] = __uint_as_float(w.x << 16); v[1] = __uint_as_float(w.x & 0xffff0000u); v[2] = __uint_as_float(w.y << 16); v[3] = __uint_as_float(w.y & 0xffff0000u); return v; }
;     __device__ __forceinline__ void operator()(const f32x4 (&acc)[2][2][4][2], const Unit& u, int wr, int wc, int fr, int fq) const {
;     ...
;             for (int m = mh; m < mh + 2; ++m)
; #pragma unroll
;                 for (int bj = 0; bj < 2; ++bj)
; #pragma unroll
;                     for (int n = 0; n < 2; ++n) { const size_t off = (size_t)(row0 + ai * HALF + m * 16) * 1024 + col0 + bj * HALF + n * 4;
;                         pg[m][bj][n] = *(const u32x2*)(G + off); if (ADD) pm_[m][bj][n] = *(const u32x2*)(Mg + off); }
;             asm volatile("" ::: "memory");
; #pragma unroll
;             for (int m = mh; m < mh + 2; ++m)
; #pragma unroll
;                 for (int bj = 0; bj < 2; ++bj)
; #pragma unroll
;                     for (int n = 0; n < 2; ++n) { const size_t off = (size_t)(row0 + ai * HALF + m * 16) * 1024 + col0 + bj * HALF + n * 4;
;                         f32x4 o = unpack4(pg[m][bj][n]) * acc[ai][bj][m][n]; if (ADD) o = o + unpack4(pm_[m][bj][n]);
;                         *(u32x2*)(Mg + off) = pack4(o); }
	v_lshlrev_b32_e32 v164, 16, v100
	v_and_b32_e32 v165, 0xffff0000, v100
	v_lshlrev_b32_e32 v100, 16, v101
	v_and_b32_e32 v101, 0xffff0000, v101
	v_pk_fma_f32 v[94:95], v[94:95], v[96:97], v[100:101]
	v_pk_fma_f32 v[92:93], v[92:93], v[162:163], v[164:165]
	v_lshlrev_b32_e32 v96, 16, v99
	v_cvt_pk_bf16_f32 v92, v92, v93
	v_cvt_pk_bf16_f32 v93, v94, v95
	v_lshlrev_b32_e32 v94, 16, v98
	v_and_b32_e32 v95, 0xffff0000, v98
	v_and_b32_e32 v97, 0xffff0000, v99
	v_lshlrev_b32_e32 v98, 16, v102
	v_and_b32_e32 v99, 0xffff0000, v102
	v_lshlrev_b32_e32 v100, 16, v103
	v_and_b32_e32 v101, 0xffff0000, v103
	v_pk_fma_f32 v[90:91], v[90:91], v[96:97], v[100:101]
	v_pk_fma_f32 v[88:89], v[88:89], v[94:95], v[98:99]
	v_cvt_pk_bf16_f32 v95, v90, v91
	v_cvt_pk_bf16_f32 v94, v88, v89
	global_store_dwordx4 v[158:159], v[92:95], off
	s_waitcnt vmcnt(6)
	v_lshlrev_b32_e32 v88, 16, v104
	v_and_b32_e32 v89, 0xffff0000, v104
	v_lshlrev_b32_e32 v90, 16, v105
	v_and_b32_e32 v91, 0xffff0000, v105
	s_waitcnt vmcnt(5)
	v_lshlrev_b32_e32 v92, 16, v108
	v_and_b32_e32 v93, 0xffff0000, v108
	v_lshlrev_b32_e32 v94, 16, v109
	v_and_b32_e32 v95, 0xffff0000, v109
	v_pk_fma_f32 v[86:87], v[86:87], v[90:91], v[94:95]
	v_pk_fma_f32 v[84:85], v[84:85], v[88:89], v[92:93]
	v_lshlrev_b32_e32 v88, 16, v107
	v_cvt_pk_bf16_f32 v84, v84, v85
	v_cvt_pk_bf16_f32 v85, v86, v87
	v_lshlrev_b32_e32 v86, 16, v106
	v_and_b32_e32 v87, 0xffff0000, v106
	v_and_b32_e32 v89, 0xffff0000, v107
	v_lshlrev_b32_e32 v90, 16, v110
	v_and_b32_e32 v91, 0xffff0000, v110
	v_lshlrev_b32_e32 v92, 16, v111
	v_and_b32_e32 v93, 0xffff0000, v111
	v_pk_fma_f32 v[78:79], v[78:79], v[88:89], v[92:93]
	v_pk_fma_f32 v[76:77], v[76:77], v[86:87], v[90:91]
	v_cvt_pk_bf16_f32 v87, v78, v79
	v_cvt_pk_bf16_f32 v86, v76, v77
	global_store_dwordx4 v[158:159], v[84:87], off offset:256
	s_waitcnt vmcnt(5)
	v_lshlrev_b32_e32 v76, 16, v112
	v_and_b32_e32 v77, 0xffff0000, v112
	v_lshlrev_b32_e32 v78, 16, v113
	v_and_b32_e32 v79, 0xffff0000, v113
	s_waitcnt vmcnt(4)
	v_lshlrev_b32_e32 v84, 16, v116
	v_and_b32_e32 v85, 0xffff0000, v116
	v_lshlrev_b32_e32 v86, 16, v117
	v_and_b32_e32 v87, 0xffff0000, v117
	v_pk_fma_f32 v[78:79], v[82:83], v[78:79], v[86:87]
	v_pk_fma_f32 v[76:77], v[80:81], v[76:77], v[84:85]
	v_lshlrev_b32_e32 v80, 16, v115
	v_cvt_pk_bf16_f32 v76, v76, v77
	v_cvt_pk_bf16_f32 v77, v78, v79
	v_lshlrev_b32_e32 v78, 16, v114
	v_and_b32_e32 v79, 0xffff0000, v114
	v_and_b32_e32 v81, 0xffff0000, v115
	v_lshlrev_b32_e32 v82, 16, v118
	v_and_b32_e32 v83, 0xffff0000, v118
	v_lshlrev_b32_e32 v84, 16, v119
	v_and_b32_e32 v85, 0xffff0000, v119
	v_pk_fma_f32 v[74:75], v[74:75], v[80:81], v[84:85]
	v_pk_fma_f32 v[72:73], v[72:73], v[78:79], v[82:83]
	v_cvt_pk_bf16_f32 v79, v74, v75
	v_cvt_pk_bf16_f32 v78, v72, v73
	global_store_dwordx4 v[160:161], v[76:79], off
	s_waitcnt vmcnt(4)
	v_lshlrev_b32_e32 v72, 16, v120
	v_and_b32_e32 v73, 0xffff0000, v120
	v_lshlrev_b32_e32 v74, 16, v121
	v_and_b32_e32 v75, 0xffff0000, v121
	s_waitcnt vmcnt(3)
	v_lshlrev_b32_e32 v76, 16, v124
	v_and_b32_e32 v77, 0xffff0000, v124
	v_lshlrev_b32_e32 v78, 16, v125
	v_and_b32_e32 v79, 0xffff0000, v125
	v_pk_fma_f32 v[70:71], v[70:71], v[74:75], v[78:79]
	v_pk_fma_f32 v[68:69], v[68:69], v[72:73], v[76:77]
	v_lshlrev_b32_e32 v72, 16, v123
	v_cvt_pk_bf16_f32 v68, v68, v69
	v_cvt_pk_bf16_f32 v69, v70, v71
	v_lshlrev_b32_e32 v70, 16, v122
	v_and_b32_e32 v71, 0xffff0000, v122
	v_and_b32_e32 v73, 0xffff0000, v123
	v_lshlrev_b32_e32 v74, 16, v126
	v_and_b32_e32 v75, 0xffff0000, v126
	v_lshlrev_b32_e32 v76, 16, v127
	v_and_b32_e32 v77, 0xffff0000, v127
	v_pk_fma_f32 v[66:67], v[66:67], v[72:73], v[76:77]
	v_pk_fma_f32 v[64:65], v[64:65], v[70:71], v[74:75]
	v_cvt_pk_bf16_f32 v71, v66, v67
	v_cvt_pk_bf16_f32 v70, v64, v65
	global_store_dwordx4 v[160:161], v[68:71], off offset:256
	v_add_u32_e32 v84, 0x90, v146
	v_ashrrev_i32_e32 v85, 31, v84
	v_add_u32_e32 v68, 0x80, v146
	v_ashrrev_i32_e32 v69, 31, v68
	v_lshlrev_b64 v[64:65], 10, v[68:69]
	v_lshl_add_u64 v[64:65], v[64:65], 0, v[144:145]
	v_lshlrev_b64 v[76:77], 1, v[64:65]
	v_lshlrev_b64 v[68:69], 11, v[68:69]
	v_lshl_add_u64 v[64:65], s[6:7], 0, v[76:77]
	v_lshl_add_u64 v[96:97], v[148:149], 0, v[68:69]
	global_load_dwordx4 v[64:67], v[64:65], off
	v_or_b32_e32 v76, 0x100, v76
	global_load_dwordx4 v[68:71], v[96:97], off
	v_lshl_add_u64 v[72:73], s[6:7], 0, v[76:77]
	v_lshl_add_u64 v[76:77], s[0:1], 0, v[76:77]
	global_load_dwordx4 v[72:75], v[72:73], off
	v_lshlrev_b64 v[80:81], 10, v[84:85]
	global_load_dwordx4 v[76:79], v[76:77], off
	v_lshl_add_u64 v[80:81], v[80:81], 0, v[144:145]
	v_lshlrev_b64 v[92:93], 1, v[80:81]
	v_lshlrev_b64 v[84:85], 11, v[84:85]
	v_lshl_add_u64 v[80:81], s[6:7], 0, v[92:93]
	v_lshl_add_u64 v[98:99], v[148:149], 0, v[84:85]
	global_load_dwordx4 v[80:83], v[80:81], off
	v_or_b32_e32 v92, 0x100, v92
	global_load_dwordx4 v[84:87], v[98:99], off
	v_lshl_add_u64 v[88:89], s[6:7], 0, v[92:93]
	v_lshl_add_u64 v[92:93], s[0:1], 0, v[92:93]
	global_load_dwordx4 v[88:91], v[88:89], off
	s_waitcnt vmcnt(6)
	v_lshlrev_b32_e32 v100, 16, v64
	global_load_dwordx4 v[92:95], v[92:93], off
	v_and_b32_e32 v101, 0xffff0000, v64
	v_lshlrev_b32_e32 v64, 16, v65
	v_and_b32_e32 v65, 0xffff0000, v65
	s_waitcnt vmcnt(6)
; __device__ __forceinline__ u32x2 pack4(f32x4 v) { u32x2 w; w.x = cvt_pk_bf16(v[0], v[1]); w.y = cvt_pk_bf16(v[2], v[3]); return w; }
; __device__ __forceinline__ f32x4 unpack4(u32x2 w) { f32x4 v; v[0] = __uint_as_float(w.x << 16); v[1] = __uint_as_float(w.x & 0xffff0000u); v[2] = __uint_as_float(w.y << 16); v[3] = __uint_as_float(w.y & 0xffff0000u); return v; }
;     __device__ __forceinline__ void operator()(const f32x4 (&acc)[2][2][4][2], const Unit& u, int wr, int wc, int fr, int fq) const {
;     ...
;                     for (int n = 0; n < 2; ++n) { const size_t off = (size_t)(row0 + ai * HALF + m * 16) * 1024 + col0 + bj * HALF + n * 4;
;                         pg[m][bj][n] = *(const u32x2*)(G + off); if (ADD) pm_[m][bj][n] = *(const u32x2*)(Mg + off); }
;             asm volatile("" ::: "memory");
; #pragma unroll
;             for (int m = mh; m < mh + 2; ++m)
; #pragma unroll
;                 for (int bj = 0; bj < 2; ++bj)
; #pragma unroll
;                     for (int n = 0; n < 2; ++n) { const size_t off = (size_t)(row0 + ai * HALF + m * 16) * 1024 + col0 + bj * HALF + n * 4;
;                         f32x4 o = unpack4(pg[m][bj][n]) * acc[ai][bj][m][n]; if (ADD) o = o + unpack4(pm_[m][bj][n]);
;                         *(u32x2*)(Mg + off) = pack4(o); }
	v_lshlrev_b32_e32 v102, 16, v68
	v_and_b32_e32 v103, 0xffff0000, v68
	v_lshlrev_b32_e32 v68, 16, v69
	v_and_b32_e32 v69, 0xffff0000, v69
	v_pk_fma_f32 v[62:63], v[62:63], v[64:65], v[68:69]
	v_pk_fma_f32 v[60:61], v[60:61], v[100:101], v[102:103]
	v_lshlrev_b32_e32 v64, 16, v67
	v_cvt_pk_bf16_f32 v60, v60, v61
	v_cvt_pk_bf16_f32 v61, v62, v63
	v_lshlrev_b32_e32 v62, 16, v66
	v_and_b32_e32 v63, 0xffff0000, v66
	v_and_b32_e32 v65, 0xffff0000, v67
	v_lshlrev_b32_e32 v66, 16, v70
	v_and_b32_e32 v67, 0xffff0000, v70
	v_lshlrev_b32_e32 v68, 16, v71
	v_and_b32_e32 v69, 0xffff0000, v71
	v_pk_fma_f32 v[58:59], v[58:59], v[64:65], v[68:69]
	v_pk_fma_f32 v[56:57], v[56:57], v[62:63], v[66:67]
	v_cvt_pk_bf16_f32 v63, v58, v59
	v_cvt_pk_bf16_f32 v62, v56, v57
	global_store_dwordx4 v[96:97], v[60:63], off
	s_waitcnt vmcnt(6)
	v_lshlrev_b32_e32 v56, 16, v72
	v_and_b32_e32 v57, 0xffff0000, v72
	v_lshlrev_b32_e32 v58, 16, v73
	v_and_b32_e32 v59, 0xffff0000, v73
	s_waitcnt vmcnt(5)
	v_lshlrev_b32_e32 v60, 16, v76
	v_and_b32_e32 v61, 0xffff0000, v76
	v_lshlrev_b32_e32 v62, 16, v77
	v_and_b32_e32 v63, 0xffff0000, v77
	v_pk_fma_f32 v[54:55], v[54:55], v[58:59], v[62:63]
	v_pk_fma_f32 v[52:53], v[52:53], v[56:57], v[60:61]
	v_lshlrev_b32_e32 v56, 16, v75
	v_cvt_pk_bf16_f32 v52, v52, v53
	v_cvt_pk_bf16_f32 v53, v54, v55
	v_lshlrev_b32_e32 v54, 16, v74
	v_and_b32_e32 v55, 0xffff0000, v74
	v_and_b32_e32 v57, 0xffff0000, v75
	v_lshlrev_b32_e32 v58, 16, v78
	v_and_b32_e32 v59, 0xffff0000, v78
	v_lshlrev_b32_e32 v60, 16, v79
	v_and_b32_e32 v61, 0xffff0000, v79
	v_pk_fma_f32 v[46:47], v[46:47], v[56:57], v[60:61]
	v_pk_fma_f32 v[44:45], v[44:45], v[54:55], v[58:59]
	v_cvt_pk_bf16_f32 v55, v46, v47
	v_cvt_pk_bf16_f32 v54, v44, v45
	global_store_dwordx4 v[96:97], v[52:55], off offset:256
	s_waitcnt vmcnt(5)
	v_lshlrev_b32_e32 v44, 16, v80
	v_and_b32_e32 v45, 0xffff0000, v80
	v_lshlrev_b32_e32 v46, 16, v81
	v_and_b32_e32 v47, 0xffff0000, v81
	s_waitcnt vmcnt(4)
	v_lshlrev_b32_e32 v52, 16, v84
	v_and_b32_e32 v53, 0xffff0000, v84
	v_lshlrev_b32_e32 v54, 16, v85
	v_and_b32_e32 v55, 0xffff0000, v85
	v_pk_fma_f32 v[46:47], v[50:51], v[46:47], v[54:55]
	v_pk_fma_f32 v[44:45], v[48:49], v[44:45], v[52:53]
	v_lshlrev_b32_e32 v48, 16, v83
	v_cvt_pk_bf16_f32 v44, v44, v45
	v_cvt_pk_bf16_f32 v45, v46, v47
	v_lshlrev_b32_e32 v46, 16, v82
	v_and_b32_e32 v47, 0xffff0000, v82
	v_and_b32_e32 v49, 0xffff0000, v83
	v_lshlrev_b32_e32 v50, 16, v86
	v_and_b32_e32 v51, 0xffff0000, v86
	v_lshlrev_b32_e32 v52, 16, v87
	v_and_b32_e32 v53, 0xffff0000, v87
	v_pk_fma_f32 v[42:43], v[42:43], v[48:49], v[52:53]
	v_pk_fma_f32 v[40:41], v[40:41], v[46:47], v[50:51]
	v_cvt_pk_bf16_f32 v47, v42, v43
	v_cvt_pk_bf16_f32 v46, v40, v41
	global_store_dwordx4 v[98:99], v[44:47], off
	s_waitcnt vmcnt(4)
	v_lshlrev_b32_e32 v40, 16, v88
	v_and_b32_e32 v41, 0xffff0000, v88
	v_lshlrev_b32_e32 v42, 16, v89
	v_and_b32_e32 v43, 0xffff0000, v89
	s_waitcnt vmcnt(3)
	v_lshlrev_b32_e32 v44, 16, v92
	v_and_b32_e32 v45, 0xffff0000, v92
	v_lshlrev_b32_e32 v46, 16, v93
	v_and_b32_e32 v47, 0xffff0000, v93
	v_pk_fma_f32 v[38:39], v[38:39], v[42:43], v[46:47]
	v_pk_fma_f32 v[36:37], v[36:37], v[40:41], v[44:45]
	v_lshlrev_b32_e32 v40, 16, v91
	v_cvt_pk_bf16_f32 v36, v36, v37
	v_cvt_pk_bf16_f32 v37, v38, v39
	v_lshlrev_b32_e32 v38, 16, v90
	v_and_b32_e32 v39, 0xffff0000, v90
	v_and_b32_e32 v41, 0xffff0000, v91
	v_lshlrev_b32_e32 v42, 16, v94
	v_and_b32_e32 v43, 0xffff0000, v94
	v_lshlrev_b32_e32 v44, 16, v95
	v_and_b32_e32 v45, 0xffff0000, v95
	v_pk_fma_f32 v[34:35], v[34:35], v[40:41], v[44:45]
	v_pk_fma_f32 v[32:33], v[32:33], v[38:39], v[42:43]
	v_cvt_pk_bf16_f32 v39, v34, v35
	v_cvt_pk_bf16_f32 v38, v32, v33
	global_store_dwordx4 v[98:99], v[36:39], off offset:256
	v_add_u32_e32 v52, 0xb0, v146
	v_ashrrev_i32_e32 v53, 31, v52
	v_add_u32_e32 v36, 0xa0, v146
	v_ashrrev_i32_e32 v37, 31, v36
	v_lshlrev_b64 v[32:33], 10, v[36:37]
	v_lshl_add_u64 v[32:33], v[32:33], 0, v[144:145]
	v_lshlrev_b64 v[44:45], 1, v[32:33]
	v_lshlrev_b64 v[36:37], 11, v[36:37]
	v_lshl_add_u64 v[32:33], s[6:7], 0, v[44:45]
	v_lshl_add_u64 v[64:65], v[148:149], 0, v[36:37]
	global_load_dwordx4 v[32:35], v[32:33], off
	v_or_b32_e32 v44, 0x100, v44
	global_load_dwordx4 v[36:39], v[64:65], off
	v_lshl_add_u64 v[40:41], s[6:7], 0, v[44:45]
	v_lshl_add_u64 v[44:45], s[0:1], 0, v[44:45]
	global_load_dwordx4 v[40:43], v[40:41], off
	v_lshlrev_b64 v[48:49], 10, v[52:53]
	global_load_dwordx4 v[44:47], v[44:45], off
	v_lshl_add_u64 v[48:49], v[48:49], 0, v[144:145]
	v_lshlrev_b64 v[60:61], 1, v[48:49]
	v_lshlrev_b64 v[52:53], 11, v[52:53]
	v_lshl_add_u64 v[48:49], s[6:7], 0, v[60:61]
	v_lshl_add_u64 v[66:67], v[148:149], 0, v[52:53]
	global_load_dwordx4 v[48:51], v[48:49], off
	v_or_b32_e32 v60, 0x100, v60
	global_load_dwordx4 v[52:55], v[66:67], off
	v_lshl_add_u64 v[56:57], s[6:7], 0, v[60:61]
	v_lshl_add_u64 v[60:61], s[0:1], 0, v[60:61]
	global_load_dwordx4 v[56:59], v[56:57], off
	s_waitcnt vmcnt(6)
; __device__ __forceinline__ u32x2 pack4(f32x4 v) { u32x2 w; w.x = cvt_pk_bf16(v[0], v[1]); w.y = cvt_pk_bf16(v[2], v[3]); return w; }
; __device__ __forceinline__ f32x4 unpack4(u32x2 w) { f32x4 v; v[0] = __uint_as_float(w.x << 16); v[1] = __uint_as_float(w.x & 0xffff0000u); v[2] = __uint_as_float(w.y << 16); v[3] = __uint_as_float(w.y & 0xffff0000u); return v; }
; #define PG8_WAIT_V(n) asm volatile("s_waitcnt vmcnt(" #n ")" ::: "memory")
; #define PG8_BAR __builtin_amdgcn_s_barrier()
;     __device__ __forceinline__ void operator()(const f32x4 (&acc)[2][2][4][2], const Unit& u, int wr, int wc, int fr, int fq) const {
;     ...
;                     for (int n = 0; n < 2; ++n) { const size_t off = (size_t)(row0 + ai * HALF + m * 16) * 1024 + col0 + bj * HALF + n * 4;
;                         pg[m][bj][n] = *(const u32x2*)(G + off); if (ADD) pm_[m][bj][n] = *(const u32x2*)(Mg + off); }
;             asm volatile("" ::: "memory");
; #pragma unroll
;             for (int m = mh; m < mh + 2; ++m)
; #pragma unroll
;                 for (int bj = 0; bj < 2; ++bj)
; #pragma unroll
;                     for (int n = 0; n < 2; ++n) { const size_t off = (size_t)(row0 + ai * HALF + m * 16) * 1024 + col0 + bj * HALF + n * 4;
;                         f32x4 o = unpack4(pg[m][bj][n]) * acc[ai][bj][m][n]; if (ADD) o = o + unpack4(pm_[m][bj][n]);
;                         *(u32x2*)(Mg + off) = pack4(o); }
;             asm volatile("" ::: "memory");
;         }
; template <class Epi, class Sched, bool ALIGN_EPI = false, bool SP2 = false>
; __device__ __forceinline__ void gemm_phase(PG8_LAS unsigned char* lds, const Gemm g, const Sched& S, const Epi& E) {
;     ...
;     PG8_WAIT_V(0);
;     if constexpr (!ALIGN_EPI) { if (wr == 0) PG8_BAR; }
;     PG8_BAR;
	v_lshlrev_b32_e32 v68, 16, v32
	global_load_dwordx4 v[60:63], v[60:61], off
	v_and_b32_e32 v69, 0xffff0000, v32
	v_lshlrev_b32_e32 v32, 16, v33
	v_and_b32_e32 v33, 0xffff0000, v33
	s_waitcnt vmcnt(6)
	v_lshlrev_b32_e32 v70, 16, v36
	v_and_b32_e32 v71, 0xffff0000, v36
	v_lshlrev_b32_e32 v36, 16, v37
	v_and_b32_e32 v37, 0xffff0000, v37
	v_pk_fma_f32 v[30:31], v[30:31], v[32:33], v[36:37]
	v_pk_fma_f32 v[28:29], v[28:29], v[68:69], v[70:71]
	v_lshlrev_b32_e32 v32, 16, v35
	v_cvt_pk_bf16_f32 v28, v28, v29
	v_cvt_pk_bf16_f32 v29, v30, v31
	v_lshlrev_b32_e32 v30, 16, v34
	v_and_b32_e32 v31, 0xffff0000, v34
	v_and_b32_e32 v33, 0xffff0000, v35
	v_lshlrev_b32_e32 v34, 16, v38
	v_and_b32_e32 v35, 0xffff0000, v38
	v_lshlrev_b32_e32 v36, 16, v39
	v_and_b32_e32 v37, 0xffff0000, v39
	v_pk_fma_f32 v[26:27], v[26:27], v[32:33], v[36:37]
	v_pk_fma_f32 v[24:25], v[24:25], v[30:31], v[34:35]
	v_cvt_pk_bf16_f32 v31, v26, v27
	v_cvt_pk_bf16_f32 v30, v24, v25
	global_store_dwordx4 v[64:65], v[28:31], off
	s_waitcnt vmcnt(6)
	v_lshlrev_b32_e32 v24, 16, v40
	v_and_b32_e32 v25, 0xffff0000, v40
	v_lshlrev_b32_e32 v26, 16, v41
	v_and_b32_e32 v27, 0xffff0000, v41
	s_waitcnt vmcnt(5)
	v_lshlrev_b32_e32 v28, 16, v44
	v_and_b32_e32 v29, 0xffff0000, v44
	v_lshlrev_b32_e32 v30, 16, v45
	v_and_b32_e32 v31, 0xffff0000, v45
	v_pk_fma_f32 v[22:23], v[22:23], v[26:27], v[30:31]
	v_pk_fma_f32 v[20:21], v[20:21], v[24:25], v[28:29]
	v_lshlrev_b32_e32 v24, 16, v43
	v_cvt_pk_bf16_f32 v20, v20, v21
	v_cvt_pk_bf16_f32 v21, v22, v23
	v_lshlrev_b32_e32 v22, 16, v42
	v_and_b32_e32 v23, 0xffff0000, v42
	v_and_b32_e32 v25, 0xffff0000, v43
	v_lshlrev_b32_e32 v26, 16, v46
	v_and_b32_e32 v27, 0xffff0000, v46
	v_lshlrev_b32_e32 v28, 16, v47
	v_and_b32_e32 v29, 0xffff0000, v47
	v_pk_fma_f32 v[14:15], v[14:15], v[24:25], v[28:29]
	v_pk_fma_f32 v[12:13], v[12:13], v[22:23], v[26:27]
	v_cvt_pk_bf16_f32 v23, v14, v15
	v_cvt_pk_bf16_f32 v22, v12, v13
	global_store_dwordx4 v[64:65], v[20:23], off offset:256
	s_waitcnt vmcnt(5)
	v_lshlrev_b32_e32 v12, 16, v48
	v_and_b32_e32 v13, 0xffff0000, v48
	v_lshlrev_b32_e32 v14, 16, v49
	v_and_b32_e32 v15, 0xffff0000, v49
	s_waitcnt vmcnt(4)
	v_lshlrev_b32_e32 v20, 16, v52
	v_and_b32_e32 v21, 0xffff0000, v52
	v_lshlrev_b32_e32 v22, 16, v53
	v_and_b32_e32 v23, 0xffff0000, v53
	v_pk_fma_f32 v[14:15], v[18:19], v[14:15], v[22:23]
	v_pk_fma_f32 v[12:13], v[16:17], v[12:13], v[20:21]
	v_lshlrev_b32_e32 v16, 16, v51
	v_cvt_pk_bf16_f32 v12, v12, v13
	v_cvt_pk_bf16_f32 v13, v14, v15
	v_lshlrev_b32_e32 v14, 16, v50
	v_and_b32_e32 v15, 0xffff0000, v50
	v_and_b32_e32 v17, 0xffff0000, v51
	v_lshlrev_b32_e32 v18, 16, v54
	v_and_b32_e32 v19, 0xffff0000, v54
	v_lshlrev_b32_e32 v20, 16, v55
	v_and_b32_e32 v21, 0xffff0000, v55
	v_pk_fma_f32 v[10:11], v[10:11], v[16:17], v[20:21]
	v_pk_fma_f32 v[8:9], v[8:9], v[14:15], v[18:19]
	v_cvt_pk_bf16_f32 v15, v10, v11
	v_cvt_pk_bf16_f32 v14, v8, v9
	global_store_dwordx4 v[66:67], v[12:15], off
	s_waitcnt vmcnt(4)
	v_lshlrev_b32_e32 v8, 16, v56
	v_and_b32_e32 v9, 0xffff0000, v56
	v_lshlrev_b32_e32 v10, 16, v57
	v_and_b32_e32 v11, 0xffff0000, v57
	s_waitcnt vmcnt(3)
	v_lshlrev_b32_e32 v12, 16, v60
	v_and_b32_e32 v13, 0xffff0000, v60
	v_lshlrev_b32_e32 v14, 16, v61
	v_and_b32_e32 v15, 0xffff0000, v61
	v_pk_fma_f32 v[6:7], v[6:7], v[10:11], v[14:15]
	v_pk_fma_f32 v[4:5], v[4:5], v[8:9], v[12:13]
	v_lshlrev_b32_e32 v8, 16, v59
	v_cvt_pk_bf16_f32 v4, v4, v5
	v_cvt_pk_bf16_f32 v5, v6, v7
	v_lshlrev_b32_e32 v6, 16, v58
	v_and_b32_e32 v7, 0xffff0000, v58
	v_and_b32_e32 v9, 0xffff0000, v59
	v_lshlrev_b32_e32 v10, 16, v62
	v_and_b32_e32 v11, 0xffff0000, v62
	v_lshlrev_b32_e32 v12, 16, v63
	v_and_b32_e32 v13, 0xffff0000, v63
	v_pk_fma_f32 v[2:3], v[2:3], v[8:9], v[12:13]
	v_pk_fma_f32 v[0:1], v[0:1], v[6:7], v[10:11]
	v_cvt_pk_bf16_f32 v7, v2, v3
	v_cvt_pk_bf16_f32 v6, v0, v1
	global_store_dwordx4 v[66:67], v[4:7], off offset:256
	s_cbranch_vccz .LBB0_744
	s_waitcnt vmcnt(0)
	s_cmpk_gt_u32 s40, 0xff
	s_cbranch_scc1 .LBB0_751
	s_barrier

; #define PG8_STAGE(bufoff, gbase, voff) do { _Pragma("unroll") for (int _i = 0; _i < 2; ++_i) \
;         __builtin_amdgcn_global_load_lds((const unsigned*)((const char*)(gbase) + (voff)[_i]), (PG8_LAS unsigned*)(lds + (bufoff) + ldsw + _i * 8192), 16, 0, 0); } while (0)
; #define PG8_LDA(dst, b, h) do { _Pragma("unroll") for (int m = 0; m < 4; ++m) _Pragma("unroll") for (int k = 0; k < 2; ++k) dst[m][k] = *(const PG8_LAS bf16x8*)(lds + PG8_SA(b, h) + aoff + m * 2048 + k * 1024); } while (0)
; #define PG8_LDB(dst, b, h) do { _Pragma("unroll") for (int n = 0; n < 2; ++n) _Pragma("unroll") for (int k = 0; k < 2; ++k) dst[n][k] = *(const PG8_LAS bf16x8*)(lds + PG8_SB(b, h) + boff + n * 2048 + k * 1024); } while (0)
; #define PG8_MMA(ai, bj, At, Bt) do { __builtin_amdgcn_s_setprio(1); _Pragma("unroll") for (int m = 0; m < 4; ++m) _Pragma("unroll") for (int n = 0; n < 2; ++n) _Pragma("unroll") for (int k = 0; k < 2; ++k) \
;         acc[ai][bj][m][n] = __builtin_amdgcn_mfma_f32_16x16x32_bf16(Bt[n][k], At[m][k], acc[ai][bj][m][n], 0, 0, 0); __builtin_amdgcn_s_setprio(0); } while (0)
; #define PG8_WAIT_V(n) asm volatile("s_waitcnt vmcnt(" #n ")" ::: "memory")
; #define PG8_WAIT_L(n) asm volatile("s_waitcnt lgkmcnt(" #n ")" ::: "memory")
; #define PG8_BAR __builtin_amdgcn_s_barrier()
; #define PG8_SCHED __builtin_amdgcn_sched_barrier(0)
; template <class Epi, class Sched, bool ALIGN_EPI = false, bool SP2 = false>
; __device__ __forceinline__ void gemm_phase(PG8_LAS unsigned char* lds, const Gemm g, const Sched& S, const Epi& E) {
;     ...
;             PG8_LDB(B0, 0, 0); PG8_LDB(B1, 0, 1); PG8_SCHED; PG8_LDA(At, 0, 0); PG8_STAGE(PG8_SA(1, 1), a1 + hstep, voffA);
;             PG8_WAIT_V(8); PG8_WAIT_L(0); PG8_BAR; PG8_MMA(0, 0, At, B0); PG8_MMA(0, 1, At, B1); PG8_BAR; PG8_SCHED;
;             PG8_LDA(At, 0, 1); PG8_STAGE(PG8_SB(0, 0), b2, voffB); PG8_STAGE(PG8_SB(0, 1), b2 + hstep, voffB); PG8_STAGE(PG8_SA(0, 0), a2, voffA);
;             PG8_WAIT_V(8); PG8_WAIT_L(0); PG8_BAR; PG8_MMA(1, 0, At, B0); PG8_MMA(1, 1, At, B1); PG8_BAR; PG8_SCHED;
.LBB0_813:
	ds_read_b128 v[128:131], v173
	ds_read_b128 v[132:135], v173 offset:1024
	ds_read_b128 v[136:139], v173 offset:2048
	ds_read_b128 v[140:143], v173 offset:3072
	ds_read_b128 v[160:163], v174
	ds_read_b128 v[164:167], v174 offset:1024
	ds_read_b128 v[178:181], v174 offset:2048
	ds_read_b128 v[182:185], v174 offset:3072
	s_add_u32 s26, s24, 0xfffc0080
	s_addc_u32 s27, s25, -1
	s_cmp_eq_u32 s70, 12
	s_cselect_b32 s37, s15, s27
	s_cselect_b32 s36, s60, s26
	s_cselect_b32 s27, s13, s69
	s_cselect_b32 s26, s61, s68
	v_lshl_add_u64 v[168:169], s[24:25], 0, v[152:153]
	s_add_i32 m0, s42, 0xc000
	ds_read_b128 v[186:189], v175
	ds_read_b128 v[190:193], v175 offset:1024
	ds_read_b128 v[194:197], v175 offset:2048
	ds_read_b128 v[198:201], v175 offset:3072
	ds_read_b128 v[202:205], v175 offset:4096
	ds_read_b128 v[206:209], v175 offset:5120
	ds_read_b128 v[210:213], v175 offset:6144
	ds_read_b128 v[214:217], v175 offset:7168
	global_load_lds_dwordx4 v[168:169], off
	v_lshl_add_u64 v[168:169], s[24:25], 0, v[154:155]
	s_add_i32 m0, s42, 0xe000
	s_nop 0
	global_load_lds_dwordx4 v[168:169], off
	s_waitcnt vmcnt(8)
	s_waitcnt lgkmcnt(0)
	s_barrier
	s_setprio 1
	s_waitcnt lgkmcnt(0)
	v_mfma_f32_16x16x32_bf16 v[124:127], v[128:131], v[186:189], v[124:127]
	v_mfma_f32_16x16x32_bf16 v[120:123], v[136:139], v[186:189], v[120:123]
	v_mfma_f32_16x16x32_bf16 v[108:111], v[128:131], v[194:197], v[108:111]
	v_mfma_f32_16x16x32_bf16 v[104:107], v[136:139], v[194:197], v[104:107]
	v_mfma_f32_16x16x32_bf16 v[92:95], v[128:131], v[202:205], v[92:95]
	v_mfma_f32_16x16x32_bf16 v[88:91], v[136:139], v[202:205], v[88:91]
	v_mfma_f32_16x16x32_bf16 v[76:79], v[128:131], v[210:213], v[76:79]
	v_mfma_f32_16x16x32_bf16 v[72:75], v[136:139], v[210:213], v[72:75]
	v_mfma_f32_16x16x32_bf16 v[124:127], v[132:135], v[190:193], v[124:127]
	v_mfma_f32_16x16x32_bf16 v[120:123], v[140:143], v[190:193], v[120:123]
	v_mfma_f32_16x16x32_bf16 v[108:111], v[132:135], v[198:201], v[108:111]
	v_mfma_f32_16x16x32_bf16 v[104:107], v[140:143], v[198:201], v[104:107]
	v_mfma_f32_16x16x32_bf16 v[92:95], v[132:135], v[206:209], v[92:95]
	v_mfma_f32_16x16x32_bf16 v[88:91], v[140:143], v[206:209], v[88:91]
	v_mfma_f32_16x16x32_bf16 v[76:79], v[132:135], v[214:217], v[76:79]
	v_mfma_f32_16x16x32_bf16 v[72:75], v[140:143], v[214:217], v[72:75]
	s_setprio 0
	s_setprio 1
	v_mfma_f32_16x16x32_bf16 v[116:119], v[160:163], v[186:189], v[116:119]
	v_mfma_f32_16x16x32_bf16 v[112:115], v[178:181], v[186:189], v[112:115]
	v_mfma_f32_16x16x32_bf16 v[100:103], v[160:163], v[194:197], v[100:103]
	v_mfma_f32_16x16x32_bf16 v[96:99], v[178:181], v[194:197], v[96:99]
	v_mfma_f32_16x16x32_bf16 v[84:87], v[160:163], v[202:205], v[84:87]
	v_mfma_f32_16x16x32_bf16 v[80:83], v[178:181], v[202:205], v[80:83]
	v_mfma_f32_16x16x32_bf16 v[68:71], v[160:163], v[210:213], v[68:71]
	v_mfma_f32_16x16x32_bf16 v[64:67], v[178:181], v[210:213], v[64:67]
	v_mfma_f32_16x16x32_bf16 v[116:119], v[164:167], v[190:193], v[116:119]
	v_mfma_f32_16x16x32_bf16 v[112:115], v[182:185], v[190:193], v[112:115]
	v_mfma_f32_16x16x32_bf16 v[100:103], v[164:167], v[198:201], v[100:103]
	v_mfma_f32_16x16x32_bf16 v[96:99], v[182:185], v[198:201], v[96:99]
	v_mfma_f32_16x16x32_bf16 v[84:87], v[164:167], v[206:209], v[84:87]
	v_mfma_f32_16x16x32_bf16 v[80:83], v[182:185], v[206:209], v[80:83]
	v_mfma_f32_16x16x32_bf16 v[68:71], v[164:167], v[214:217], v[68:71]
	v_mfma_f32_16x16x32_bf16 v[64:67], v[182:185], v[214:217], v[64:67]
	s_setprio 0
	s_barrier
	s_sleep 1
	s_add_i32 s71, s52, s39
	v_lshl_add_u64 v[168:169], s[26:27], 0, v[148:149]
	s_mov_b32 m0, s71
	ds_read_b128 v[186:189], v175 offset:16384
	ds_read_b128 v[190:193], v175 offset:17408
	ds_read_b128 v[194:197], v175 offset:18432
	ds_read_b128 v[198:201], v175 offset:19456
	ds_read_b128 v[202:205], v175 offset:20480
	ds_read_b128 v[206:209], v175 offset:21504
	ds_read_b128 v[210:213], v175 offset:22528
	ds_read_b128 v[214:217], v175 offset:23552
	global_load_lds_dwordx4 v[168:169], off
	s_add_i32 m0, s71, 0x2000
	s_add_u32 s72, s26, 0x40000
	v_lshl_add_u64 v[218:219], s[26:27], 0, v[144:145]
	s_addc_u32 s73, s27, 0
	s_add_i32 s71, s53, s39
	global_load_lds_dwordx4 v[218:219], off
	v_lshl_add_u64 v[220:221], s[72:73], 0, v[148:149]
	s_mov_b32 m0, s71
	v_lshl_add_u64 v[222:223], s[36:37], 0, v[146:147]
	global_load_lds_dwordx4 v[220:221], off
	v_lshl_add_u64 v[220:221], s[72:73], 0, v[144:145]
	s_add_i32 m0, s71, 0x2000
	s_nop 0
	global_load_lds_dwordx4 v[220:221], off
	v_lshl_add_u64 v[220:221], s[36:37], 0, v[150:151]
	s_mov_b32 m0, s42
	s_nop 0
	global_load_lds_dwordx4 v[220:221], off
	s_mov_b32 m0, s43
	s_nop 0
	global_load_lds_dwordx4 v[222:223], off
	s_waitcnt vmcnt(8)
	s_waitcnt lgkmcnt(0)
	s_barrier
; #define PG8_STAGE(bufoff, gbase, voff) do { _Pragma("unroll") for (int _i = 0; _i < 2; ++_i) \
;         __builtin_amdgcn_global_load_lds((const unsigned*)((const char*)(gbase) + (voff)[_i]), (PG8_LAS unsigned*)(lds + (bufoff) + ldsw + _i * 8192), 16, 0, 0); } while (0)
; #define PG8_LDA(dst, b, h) do { _Pragma("unroll") for (int m = 0; m < 4; ++m) _Pragma("unroll") for (int k = 0; k < 2; ++k) dst[m][k] = *(const PG8_LAS bf16x8*)(lds + PG8_SA(b, h) + aoff + m * 2048 + k * 1024); } while (0)
; #define PG8_LDB(dst, b, h) do { _Pragma("unroll") for (int n = 0; n < 2; ++n) _Pragma("unroll") for (int k = 0; k < 2; ++k) dst[n][k] = *(const PG8_LAS bf16x8*)(lds + PG8_SB(b, h) + boff + n * 2048 + k * 1024); } while (0)
; #define PG8_MMA(ai, bj, At, Bt) do { __builtin_amdgcn_s_setprio(1); _Pragma("unroll") for (int m = 0; m < 4; ++m) _Pragma("unroll") for (int n = 0; n < 2; ++n) _Pragma("unroll") for (int k = 0; k < 2; ++k) \
;         acc[ai][bj][m][n] = __builtin_amdgcn_mfma_f32_16x16x32_bf16(Bt[n][k], At[m][k], acc[ai][bj][m][n], 0, 0, 0); __builtin_amdgcn_s_setprio(0); } while (0)
; #define PG8_WAIT_V(n) asm volatile("s_waitcnt vmcnt(" #n ")" ::: "memory")
; #define PG8_WAIT_L(n) asm volatile("s_waitcnt lgkmcnt(" #n ")" ::: "memory")
; #define PG8_BAR __builtin_amdgcn_s_barrier()
; #define PG8_SCHED __builtin_amdgcn_sched_barrier(0)
; template <class Epi, class Sched, bool ALIGN_EPI = false, bool SP2 = false>
; __device__ __forceinline__ void gemm_phase(PG8_LAS unsigned char* lds, const Gemm g, const Sched& S, const Epi& E) {
;     ...
;             PG8_WAIT_V(8); PG8_WAIT_L(0); PG8_BAR; PG8_MMA(1, 0, At, B0); PG8_MMA(1, 1, At, B1); PG8_BAR; PG8_SCHED;
;             PG8_LDB(B0, 1, 0); PG8_LDB(B1, 1, 1); PG8_SCHED; PG8_LDA(At, 1, 0); PG8_STAGE(PG8_SA(0, 1), a2 + hstep, voffA);
;             PG8_WAIT_V(8); PG8_WAIT_L(0); PG8_BAR; PG8_MMA(0, 0, At, B0); PG8_MMA(0, 1, At, B1); PG8_BAR; PG8_SCHED;
;             PG8_LDA(At, 1, 1); PG8_STAGE(PG8_SB(1, 0), b3, voffB); PG8_STAGE(PG8_SB(1, 1), b3 + hstep, voffB); PG8_STAGE(PG8_SA(1, 0), a3, voffA);
	s_setprio 1
	s_waitcnt lgkmcnt(0)
	v_mfma_f32_16x16x32_bf16 v[60:63], v[128:131], v[186:189], v[60:63]
	v_mfma_f32_16x16x32_bf16 v[56:59], v[136:139], v[186:189], v[56:59]
	v_mfma_f32_16x16x32_bf16 v[44:47], v[128:131], v[194:197], v[44:47]
	v_mfma_f32_16x16x32_bf16 v[40:43], v[136:139], v[194:197], v[40:43]
	v_mfma_f32_16x16x32_bf16 v[28:31], v[128:131], v[202:205], v[28:31]
	v_mfma_f32_16x16x32_bf16 v[24:27], v[136:139], v[202:205], v[24:27]
	v_mfma_f32_16x16x32_bf16 v[12:15], v[128:131], v[210:213], v[12:15]
	v_mfma_f32_16x16x32_bf16 v[8:11], v[136:139], v[210:213], v[8:11]
	v_mfma_f32_16x16x32_bf16 v[60:63], v[132:135], v[190:193], v[60:63]
	v_mfma_f32_16x16x32_bf16 v[56:59], v[140:143], v[190:193], v[56:59]
	v_mfma_f32_16x16x32_bf16 v[44:47], v[132:135], v[198:201], v[44:47]
	v_mfma_f32_16x16x32_bf16 v[40:43], v[140:143], v[198:201], v[40:43]
	v_mfma_f32_16x16x32_bf16 v[28:31], v[132:135], v[206:209], v[28:31]
	v_mfma_f32_16x16x32_bf16 v[24:27], v[140:143], v[206:209], v[24:27]
	v_mfma_f32_16x16x32_bf16 v[12:15], v[132:135], v[214:217], v[12:15]
	v_mfma_f32_16x16x32_bf16 v[8:11], v[140:143], v[214:217], v[8:11]
	s_setprio 0
	s_setprio 1
	v_mfma_f32_16x16x32_bf16 v[52:55], v[160:163], v[186:189], v[52:55]
	v_mfma_f32_16x16x32_bf16 v[48:51], v[178:181], v[186:189], v[48:51]
	v_mfma_f32_16x16x32_bf16 v[36:39], v[160:163], v[194:197], v[36:39]
	v_mfma_f32_16x16x32_bf16 v[32:35], v[178:181], v[194:197], v[32:35]
	v_mfma_f32_16x16x32_bf16 v[20:23], v[160:163], v[202:205], v[20:23]
	v_mfma_f32_16x16x32_bf16 v[16:19], v[178:181], v[202:205], v[16:19]
	v_mfma_f32_16x16x32_bf16 v[4:7], v[160:163], v[210:213], v[4:7]
	v_mfma_f32_16x16x32_bf16 v[0:3], v[178:181], v[210:213], v[0:3]
	v_mfma_f32_16x16x32_bf16 v[52:55], v[164:167], v[190:193], v[52:55]
	v_mfma_f32_16x16x32_bf16 v[48:51], v[182:185], v[190:193], v[48:51]
	v_mfma_f32_16x16x32_bf16 v[36:39], v[164:167], v[198:201], v[36:39]
	v_mfma_f32_16x16x32_bf16 v[32:35], v[182:185], v[198:201], v[32:35]
	v_mfma_f32_16x16x32_bf16 v[20:23], v[164:167], v[206:209], v[20:23]
	v_mfma_f32_16x16x32_bf16 v[16:19], v[182:185], v[206:209], v[16:19]
	v_mfma_f32_16x16x32_bf16 v[4:7], v[164:167], v[214:217], v[4:7]
	v_mfma_f32_16x16x32_bf16 v[0:3], v[182:185], v[214:217], v[0:3]
	s_setprio 0
	s_barrier
	s_sleep 1
	s_add_i32 s71, 0, 0x18000
	s_add_i32 s72, 0, 0x1c000
	v_add_u32_e32 v140, s71, v171
	v_add_u32_e32 v177, s72, v171
	ds_read_b128 v[128:131], v140
	ds_read_b128 v[132:135], v140 offset:1024
	ds_read_b128 v[136:139], v140 offset:2048
	ds_read_b128 v[140:143], v140 offset:3072
	ds_read_b128 v[160:163], v177
	ds_read_b128 v[164:167], v177 offset:1024
	ds_read_b128 v[178:181], v177 offset:2048
	ds_read_b128 v[182:185], v177 offset:3072
	s_add_u32 s36, s36, 0x40000
	s_addc_u32 s37, s37, 0
	s_mov_b32 m0, s44
	v_lshl_add_u64 v[224:225], s[36:37], 0, v[150:151]
	ds_read_b128 v[186:189], v175 offset:32768
	ds_read_b128 v[190:193], v175 offset:33792
	ds_read_b128 v[194:197], v175 offset:34816
	ds_read_b128 v[198:201], v175 offset:35840
	ds_read_b128 v[202:205], v175 offset:36864
	ds_read_b128 v[206:209], v175 offset:37888
	ds_read_b128 v[210:213], v175 offset:38912
	ds_read_b128 v[214:217], v175 offset:39936
	global_load_lds_dwordx4 v[224:225], off
	v_lshl_add_u64 v[224:225], s[36:37], 0, v[146:147]
	s_mov_b32 m0, s45
	s_nop 0
	global_load_lds_dwordx4 v[224:225], off
	s_waitcnt vmcnt(8)
	s_waitcnt lgkmcnt(0)
	s_barrier
	s_setprio 1
	s_waitcnt lgkmcnt(0)
	v_mfma_f32_16x16x32_bf16 v[124:127], v[128:131], v[186:189], v[124:127]
	v_mfma_f32_16x16x32_bf16 v[120:123], v[136:139], v[186:189], v[120:123]
	v_mfma_f32_16x16x32_bf16 v[108:111], v[128:131], v[194:197], v[108:111]
	v_mfma_f32_16x16x32_bf16 v[104:107], v[136:139], v[194:197], v[104:107]
	v_mfma_f32_16x16x32_bf16 v[92:95], v[128:131], v[202:205], v[92:95]
	v_mfma_f32_16x16x32_bf16 v[88:91], v[136:139], v[202:205], v[88:91]
	v_mfma_f32_16x16x32_bf16 v[76:79], v[128:131], v[210:213], v[76:79]
	v_mfma_f32_16x16x32_bf16 v[72:75], v[136:139], v[210:213], v[72:75]
	v_mfma_f32_16x16x32_bf16 v[124:127], v[132:135], v[190:193], v[124:127]
	v_mfma_f32_16x16x32_bf16 v[120:123], v[140:143], v[190:193], v[120:123]
	v_mfma_f32_16x16x32_bf16 v[108:111], v[132:135], v[198:201], v[108:111]
	v_mfma_f32_16x16x32_bf16 v[104:107], v[140:143], v[198:201], v[104:107]
	v_mfma_f32_16x16x32_bf16 v[92:95], v[132:135], v[206:209], v[92:95]
	v_mfma_f32_16x16x32_bf16 v[88:91], v[140:143], v[206:209], v[88:91]
	v_mfma_f32_16x16x32_bf16 v[76:79], v[132:135], v[214:217], v[76:79]
	v_mfma_f32_16x16x32_bf16 v[72:75], v[140:143], v[214:217], v[72:75]
	s_setprio 0
	s_setprio 1
	v_mfma_f32_16x16x32_bf16 v[116:119], v[160:163], v[186:189], v[116:119]
	v_mfma_f32_16x16x32_bf16 v[112:115], v[178:181], v[186:189], v[112:115]
	v_mfma_f32_16x16x32_bf16 v[100:103], v[160:163], v[194:197], v[100:103]
	v_mfma_f32_16x16x32_bf16 v[96:99], v[178:181], v[194:197], v[96:99]
	v_mfma_f32_16x16x32_bf16 v[84:87], v[160:163], v[202:205], v[84:87]
	v_mfma_f32_16x16x32_bf16 v[80:83], v[178:181], v[202:205], v[80:83]
	v_mfma_f32_16x16x32_bf16 v[68:71], v[160:163], v[210:213], v[68:71]
	v_mfma_f32_16x16x32_bf16 v[64:67], v[178:181], v[210:213], v[64:67]
	v_mfma_f32_16x16x32_bf16 v[116:119], v[164:167], v[190:193], v[116:119]
	v_mfma_f32_16x16x32_bf16 v[112:115], v[182:185], v[190:193], v[112:115]
	v_mfma_f32_16x16x32_bf16 v[100:103], v[164:167], v[198:201], v[100:103]
	v_mfma_f32_16x16x32_bf16 v[96:99], v[182:185], v[198:201], v[96:99]
	v_mfma_f32_16x16x32_bf16 v[84:87], v[164:167], v[206:209], v[84:87]
	v_mfma_f32_16x16x32_bf16 v[80:83], v[182:185], v[206:209], v[80:83]
	v_mfma_f32_16x16x32_bf16 v[68:71], v[164:167], v[214:217], v[68:71]
	v_mfma_f32_16x16x32_bf16 v[64:67], v[182:185], v[214:217], v[64:67]
	s_setprio 0
	s_barrier
; #define PG8_STAGE(bufoff, gbase, voff) do { _Pragma("unroll") for (int _i = 0; _i < 2; ++_i) \
;         __builtin_amdgcn_global_load_lds((const unsigned*)((const char*)(gbase) + (voff)[_i]), (PG8_LAS unsigned*)(lds + (bufoff) + ldsw + _i * 8192), 16, 0, 0); } while (0)
; #define PG8_LDA(dst, b, h) do { _Pragma("unroll") for (int m = 0; m < 4; ++m) _Pragma("unroll") for (int k = 0; k < 2; ++k) dst[m][k] = *(const PG8_LAS bf16x8*)(lds + PG8_SA(b, h) + aoff + m * 2048 + k * 1024); } while (0)
; #define PG8_MMA(ai, bj, At, Bt) do { __builtin_amdgcn_s_setprio(1); _Pragma("unroll") for (int m = 0; m < 4; ++m) _Pragma("unroll") for (int n = 0; n < 2; ++n) _Pragma("unroll") for (int k = 0; k < 2; ++k) \
;         acc[ai][bj][m][n] = __builtin_amdgcn_mfma_f32_16x16x32_bf16(Bt[n][k], At[m][k], acc[ai][bj][m][n], 0, 0, 0); __builtin_amdgcn_s_setprio(0); } while (0)
; #define PG8_WAIT_V(n) asm volatile("s_waitcnt vmcnt(" #n ")" ::: "memory")
; #define PG8_WAIT_L(n) asm volatile("s_waitcnt lgkmcnt(" #n ")" ::: "memory")
; #define PG8_BAR __builtin_amdgcn_s_barrier()
; #define PG8_SCHED __builtin_amdgcn_sched_barrier(0)
; template <class Epi, class Sched, bool ALIGN_EPI = false, bool SP2 = false>
; __device__ __forceinline__ void gemm_phase(PG8_LAS unsigned char* lds, const Gemm g, const Sched& S, const Epi& E) {
;     ...
;             PG8_WAIT_V(8); PG8_WAIT_L(0); PG8_BAR; PG8_MMA(0, 0, At, B0); PG8_MMA(0, 1, At, B1); PG8_BAR; PG8_SCHED;
;             PG8_LDA(At, 1, 1); PG8_STAGE(PG8_SB(1, 0), b3, voffB); PG8_STAGE(PG8_SB(1, 1), b3 + hstep, voffB); PG8_STAGE(PG8_SA(1, 0), a3, voffA);
;             PG8_WAIT_V(8); PG8_WAIT_L(0); PG8_BAR; PG8_MMA(1, 0, At, B0); PG8_MMA(1, 1, At, B1); PG8_BAR; PG8_SCHED;
	s_sleep 1
	s_add_i32 s36, s71, s39
	v_lshl_add_u64 v[168:169], v[168:169], 0, s[6:7]
	s_mov_b32 m0, s36
	ds_read_b128 v[186:189], v175 offset:49152
	ds_read_b128 v[190:193], v175 offset:50176
	ds_read_b128 v[194:197], v175 offset:51200
	ds_read_b128 v[198:201], v175 offset:52224
	ds_read_b128 v[202:205], v175 offset:53248
	ds_read_b128 v[206:209], v175 offset:54272
	ds_read_b128 v[210:213], v175 offset:55296
	ds_read_b128 v[214:217], v175 offset:56320
	global_load_lds_dwordx4 v[168:169], off
	s_add_i32 m0, s36, 0x2000
	s_add_u32 s26, s26, 0x40080
	v_lshl_add_u64 v[168:169], v[218:219], 0, s[6:7]
	s_addc_u32 s27, s27, 0
	s_add_i32 s36, s72, s39
	global_load_lds_dwordx4 v[168:169], off
	v_lshl_add_u64 v[168:169], s[26:27], 0, v[148:149]
	s_mov_b32 m0, s36
	s_nop 0
	global_load_lds_dwordx4 v[168:169], off
	v_lshl_add_u64 v[168:169], s[26:27], 0, v[144:145]
	s_add_i32 m0, s36, 0x2000
	s_nop 0
	global_load_lds_dwordx4 v[168:169], off
	v_lshl_add_u64 v[168:169], v[220:221], 0, s[6:7]
	s_mov_b32 m0, s47
	s_nop 0
	global_load_lds_dwordx4 v[168:169], off
	v_lshl_add_u64 v[168:169], v[222:223], 0, s[6:7]
	s_mov_b32 m0, s48
	s_nop 0
	global_load_lds_dwordx4 v[168:169], off
	s_waitcnt vmcnt(8)
	s_waitcnt lgkmcnt(0)
	s_barrier
	s_setprio 1
	s_waitcnt lgkmcnt(0)
	v_mfma_f32_16x16x32_bf16 v[60:63], v[128:131], v[186:189], v[60:63]
	v_mfma_f32_16x16x32_bf16 v[56:59], v[136:139], v[186:189], v[56:59]
	v_mfma_f32_16x16x32_bf16 v[44:47], v[128:131], v[194:197], v[44:47]
	v_mfma_f32_16x16x32_bf16 v[40:43], v[136:139], v[194:197], v[40:43]
	v_mfma_f32_16x16x32_bf16 v[28:31], v[128:131], v[202:205], v[28:31]
	v_mfma_f32_16x16x32_bf16 v[24:27], v[136:139], v[202:205], v[24:27]
	v_mfma_f32_16x16x32_bf16 v[12:15], v[128:131], v[210:213], v[12:15]
	v_mfma_f32_16x16x32_bf16 v[8:11], v[136:139], v[210:213], v[8:11]
	v_mfma_f32_16x16x32_bf16 v[60:63], v[132:135], v[190:193], v[60:63]
	v_mfma_f32_16x16x32_bf16 v[56:59], v[140:143], v[190:193], v[56:59]
	v_mfma_f32_16x16x32_bf16 v[44:47], v[132:135], v[198:201], v[44:47]
	v_mfma_f32_16x16x32_bf16 v[40:43], v[140:143], v[198:201], v[40:43]
	v_mfma_f32_16x16x32_bf16 v[28:31], v[132:135], v[206:209], v[28:31]
	v_mfma_f32_16x16x32_bf16 v[24:27], v[140:143], v[206:209], v[24:27]
	v_mfma_f32_16x16x32_bf16 v[12:15], v[132:135], v[214:217], v[12:15]
	v_mfma_f32_16x16x32_bf16 v[8:11], v[140:143], v[214:217], v[8:11]
	s_setprio 0
	s_setprio 1
	v_mfma_f32_16x16x32_bf16 v[52:55], v[160:163], v[186:189], v[52:55]
	v_mfma_f32_16x16x32_bf16 v[48:51], v[178:181], v[186:189], v[48:51]
	v_mfma_f32_16x16x32_bf16 v[36:39], v[160:163], v[194:197], v[36:39]
	v_mfma_f32_16x16x32_bf16 v[32:35], v[178:181], v[194:197], v[32:35]
	v_mfma_f32_16x16x32_bf16 v[20:23], v[160:163], v[202:205], v[20:23]
	v_mfma_f32_16x16x32_bf16 v[16:19], v[178:181], v[202:205], v[16:19]
	v_mfma_f32_16x16x32_bf16 v[4:7], v[160:163], v[210:213], v[4:7]
	v_mfma_f32_16x16x32_bf16 v[0:3], v[178:181], v[210:213], v[0:3]
	v_mfma_f32_16x16x32_bf16 v[52:55], v[164:167], v[190:193], v[52:55]
	v_mfma_f32_16x16x32_bf16 v[48:51], v[182:185], v[190:193], v[48:51]
	v_mfma_f32_16x16x32_bf16 v[36:39], v[164:167], v[198:201], v[36:39]
	v_mfma_f32_16x16x32_bf16 v[32:35], v[182:185], v[198:201], v[32:35]
	v_mfma_f32_16x16x32_bf16 v[20:23], v[164:167], v[206:209], v[20:23]
	v_mfma_f32_16x16x32_bf16 v[16:19], v[182:185], v[206:209], v[16:19]
	v_mfma_f32_16x16x32_bf16 v[4:7], v[164:167], v[214:217], v[4:7]
	v_mfma_f32_16x16x32_bf16 v[0:3], v[182:185], v[214:217], v[0:3]
	s_setprio 0
	s_barrier
	s_sleep 1
	s_add_i32 s70, s70, 2
	s_add_u32 s24, s24, 0x100
	s_addc_u32 s25, s25, 0
	s_add_u32 s68, s68, 0x100
	s_addc_u32 s69, s69, 0
	s_cmp_gt_u32 s70, 13
	s_cbranch_scc0 .LBB0_813
; __device__ __forceinline__ u32x2 pack4(f32x4 v) { u32x2 w; w.x = cvt_pk_bf16(v[0], v[1]); w.y = cvt_pk_bf16(v[2], v[3]); return w; }
;     __device__ __forceinline__ void operator()(const f32x4 (&acc)[2][2][4][2], const Unit& u, int wr, int wc, int fr, int fq) const {
;     ...
;                     for (int n = 0; n < 2; ++n) pre[m][bj][n] = *(const f32x4*)(base + (size_t)(row0 + ai * HALF + m * 16) * 1024 + col0 + bj * HALF + n * 4);
;             asm volatile("" ::: "memory");
; #pragma unroll
;             for (int m = mh; m < mh + 2; ++m) { const int row = row0 + ai * HALF + m * 16; const size_t off = (size_t)row * 1024 + col0; float ss = 0.f;
; #pragma unroll
;                 for (int bj = 0; bj < 2; ++bj) { u32x4e w;
; #pragma unroll
;                     for (int n = 0; n < 2; ++n) { const f32x4 o = pre[m][bj][n] + acc[ai][bj][m][n] * s;
;                         *(f32x4*)(out + off + bj * HALF + n * 4) = o;
;                         if (NORMOUT) { const u32x2 p = pack4(o); w[2 * n] = p.x; w[2 * n + 1] = p.y; ss += (o[0] * o[0] + o[1] * o[1]) + (o[2] * o[2] + o[3] * o[3]); } }
;                     if (NORMOUT) *(u32x4e*)(xn + off + bj * HALF) = w; }
;                 if (NORMOUT) { ss += __shfl_xor(ss, 16); ss += __shfl_xor(ss, 32); if (fq == 0) ssq[(size_t)row * 16 + u.pn * 4 + wc] = ss; } }
	v_lshl_add_u32 v164, s22, 8, v170
	v_lshl_or_b32 v160, s23, 8, v172
	v_ashrrev_i32_e32 v161, 31, v160
	v_ashrrev_i32_e32 v165, 31, v164
	v_lshl_add_u64 v[162:163], v[160:161], 2, s[56:57]
	v_lshlrev_b64 v[128:129], 12, v[164:165]
	v_lshl_add_u64 v[196:197], v[162:163], 0, v[128:129]
	global_load_dwordx4 v[180:183], v[196:197], off
	global_load_dwordx4 v[184:187], v[196:197], off offset:16
	global_load_dwordx4 v[188:191], v[196:197], off offset:512
	global_load_dwordx4 v[192:195], v[196:197], off offset:528
	v_or_b32_e32 v166, 16, v164
	v_ashrrev_i32_e32 v167, 31, v166
	v_lshlrev_b64 v[128:129], 12, v[166:167]
	v_lshl_add_u64 v[168:169], v[162:163], 0, v[128:129]
	global_load_dwordx4 v[136:139], v[168:169], off offset:16
	global_load_dwordx4 v[140:143], v[168:169], off
	global_load_dwordx4 v[128:131], v[168:169], off offset:528
	global_load_dwordx4 v[132:135], v[168:169], off offset:512
	v_and_b32_e32 v178, 64, v176
	v_xor_b32_e32 v177, 16, v176
	v_add_u32_e32 v178, 64, v178
	v_xor_b32_e32 v179, 32, v176
	v_cmp_lt_i32_e32 vcc, v177, v178
	v_lshlrev_b64 v[198:199], 10, v[164:165]
	v_lshl_add_u64 v[198:199], v[198:199], 0, v[160:161]
	v_cndmask_b32_e32 v177, v176, v177, vcc
	v_cmp_lt_i32_e32 vcc, v179, v178
	v_lshlrev_b32_e32 v178, 2, v177
	v_lshl_add_u64 v[198:199], v[198:199], 1, s[64:65]
	v_cndmask_b32_e32 v179, v176, v179, vcc
	v_lshlrev_b32_e32 v177, 2, v179
	s_lshl_b32 s22, s23, 2
	s_ashr_i32 s23, s22, 31
	s_lshl_b64 s[22:23], s[22:23], 2
	s_add_u32 s22, s50, s22
	s_addc_u32 s23, s51, s23
	s_waitcnt vmcnt(0)
	v_pk_add_f32 v[126:127], v[182:183], v[126:127]
	v_pk_add_f32 v[124:125], v[180:181], v[124:125]
	v_pk_add_f32 v[122:123], v[186:187], v[122:123]
	v_pk_add_f32 v[120:121], v[184:185], v[120:121]
	v_pk_add_f32 v[118:119], v[190:191], v[118:119]
	v_pk_add_f32 v[116:117], v[188:189], v[116:117]
	v_pk_add_f32 v[182:183], v[194:195], v[114:115]
	v_pk_add_f32 v[180:181], v[192:193], v[112:113]
	global_store_dwordx4 v[196:197], v[124:127], off
	v_cvt_pk_bf16_f32 v112, v124, v125
	v_cvt_pk_bf16_f32 v113, v126, v127
	v_mul_f32_e32 v125, v125, v125
	v_mul_f32_e32 v127, v127, v127
	global_store_dwordx4 v[196:197], v[120:123], off offset:16
	v_cvt_pk_bf16_f32 v114, v120, v121
	v_cvt_pk_bf16_f32 v115, v122, v123
	v_mul_f32_e32 v121, v121, v121
	v_mul_f32_e32 v123, v123, v123
	v_mul_f32_e32 v179, v117, v117
	v_mul_f32_e32 v184, v119, v119
	v_fmac_f32_e32 v125, v124, v124
	v_fmac_f32_e32 v127, v126, v126
	v_fmac_f32_e32 v121, v120, v120
	v_fmac_f32_e32 v123, v122, v122
	v_mul_f32_e32 v185, v181, v181
	v_mul_f32_e32 v186, v183, v183
	v_fmac_f32_e32 v179, v116, v116
	v_fmac_f32_e32 v184, v118, v118
	v_add_f32_e32 v120, v125, v127
	v_add_f32_e32 v121, v121, v123
	v_fmac_f32_e32 v185, v180, v180
	v_fmac_f32_e32 v186, v182, v182
	v_add_f32_e32 v122, v179, v184
	v_add_f32_e32 v120, v120, v121
	v_add_f32_e32 v120, v122, v120
	v_add_f32_e32 v121, v185, v186
	v_add_f32_e32 v120, v121, v120
	ds_bpermute_b32 v121, v178, v120
	global_store_dwordx4 v[198:199], v[112:115], off
	global_store_dwordx4 v[196:197], v[116:119], off offset:512
	global_store_dwordx4 v[196:197], v[180:183], off offset:528
	v_cvt_pk_bf16_f32 v114, v116, v117
	v_cvt_pk_bf16_f32 v115, v118, v119
	s_waitcnt lgkmcnt(0)
	v_add_f32_e32 v112, v120, v121
	ds_bpermute_b32 v113, v177, v112
	v_cvt_pk_bf16_f32 v116, v180, v181
	v_cvt_pk_bf16_f32 v117, v182, v183
	global_store_dwordx4 v[198:199], v[114:117], off offset:256
	s_and_saveexec_b64 s[24:25], s[2:3]
	s_cbranch_execz .LBB0_816
	v_lshlrev_b64 v[114:115], 6, v[164:165]
	v_lshl_add_u64 v[114:115], s[22:23], 0, v[114:115]
	s_waitcnt lgkmcnt(0)
	v_add_f32_e32 v112, v112, v113
	global_store_dword v[114:115], v112, off

; #define PG8_STAGE(bufoff, gbase, voff) do { _Pragma("unroll") for (int _i = 0; _i < 2; ++_i) \
;         __builtin_amdgcn_global_load_lds((const unsigned*)((const char*)(gbase) + (voff)[_i]), (PG8_LAS unsigned*)(lds + (bufoff) + ldsw + _i * 8192), 16, 0, 0); } while (0)
; #define PG8_LDA(dst, b, h) do { _Pragma("unroll") for (int m = 0; m < 4; ++m) _Pragma("unroll") for (int k = 0; k < 2; ++k) dst[m][k] = *(const PG8_LAS bf16x8*)(lds + PG8_SA(b, h) + aoff + m * 2048 + k * 1024); } while (0)
; #define PG8_LDB(dst, b, h) do { _Pragma("unroll") for (int n = 0; n < 2; ++n) _Pragma("unroll") for (int k = 0; k < 2; ++k) dst[n][k] = *(const PG8_LAS bf16x8*)(lds + PG8_SB(b, h) + boff + n * 2048 + k * 1024); } while (0)
; #define PG8_MMA(ai, bj, At, Bt) do { __builtin_amdgcn_s_setprio(1); _Pragma("unroll") for (int m = 0; m < 4; ++m) _Pragma("unroll") for (int n = 0; n < 2; ++n) _Pragma("unroll") for (int k = 0; k < 2; ++k) \
;         acc[ai][bj][m][n] = __builtin_amdgcn_mfma_f32_16x16x32_bf16(Bt[n][k], At[m][k], acc[ai][bj][m][n], 0, 0, 0); __builtin_amdgcn_s_setprio(0); } while (0)
; #define PG8_WAIT_V(n) asm volatile("s_waitcnt vmcnt(" #n ")" ::: "memory")
; #define PG8_WAIT_L(n) asm volatile("s_waitcnt lgkmcnt(" #n ")" ::: "memory")
; #define PG8_BAR __builtin_amdgcn_s_barrier()
; #define PG8_SCHED __builtin_amdgcn_sched_barrier(0)
; template <class Epi, class Sched, bool ALIGN_EPI = false, bool SP2 = false>
; __device__ __forceinline__ void gemm_phase(PG8_LAS unsigned char* lds, const Gemm g, const Sched& S, const Epi& E) {
;     ...
;             PG8_LDB(B0, 0, 0); PG8_LDB(B1, 0, 1); PG8_SCHED; PG8_LDA(At, 0, 0); PG8_STAGE(PG8_SA(1, 1), a1 + hstep, voffA);
;             PG8_WAIT_V(8); PG8_WAIT_L(0); PG8_BAR; PG8_MMA(0, 0, At, B0); PG8_MMA(0, 1, At, B1); PG8_BAR; PG8_SCHED;
;             PG8_LDA(At, 0, 1); PG8_STAGE(PG8_SB(0, 0), b2, voffB); PG8_STAGE(PG8_SB(0, 1), b2 + hstep, voffB); PG8_STAGE(PG8_SA(0, 0), a2, voffA);
;             PG8_WAIT_V(8); PG8_WAIT_L(0); PG8_BAR; PG8_MMA(1, 0, At, B0); PG8_MMA(1, 1, At, B1); PG8_BAR; PG8_SCHED;
.LBB0_895:
	ds_read_b128 v[128:131], v183
	ds_read_b128 v[132:135], v183 offset:1024
	ds_read_b128 v[136:139], v183 offset:2048
	ds_read_b128 v[140:143], v183 offset:3072
	ds_read_b128 v[162:165], v184
	ds_read_b128 v[166:169], v184 offset:1024
	ds_read_b128 v[170:173], v184 offset:2048
	ds_read_b128 v[174:177], v184 offset:3072
	s_add_u32 s26, s4, 0xfffc0080
	s_addc_u32 s27, s5, -1
	s_cmp_eq_u32 s67, 12
	s_cselect_b32 s37, s1, s27
	s_cselect_b32 s36, s21, s26
	s_cselect_b32 s27, s19, s66
	s_cselect_b32 s26, s60, s61
	v_lshl_add_u64 v[222:223], s[4:5], 0, v[154:155]
	s_add_i32 m0, s41, 0xc000
	ds_read_b128 v[190:193], v185
	ds_read_b128 v[194:197], v185 offset:1024
	ds_read_b128 v[198:201], v185 offset:2048
	ds_read_b128 v[202:205], v185 offset:3072
	ds_read_b128 v[206:209], v185 offset:4096
	ds_read_b128 v[210:213], v185 offset:5120
	ds_read_b128 v[214:217], v185 offset:6144
	ds_read_b128 v[218:221], v185 offset:7168
	global_load_lds_dwordx4 v[222:223], off
	v_lshl_add_u64 v[222:223], s[4:5], 0, v[156:157]
	s_add_i32 m0, s41, 0xe000
	s_nop 0
	global_load_lds_dwordx4 v[222:223], off
	s_waitcnt vmcnt(8)
	s_waitcnt lgkmcnt(0)
	s_barrier
	s_setprio 1
	s_waitcnt lgkmcnt(0)
	v_mfma_f32_16x16x32_bf16 v[124:127], v[128:131], v[190:193], v[124:127]
	v_mfma_f32_16x16x32_bf16 v[120:123], v[136:139], v[190:193], v[120:123]
	v_mfma_f32_16x16x32_bf16 v[108:111], v[128:131], v[198:201], v[108:111]
	v_mfma_f32_16x16x32_bf16 v[104:107], v[136:139], v[198:201], v[104:107]
	v_mfma_f32_16x16x32_bf16 v[92:95], v[128:131], v[206:209], v[92:95]
	v_mfma_f32_16x16x32_bf16 v[88:91], v[136:139], v[206:209], v[88:91]
	v_mfma_f32_16x16x32_bf16 v[76:79], v[128:131], v[214:217], v[76:79]
	v_mfma_f32_16x16x32_bf16 v[72:75], v[136:139], v[214:217], v[72:75]
	v_mfma_f32_16x16x32_bf16 v[124:127], v[132:135], v[194:197], v[124:127]
	v_mfma_f32_16x16x32_bf16 v[120:123], v[140:143], v[194:197], v[120:123]
	v_mfma_f32_16x16x32_bf16 v[108:111], v[132:135], v[202:205], v[108:111]
	v_mfma_f32_16x16x32_bf16 v[104:107], v[140:143], v[202:205], v[104:107]
	v_mfma_f32_16x16x32_bf16 v[92:95], v[132:135], v[210:213], v[92:95]
	v_mfma_f32_16x16x32_bf16 v[88:91], v[140:143], v[210:213], v[88:91]
	v_mfma_f32_16x16x32_bf16 v[76:79], v[132:135], v[218:221], v[76:79]
	v_mfma_f32_16x16x32_bf16 v[72:75], v[140:143], v[218:221], v[72:75]
	s_setprio 0
	s_setprio 1
	v_mfma_f32_16x16x32_bf16 v[116:119], v[162:165], v[190:193], v[116:119]
	v_mfma_f32_16x16x32_bf16 v[112:115], v[170:173], v[190:193], v[112:115]
	v_mfma_f32_16x16x32_bf16 v[100:103], v[162:165], v[198:201], v[100:103]
	v_mfma_f32_16x16x32_bf16 v[96:99], v[170:173], v[198:201], v[96:99]
	v_mfma_f32_16x16x32_bf16 v[84:87], v[162:165], v[206:209], v[84:87]
	v_mfma_f32_16x16x32_bf16 v[80:83], v[170:173], v[206:209], v[80:83]
	v_mfma_f32_16x16x32_bf16 v[68:71], v[162:165], v[214:217], v[68:71]
	v_mfma_f32_16x16x32_bf16 v[64:67], v[170:173], v[214:217], v[64:67]
	v_mfma_f32_16x16x32_bf16 v[116:119], v[166:169], v[194:197], v[116:119]
	v_mfma_f32_16x16x32_bf16 v[112:115], v[174:177], v[194:197], v[112:115]
	v_mfma_f32_16x16x32_bf16 v[100:103], v[166:169], v[202:205], v[100:103]
	v_mfma_f32_16x16x32_bf16 v[96:99], v[174:177], v[202:205], v[96:99]
	v_mfma_f32_16x16x32_bf16 v[84:87], v[166:169], v[210:213], v[84:87]
	v_mfma_f32_16x16x32_bf16 v[80:83], v[174:177], v[210:213], v[80:83]
	v_mfma_f32_16x16x32_bf16 v[68:71], v[166:169], v[218:221], v[68:71]
	v_mfma_f32_16x16x32_bf16 v[64:67], v[174:177], v[218:221], v[64:67]
	s_setprio 0
	s_barrier
	s_sleep 1
	s_add_i32 s68, s49, s38
	v_lshl_add_u64 v[222:223], s[26:27], 0, v[148:149]
	s_mov_b32 m0, s68
	ds_read_b128 v[190:193], v185 offset:16384
	ds_read_b128 v[194:197], v185 offset:17408
	ds_read_b128 v[198:201], v185 offset:18432
	ds_read_b128 v[202:205], v185 offset:19456
	ds_read_b128 v[206:209], v185 offset:20480
	ds_read_b128 v[210:213], v185 offset:21504
	ds_read_b128 v[214:217], v185 offset:22528
	ds_read_b128 v[218:221], v185 offset:23552
	global_load_lds_dwordx4 v[222:223], off
	s_add_i32 m0, s68, 0x2000
	s_add_u32 s68, s26, 0x40000
	v_lshl_add_u64 v[224:225], s[26:27], 0, v[144:145]
	s_addc_u32 s69, s27, 0
	s_add_i32 s70, s50, s38
	global_load_lds_dwordx4 v[224:225], off
	v_lshl_add_u64 v[226:227], s[68:69], 0, v[148:149]
	s_mov_b32 m0, s70
	v_lshl_add_u64 v[228:229], s[36:37], 0, v[146:147]
	global_load_lds_dwordx4 v[226:227], off
	v_lshl_add_u64 v[226:227], s[68:69], 0, v[144:145]
	s_add_i32 m0, s70, 0x2000
	s_nop 0
	global_load_lds_dwordx4 v[226:227], off
	v_lshl_add_u64 v[226:227], s[36:37], 0, v[150:151]
	s_mov_b32 m0, s41
	s_nop 0
	global_load_lds_dwordx4 v[226:227], off
	s_mov_b32 m0, s42
	s_nop 0
	global_load_lds_dwordx4 v[228:229], off
	s_waitcnt vmcnt(8)
	s_waitcnt lgkmcnt(0)
	s_barrier
; #define PG8_STAGE(bufoff, gbase, voff) do { _Pragma("unroll") for (int _i = 0; _i < 2; ++_i) \
;         __builtin_amdgcn_global_load_lds((const unsigned*)((const char*)(gbase) + (voff)[_i]), (PG8_LAS unsigned*)(lds + (bufoff) + ldsw + _i * 8192), 16, 0, 0); } while (0)
; #define PG8_LDA(dst, b, h) do { _Pragma("unroll") for (int m = 0; m < 4; ++m) _Pragma("unroll") for (int k = 0; k < 2; ++k) dst[m][k] = *(const PG8_LAS bf16x8*)(lds + PG8_SA(b, h) + aoff + m * 2048 + k * 1024); } while (0)
; #define PG8_LDB(dst, b, h) do { _Pragma("unroll") for (int n = 0; n < 2; ++n) _Pragma("unroll") for (int k = 0; k < 2; ++k) dst[n][k] = *(const PG8_LAS bf16x8*)(lds + PG8_SB(b, h) + boff + n * 2048 + k * 1024); } while (0)
; #define PG8_MMA(ai, bj, At, Bt) do { __builtin_amdgcn_s_setprio(1); _Pragma("unroll") for (int m = 0; m < 4; ++m) _Pragma("unroll") for (int n = 0; n < 2; ++n) _Pragma("unroll") for (int k = 0; k < 2; ++k) \
;         acc[ai][bj][m][n] = __builtin_amdgcn_mfma_f32_16x16x32_bf16(Bt[n][k], At[m][k], acc[ai][bj][m][n], 0, 0, 0); __builtin_amdgcn_s_setprio(0); } while (0)
; #define PG8_WAIT_V(n) asm volatile("s_waitcnt vmcnt(" #n ")" ::: "memory")
; #define PG8_WAIT_L(n) asm volatile("s_waitcnt lgkmcnt(" #n ")" ::: "memory")
; #define PG8_BAR __builtin_amdgcn_s_barrier()
; #define PG8_SCHED __builtin_amdgcn_sched_barrier(0)
; template <class Epi, class Sched, bool ALIGN_EPI = false, bool SP2 = false>
; __device__ __forceinline__ void gemm_phase(PG8_LAS unsigned char* lds, const Gemm g, const Sched& S, const Epi& E) {
;     ...
;             PG8_WAIT_V(8); PG8_WAIT_L(0); PG8_BAR; PG8_MMA(1, 0, At, B0); PG8_MMA(1, 1, At, B1); PG8_BAR; PG8_SCHED;
;             PG8_LDB(B0, 1, 0); PG8_LDB(B1, 1, 1); PG8_SCHED; PG8_LDA(At, 1, 0); PG8_STAGE(PG8_SA(0, 1), a2 + hstep, voffA);
;             PG8_WAIT_V(8); PG8_WAIT_L(0); PG8_BAR; PG8_MMA(0, 0, At, B0); PG8_MMA(0, 1, At, B1); PG8_BAR; PG8_SCHED;
;             PG8_LDA(At, 1, 1); PG8_STAGE(PG8_SB(1, 0), b3, voffB); PG8_STAGE(PG8_SB(1, 1), b3 + hstep, voffB); PG8_STAGE(PG8_SA(1, 0), a3, voffA);
	s_setprio 1
	s_waitcnt lgkmcnt(0)
	v_mfma_f32_16x16x32_bf16 v[60:63], v[128:131], v[190:193], v[60:63]
	v_mfma_f32_16x16x32_bf16 v[56:59], v[136:139], v[190:193], v[56:59]
	v_mfma_f32_16x16x32_bf16 v[44:47], v[128:131], v[198:201], v[44:47]
	v_mfma_f32_16x16x32_bf16 v[40:43], v[136:139], v[198:201], v[40:43]
	v_mfma_f32_16x16x32_bf16 v[28:31], v[128:131], v[206:209], v[28:31]
	v_mfma_f32_16x16x32_bf16 v[24:27], v[136:139], v[206:209], v[24:27]
	v_mfma_f32_16x16x32_bf16 v[12:15], v[128:131], v[214:217], v[12:15]
	v_mfma_f32_16x16x32_bf16 v[8:11], v[136:139], v[214:217], v[8:11]
	v_mfma_f32_16x16x32_bf16 v[60:63], v[132:135], v[194:197], v[60:63]
	v_mfma_f32_16x16x32_bf16 v[56:59], v[140:143], v[194:197], v[56:59]
	v_mfma_f32_16x16x32_bf16 v[44:47], v[132:135], v[202:205], v[44:47]
	v_mfma_f32_16x16x32_bf16 v[40:43], v[140:143], v[202:205], v[40:43]
	v_mfma_f32_16x16x32_bf16 v[28:31], v[132:135], v[210:213], v[28:31]
	v_mfma_f32_16x16x32_bf16 v[24:27], v[140:143], v[210:213], v[24:27]
	v_mfma_f32_16x16x32_bf16 v[12:15], v[132:135], v[218:221], v[12:15]
	v_mfma_f32_16x16x32_bf16 v[8:11], v[140:143], v[218:221], v[8:11]
	s_setprio 0
	s_setprio 1
	v_mfma_f32_16x16x32_bf16 v[52:55], v[162:165], v[190:193], v[52:55]
	v_mfma_f32_16x16x32_bf16 v[48:51], v[170:173], v[190:193], v[48:51]
	v_mfma_f32_16x16x32_bf16 v[36:39], v[162:165], v[198:201], v[36:39]
	v_mfma_f32_16x16x32_bf16 v[32:35], v[170:173], v[198:201], v[32:35]
	v_mfma_f32_16x16x32_bf16 v[20:23], v[162:165], v[206:209], v[20:23]
	v_mfma_f32_16x16x32_bf16 v[16:19], v[170:173], v[206:209], v[16:19]
	v_mfma_f32_16x16x32_bf16 v[4:7], v[162:165], v[214:217], v[4:7]
	v_mfma_f32_16x16x32_bf16 v[0:3], v[170:173], v[214:217], v[0:3]
	v_mfma_f32_16x16x32_bf16 v[52:55], v[166:169], v[194:197], v[52:55]
	v_mfma_f32_16x16x32_bf16 v[48:51], v[174:177], v[194:197], v[48:51]
	v_mfma_f32_16x16x32_bf16 v[36:39], v[166:169], v[202:205], v[36:39]
	v_mfma_f32_16x16x32_bf16 v[32:35], v[174:177], v[202:205], v[32:35]
	v_mfma_f32_16x16x32_bf16 v[20:23], v[166:169], v[210:213], v[20:23]
	v_mfma_f32_16x16x32_bf16 v[16:19], v[174:177], v[210:213], v[16:19]
	v_mfma_f32_16x16x32_bf16 v[4:7], v[166:169], v[218:221], v[4:7]
	v_mfma_f32_16x16x32_bf16 v[0:3], v[174:177], v[218:221], v[0:3]
	s_setprio 0
	s_barrier
	s_sleep 1
	s_add_i32 s68, 0, 0x18000
	s_add_i32 s69, 0, 0x1c000
	v_add_u32_e32 v140, s68, v181
	v_add_u32_e32 v174, s69, v181
	ds_read_b128 v[128:131], v140
	ds_read_b128 v[132:135], v140 offset:1024
	ds_read_b128 v[136:139], v140 offset:2048
	ds_read_b128 v[140:143], v140 offset:3072
	ds_read_b128 v[162:165], v174
	ds_read_b128 v[166:169], v174 offset:1024
	ds_read_b128 v[170:173], v174 offset:2048
	ds_read_b128 v[174:177], v174 offset:3072
	s_add_u32 s36, s36, 0x40000
	s_addc_u32 s37, s37, 0
	s_mov_b32 m0, s43
	v_lshl_add_u64 v[232:233], s[36:37], 0, v[150:151]
	ds_read_b128 v[190:193], v185 offset:32768
	ds_read_b128 v[194:197], v185 offset:33792
	ds_read_b128 v[198:201], v185 offset:34816
	ds_read_b128 v[202:205], v185 offset:35840
	ds_read_b128 v[206:209], v185 offset:36864
	ds_read_b128 v[210:213], v185 offset:37888
	ds_read_b128 v[214:217], v185 offset:38912
	ds_read_b128 v[218:221], v185 offset:39936
	global_load_lds_dwordx4 v[232:233], off
	v_lshl_add_u64 v[232:233], s[36:37], 0, v[146:147]
	s_mov_b32 m0, s44
	s_nop 0
	global_load_lds_dwordx4 v[232:233], off
	s_waitcnt vmcnt(8)
	s_waitcnt lgkmcnt(0)
	s_barrier
	s_setprio 1
	s_waitcnt lgkmcnt(0)
	v_mfma_f32_16x16x32_bf16 v[124:127], v[128:131], v[190:193], v[124:127]
	v_mfma_f32_16x16x32_bf16 v[120:123], v[136:139], v[190:193], v[120:123]
	v_mfma_f32_16x16x32_bf16 v[108:111], v[128:131], v[198:201], v[108:111]
	v_mfma_f32_16x16x32_bf16 v[104:107], v[136:139], v[198:201], v[104:107]
	v_mfma_f32_16x16x32_bf16 v[92:95], v[128:131], v[206:209], v[92:95]
	v_mfma_f32_16x16x32_bf16 v[88:91], v[136:139], v[206:209], v[88:91]
	v_mfma_f32_16x16x32_bf16 v[76:79], v[128:131], v[214:217], v[76:79]
	v_mfma_f32_16x16x32_bf16 v[72:75], v[136:139], v[214:217], v[72:75]
	v_mfma_f32_16x16x32_bf16 v[124:127], v[132:135], v[194:197], v[124:127]
	v_mfma_f32_16x16x32_bf16 v[120:123], v[140:143], v[194:197], v[120:123]
	v_mfma_f32_16x16x32_bf16 v[108:111], v[132:135], v[202:205], v[108:111]
	v_mfma_f32_16x16x32_bf16 v[104:107], v[140:143], v[202:205], v[104:107]
	v_mfma_f32_16x16x32_bf16 v[92:95], v[132:135], v[210:213], v[92:95]
	v_mfma_f32_16x16x32_bf16 v[88:91], v[140:143], v[210:213], v[88:91]
	v_mfma_f32_16x16x32_bf16 v[76:79], v[132:135], v[218:221], v[76:79]
	v_mfma_f32_16x16x32_bf16 v[72:75], v[140:143], v[218:221], v[72:75]
	s_setprio 0
	s_setprio 1
	v_mfma_f32_16x16x32_bf16 v[116:119], v[162:165], v[190:193], v[116:119]
	v_mfma_f32_16x16x32_bf16 v[112:115], v[170:173], v[190:193], v[112:115]
	v_mfma_f32_16x16x32_bf16 v[100:103], v[162:165], v[198:201], v[100:103]
	v_mfma_f32_16x16x32_bf16 v[96:99], v[170:173], v[198:201], v[96:99]
	v_mfma_f32_16x16x32_bf16 v[84:87], v[162:165], v[206:209], v[84:87]
	v_mfma_f32_16x16x32_bf16 v[80:83], v[170:173], v[206:209], v[80:83]
	v_mfma_f32_16x16x32_bf16 v[68:71], v[162:165], v[214:217], v[68:71]
	v_mfma_f32_16x16x32_bf16 v[64:67], v[170:173], v[214:217], v[64:67]
	v_mfma_f32_16x16x32_bf16 v[116:119], v[166:169], v[194:197], v[116:119]
	v_mfma_f32_16x16x32_bf16 v[112:115], v[174:177], v[194:197], v[112:115]
	v_mfma_f32_16x16x32_bf16 v[100:103], v[166:169], v[202:205], v[100:103]
	v_mfma_f32_16x16x32_bf16 v[96:99], v[174:177], v[202:205], v[96:99]
	v_mfma_f32_16x16x32_bf16 v[84:87], v[166:169], v[210:213], v[84:87]
	v_mfma_f32_16x16x32_bf16 v[80:83], v[174:177], v[210:213], v[80:83]
	v_mfma_f32_16x16x32_bf16 v[68:71], v[166:169], v[218:221], v[68:71]
	v_mfma_f32_16x16x32_bf16 v[64:67], v[174:177], v[218:221], v[64:67]
	s_setprio 0
	s_barrier
; #define PG8_STAGE(bufoff, gbase, voff) do { _Pragma("unroll") for (int _i = 0; _i < 2; ++_i) \
;         __builtin_amdgcn_global_load_lds((const unsigned*)((const char*)(gbase) + (voff)[_i]), (PG8_LAS unsigned*)(lds + (bufoff) + ldsw + _i * 8192), 16, 0, 0); } while (0)
; #define PG8_LDA(dst, b, h) do { _Pragma("unroll") for (int m = 0; m < 4; ++m) _Pragma("unroll") for (int k = 0; k < 2; ++k) dst[m][k] = *(const PG8_LAS bf16x8*)(lds + PG8_SA(b, h) + aoff + m * 2048 + k * 1024); } while (0)
; #define PG8_MMA(ai, bj, At, Bt) do { __builtin_amdgcn_s_setprio(1); _Pragma("unroll") for (int m = 0; m < 4; ++m) _Pragma("unroll") for (int n = 0; n < 2; ++n) _Pragma("unroll") for (int k = 0; k < 2; ++k) \
;         acc[ai][bj][m][n] = __builtin_amdgcn_mfma_f32_16x16x32_bf16(Bt[n][k], At[m][k], acc[ai][bj][m][n], 0, 0, 0); __builtin_amdgcn_s_setprio(0); } while (0)
; #define PG8_WAIT_V(n) asm volatile("s_waitcnt vmcnt(" #n ")" ::: "memory")
; #define PG8_WAIT_L(n) asm volatile("s_waitcnt lgkmcnt(" #n ")" ::: "memory")
; #define PG8_BAR __builtin_amdgcn_s_barrier()
; #define PG8_SCHED __builtin_amdgcn_sched_barrier(0)
; template <class Epi, class Sched, bool ALIGN_EPI = false, bool SP2 = false>
; __device__ __forceinline__ void gemm_phase(PG8_LAS unsigned char* lds, const Gemm g, const Sched& S, const Epi& E) {
;     ...
;             PG8_WAIT_V(8); PG8_WAIT_L(0); PG8_BAR; PG8_MMA(0, 0, At, B0); PG8_MMA(0, 1, At, B1); PG8_BAR; PG8_SCHED;
;             PG8_LDA(At, 1, 1); PG8_STAGE(PG8_SB(1, 0), b3, voffB); PG8_STAGE(PG8_SB(1, 1), b3 + hstep, voffB); PG8_STAGE(PG8_SA(1, 0), a3, voffA);
;             PG8_WAIT_V(8); PG8_WAIT_L(0); PG8_BAR; PG8_MMA(1, 0, At, B0); PG8_MMA(1, 1, At, B1); PG8_BAR; PG8_SCHED;
;     ...
;         if constexpr (ALIGN_EPI) { if (wr == 0) PG8_BAR; }
	s_sleep 1
	s_add_i32 s36, s68, s38
	v_lshl_add_u64 v[222:223], v[222:223], 0, s[12:13]
	s_mov_b32 m0, s36
	ds_read_b128 v[190:193], v185 offset:49152
	ds_read_b128 v[194:197], v185 offset:50176
	ds_read_b128 v[198:201], v185 offset:51200
	ds_read_b128 v[202:205], v185 offset:52224
	ds_read_b128 v[206:209], v185 offset:53248
	ds_read_b128 v[210:213], v185 offset:54272
	ds_read_b128 v[214:217], v185 offset:55296
	ds_read_b128 v[218:221], v185 offset:56320
	global_load_lds_dwordx4 v[222:223], off
	s_add_i32 m0, s36, 0x2000
	s_add_u32 s26, s26, 0x40080
	v_lshl_add_u64 v[222:223], v[224:225], 0, s[12:13]
	s_addc_u32 s27, s27, 0
	s_add_i32 s36, s69, s38
	global_load_lds_dwordx4 v[222:223], off
	v_lshl_add_u64 v[222:223], s[26:27], 0, v[148:149]
	s_mov_b32 m0, s36
	s_nop 0
	global_load_lds_dwordx4 v[222:223], off
	v_lshl_add_u64 v[222:223], s[26:27], 0, v[144:145]
	s_add_i32 m0, s36, 0x2000
	s_nop 0
	global_load_lds_dwordx4 v[222:223], off
	v_lshl_add_u64 v[222:223], v[226:227], 0, s[12:13]
	s_mov_b32 m0, s46
	s_nop 0
	global_load_lds_dwordx4 v[222:223], off
	v_lshl_add_u64 v[222:223], v[228:229], 0, s[12:13]
	s_mov_b32 m0, s47
	s_nop 0
	global_load_lds_dwordx4 v[222:223], off
	s_waitcnt vmcnt(8)
	s_waitcnt lgkmcnt(0)
	s_barrier
	s_setprio 1
	s_waitcnt lgkmcnt(0)
	v_mfma_f32_16x16x32_bf16 v[60:63], v[128:131], v[190:193], v[60:63]
	v_mfma_f32_16x16x32_bf16 v[56:59], v[136:139], v[190:193], v[56:59]
	v_mfma_f32_16x16x32_bf16 v[44:47], v[128:131], v[198:201], v[44:47]
	v_mfma_f32_16x16x32_bf16 v[40:43], v[136:139], v[198:201], v[40:43]
	v_mfma_f32_16x16x32_bf16 v[28:31], v[128:131], v[206:209], v[28:31]
	v_mfma_f32_16x16x32_bf16 v[24:27], v[136:139], v[206:209], v[24:27]
	v_mfma_f32_16x16x32_bf16 v[12:15], v[128:131], v[214:217], v[12:15]
	v_mfma_f32_16x16x32_bf16 v[8:11], v[136:139], v[214:217], v[8:11]
	v_mfma_f32_16x16x32_bf16 v[60:63], v[132:135], v[194:197], v[60:63]
	v_mfma_f32_16x16x32_bf16 v[56:59], v[140:143], v[194:197], v[56:59]
	v_mfma_f32_16x16x32_bf16 v[44:47], v[132:135], v[202:205], v[44:47]
	v_mfma_f32_16x16x32_bf16 v[40:43], v[140:143], v[202:205], v[40:43]
	v_mfma_f32_16x16x32_bf16 v[28:31], v[132:135], v[210:213], v[28:31]
	v_mfma_f32_16x16x32_bf16 v[24:27], v[140:143], v[210:213], v[24:27]
	v_mfma_f32_16x16x32_bf16 v[12:15], v[132:135], v[218:221], v[12:15]
	v_mfma_f32_16x16x32_bf16 v[8:11], v[140:143], v[218:221], v[8:11]
	s_setprio 0
	s_setprio 1
	v_mfma_f32_16x16x32_bf16 v[52:55], v[162:165], v[190:193], v[52:55]
	v_mfma_f32_16x16x32_bf16 v[48:51], v[170:173], v[190:193], v[48:51]
	v_mfma_f32_16x16x32_bf16 v[36:39], v[162:165], v[198:201], v[36:39]
	v_mfma_f32_16x16x32_bf16 v[32:35], v[170:173], v[198:201], v[32:35]
	v_mfma_f32_16x16x32_bf16 v[20:23], v[162:165], v[206:209], v[20:23]
	v_mfma_f32_16x16x32_bf16 v[16:19], v[170:173], v[206:209], v[16:19]
	v_mfma_f32_16x16x32_bf16 v[4:7], v[162:165], v[214:217], v[4:7]
	v_mfma_f32_16x16x32_bf16 v[0:3], v[170:173], v[214:217], v[0:3]
	v_mfma_f32_16x16x32_bf16 v[52:55], v[166:169], v[194:197], v[52:55]
	v_mfma_f32_16x16x32_bf16 v[48:51], v[174:177], v[194:197], v[48:51]
	v_mfma_f32_16x16x32_bf16 v[36:39], v[166:169], v[202:205], v[36:39]
	v_mfma_f32_16x16x32_bf16 v[32:35], v[174:177], v[202:205], v[32:35]
	v_mfma_f32_16x16x32_bf16 v[20:23], v[166:169], v[210:213], v[20:23]
	v_mfma_f32_16x16x32_bf16 v[16:19], v[174:177], v[210:213], v[16:19]
	v_mfma_f32_16x16x32_bf16 v[4:7], v[166:169], v[218:221], v[4:7]
	v_mfma_f32_16x16x32_bf16 v[0:3], v[174:177], v[218:221], v[0:3]
	s_setprio 0
	s_barrier
	s_sleep 1
	s_add_i32 s67, s67, 2
	s_add_u32 s4, s4, 0x100
	s_addc_u32 s5, s5, 0
	s_add_u32 s61, s61, 0x100
	s_addc_u32 s66, s66, 0
	s_cmp_gt_u32 s67, 13
	s_cbranch_scc0 .LBB0_895
	s_and_b64 vcc, exec, s[14:15]
	s_cbranch_vccz .LBB0_898
	s_barrier

; #define PG8_STAGE(bufoff, gbase, voff) do { _Pragma("unroll") for (int _i = 0; _i < 2; ++_i) \
;         __builtin_amdgcn_global_load_lds((const unsigned*)((const char*)(gbase) + (voff)[_i]), (PG8_LAS unsigned*)(lds + (bufoff) + ldsw + _i * 8192), 16, 0, 0); } while (0)
; #define PG8_LDA(dst, b, h) do { _Pragma("unroll") for (int m = 0; m < 4; ++m) _Pragma("unroll") for (int k = 0; k < 2; ++k) dst[m][k] = *(const PG8_LAS bf16x8*)(lds + PG8_SA(b, h) + aoff + m * 2048 + k * 1024); } while (0)
; #define PG8_LDB(dst, b, h) do { _Pragma("unroll") for (int n = 0; n < 2; ++n) _Pragma("unroll") for (int k = 0; k < 2; ++k) dst[n][k] = *(const PG8_LAS bf16x8*)(lds + PG8_SB(b, h) + boff + n * 2048 + k * 1024); } while (0)
; #define PG8_MMA(ai, bj, At, Bt) do { __builtin_amdgcn_s_setprio(1); _Pragma("unroll") for (int m = 0; m < 4; ++m) _Pragma("unroll") for (int n = 0; n < 2; ++n) _Pragma("unroll") for (int k = 0; k < 2; ++k) \
;         acc[ai][bj][m][n] = __builtin_amdgcn_mfma_f32_16x16x32_bf16(Bt[n][k], At[m][k], acc[ai][bj][m][n], 0, 0, 0); __builtin_amdgcn_s_setprio(0); } while (0)
; #define PG8_WAIT_V(n) asm volatile("s_waitcnt vmcnt(" #n ")" ::: "memory")
; #define PG8_WAIT_L(n) asm volatile("s_waitcnt lgkmcnt(" #n ")" ::: "memory")
; #define PG8_BAR __builtin_amdgcn_s_barrier()
; #define PG8_SCHED __builtin_amdgcn_sched_barrier(0)
; template <class Epi, class Sched, bool ALIGN_EPI = false, bool SP2 = false>
; __device__ __forceinline__ void gemm_phase(PG8_LAS unsigned char* lds, const Gemm g, const Sched& S, const Epi& E) {
;     ...
;             PG8_LDB(B0, 0, 0); PG8_LDB(B1, 0, 1); PG8_SCHED; PG8_LDA(At, 0, 0); PG8_STAGE(PG8_SA(1, 1), a1 + hstep, voffA);
;             PG8_WAIT_V(8); PG8_WAIT_L(0); PG8_BAR; PG8_MMA(0, 0, At, B0); PG8_MMA(0, 1, At, B1); PG8_BAR; PG8_SCHED;
;             PG8_LDA(At, 0, 1); PG8_STAGE(PG8_SB(0, 0), b2, voffB); PG8_STAGE(PG8_SB(0, 1), b2 + hstep, voffB); PG8_STAGE(PG8_SA(0, 0), a2, voffA);
;             PG8_WAIT_V(8); PG8_WAIT_L(0); PG8_BAR; PG8_MMA(1, 0, At, B0); PG8_MMA(1, 1, At, B1); PG8_BAR; PG8_SCHED;
.LBB0_970:
	ds_read_b128 v[144:147], v154
	ds_read_b128 v[162:165], v154 offset:1024
	ds_read_b128 v[166:169], v154 offset:2048
	ds_read_b128 v[170:173], v154 offset:3072
	ds_read_b128 v[174:177], v155
	ds_read_b128 v[178:181], v155 offset:1024
	ds_read_b128 v[182:185], v155 offset:2048
	ds_read_b128 v[186:189], v155 offset:3072
	s_add_u32 s44, s4, 0xfff50080
	s_addc_u32 s45, s5, -1
	s_cmp_eq_u32 s73, 40
	s_cselect_b32 s47, s39, s45
	s_cselect_b32 s46, s38, s44
	s_cselect_b32 s45, s41, s72
	s_cselect_b32 s44, s40, s43
	v_lshl_add_u64 v[148:149], s[4:5], 0, v[136:137]
	s_add_i32 m0, s48, 0xc000
	ds_read_b128 v[190:193], v156
	ds_read_b128 v[194:197], v156 offset:1024
	ds_read_b128 v[198:201], v156 offset:2048
	ds_read_b128 v[202:205], v156 offset:3072
	ds_read_b128 v[206:209], v156 offset:4096
	ds_read_b128 v[210:213], v156 offset:5120
	ds_read_b128 v[214:217], v156 offset:6144
	ds_read_b128 v[218:221], v156 offset:7168
	global_load_lds_dwordx4 v[148:149], off
	v_lshl_add_u64 v[148:149], s[4:5], 0, v[138:139]
	s_add_i32 m0, s48, 0xe000
	s_nop 0
	global_load_lds_dwordx4 v[148:149], off
	s_waitcnt vmcnt(8)
	s_waitcnt lgkmcnt(0)
	s_barrier
	s_setprio 1
	s_waitcnt lgkmcnt(0)
	v_mfma_f32_16x16x32_bf16 v[124:127], v[144:147], v[190:193], v[124:127]
	v_mfma_f32_16x16x32_bf16 v[120:123], v[166:169], v[190:193], v[120:123]
	v_mfma_f32_16x16x32_bf16 v[104:107], v[144:147], v[198:201], v[104:107]
	v_mfma_f32_16x16x32_bf16 v[108:111], v[166:169], v[198:201], v[108:111]
	v_mfma_f32_16x16x32_bf16 v[88:91], v[144:147], v[206:209], v[88:91]
	v_mfma_f32_16x16x32_bf16 v[92:95], v[166:169], v[206:209], v[92:95]
	v_mfma_f32_16x16x32_bf16 v[72:75], v[144:147], v[214:217], v[72:75]
	v_mfma_f32_16x16x32_bf16 v[76:79], v[166:169], v[214:217], v[76:79]
	v_mfma_f32_16x16x32_bf16 v[124:127], v[162:165], v[194:197], v[124:127]
	v_mfma_f32_16x16x32_bf16 v[120:123], v[170:173], v[194:197], v[120:123]
	v_mfma_f32_16x16x32_bf16 v[104:107], v[162:165], v[202:205], v[104:107]
	v_mfma_f32_16x16x32_bf16 v[108:111], v[170:173], v[202:205], v[108:111]
	v_mfma_f32_16x16x32_bf16 v[88:91], v[162:165], v[210:213], v[88:91]
	v_mfma_f32_16x16x32_bf16 v[92:95], v[170:173], v[210:213], v[92:95]
	v_mfma_f32_16x16x32_bf16 v[72:75], v[162:165], v[218:221], v[72:75]
	v_mfma_f32_16x16x32_bf16 v[76:79], v[170:173], v[218:221], v[76:79]
	s_setprio 0
	s_setprio 1
	v_mfma_f32_16x16x32_bf16 v[116:119], v[174:177], v[190:193], v[116:119]
	v_mfma_f32_16x16x32_bf16 v[112:115], v[182:185], v[190:193], v[112:115]
	v_mfma_f32_16x16x32_bf16 v[100:103], v[174:177], v[198:201], v[100:103]
	v_mfma_f32_16x16x32_bf16 v[96:99], v[182:185], v[198:201], v[96:99]
	v_mfma_f32_16x16x32_bf16 v[84:87], v[174:177], v[206:209], v[84:87]
	v_mfma_f32_16x16x32_bf16 v[80:83], v[182:185], v[206:209], v[80:83]
	v_mfma_f32_16x16x32_bf16 v[68:71], v[174:177], v[214:217], v[68:71]
	v_mfma_f32_16x16x32_bf16 v[64:67], v[182:185], v[214:217], v[64:67]
	v_mfma_f32_16x16x32_bf16 v[116:119], v[178:181], v[194:197], v[116:119]
	v_mfma_f32_16x16x32_bf16 v[112:115], v[186:189], v[194:197], v[112:115]
	v_mfma_f32_16x16x32_bf16 v[100:103], v[178:181], v[202:205], v[100:103]
	v_mfma_f32_16x16x32_bf16 v[96:99], v[186:189], v[202:205], v[96:99]
	v_mfma_f32_16x16x32_bf16 v[84:87], v[178:181], v[210:213], v[84:87]
	v_mfma_f32_16x16x32_bf16 v[80:83], v[186:189], v[210:213], v[80:83]
	v_mfma_f32_16x16x32_bf16 v[68:71], v[178:181], v[218:221], v[68:71]
	v_mfma_f32_16x16x32_bf16 v[64:67], v[186:189], v[218:221], v[64:67]
	s_setprio 0
	s_barrier
	s_sleep 1
	s_add_i32 s74, s66, s33
	v_lshl_add_u64 v[148:149], s[44:45], 0, v[130:131]
	s_mov_b32 m0, s74
	ds_read_b128 v[190:193], v156 offset:16384
	ds_read_b128 v[194:197], v156 offset:17408
	ds_read_b128 v[198:201], v156 offset:18432
	ds_read_b128 v[202:205], v156 offset:19456
	ds_read_b128 v[206:209], v156 offset:20480
	ds_read_b128 v[210:213], v156 offset:21504
	ds_read_b128 v[214:217], v156 offset:22528
	ds_read_b128 v[218:221], v156 offset:23552
	global_load_lds_dwordx4 v[148:149], off
	s_add_i32 m0, s74, 0x2000
	s_add_u32 s74, s44, 0xb0000
	v_lshl_add_u64 v[222:223], s[44:45], 0, v[134:135]
	s_addc_u32 s75, s45, 0
	s_add_i32 s76, s67, s33
	global_load_lds_dwordx4 v[222:223], off
	v_lshl_add_u64 v[224:225], s[74:75], 0, v[130:131]
	s_mov_b32 m0, s76
	v_lshl_add_u64 v[226:227], s[46:47], 0, v[132:133]
	global_load_lds_dwordx4 v[224:225], off
	v_lshl_add_u64 v[224:225], s[74:75], 0, v[134:135]
	s_add_i32 m0, s76, 0x2000
	s_nop 0
	global_load_lds_dwordx4 v[224:225], off
	v_lshl_add_u64 v[224:225], s[46:47], 0, v[128:129]
	s_mov_b32 m0, s48
	s_nop 0
	global_load_lds_dwordx4 v[224:225], off
	s_mov_b32 m0, s49
	s_nop 0
	global_load_lds_dwordx4 v[226:227], off
	s_waitcnt vmcnt(8)
	s_waitcnt lgkmcnt(0)
	s_barrier
; #define PG8_STAGE(bufoff, gbase, voff) do { _Pragma("unroll") for (int _i = 0; _i < 2; ++_i) \
;         __builtin_amdgcn_global_load_lds((const unsigned*)((const char*)(gbase) + (voff)[_i]), (PG8_LAS unsigned*)(lds + (bufoff) + ldsw + _i * 8192), 16, 0, 0); } while (0)
; #define PG8_LDA(dst, b, h) do { _Pragma("unroll") for (int m = 0; m < 4; ++m) _Pragma("unroll") for (int k = 0; k < 2; ++k) dst[m][k] = *(const PG8_LAS bf16x8*)(lds + PG8_SA(b, h) + aoff + m * 2048 + k * 1024); } while (0)
; #define PG8_LDB(dst, b, h) do { _Pragma("unroll") for (int n = 0; n < 2; ++n) _Pragma("unroll") for (int k = 0; k < 2; ++k) dst[n][k] = *(const PG8_LAS bf16x8*)(lds + PG8_SB(b, h) + boff + n * 2048 + k * 1024); } while (0)
; #define PG8_MMA(ai, bj, At, Bt) do { __builtin_amdgcn_s_setprio(1); _Pragma("unroll") for (int m = 0; m < 4; ++m) _Pragma("unroll") for (int n = 0; n < 2; ++n) _Pragma("unroll") for (int k = 0; k < 2; ++k) \
;         acc[ai][bj][m][n] = __builtin_amdgcn_mfma_f32_16x16x32_bf16(Bt[n][k], At[m][k], acc[ai][bj][m][n], 0, 0, 0); __builtin_amdgcn_s_setprio(0); } while (0)
; #define PG8_WAIT_V(n) asm volatile("s_waitcnt vmcnt(" #n ")" ::: "memory")
; #define PG8_WAIT_L(n) asm volatile("s_waitcnt lgkmcnt(" #n ")" ::: "memory")
; #define PG8_BAR __builtin_amdgcn_s_barrier()
; #define PG8_SCHED __builtin_amdgcn_sched_barrier(0)
; template <class Epi, class Sched, bool ALIGN_EPI = false, bool SP2 = false>
; __device__ __forceinline__ void gemm_phase(PG8_LAS unsigned char* lds, const Gemm g, const Sched& S, const Epi& E) {
;     ...
;             PG8_WAIT_V(8); PG8_WAIT_L(0); PG8_BAR; PG8_MMA(1, 0, At, B0); PG8_MMA(1, 1, At, B1); PG8_BAR; PG8_SCHED;
;             PG8_LDB(B0, 1, 0); PG8_LDB(B1, 1, 1); PG8_SCHED; PG8_LDA(At, 1, 0); PG8_STAGE(PG8_SA(0, 1), a2 + hstep, voffA);
;             PG8_WAIT_V(8); PG8_WAIT_L(0); PG8_BAR; PG8_MMA(0, 0, At, B0); PG8_MMA(0, 1, At, B1); PG8_BAR; PG8_SCHED;
;             PG8_LDA(At, 1, 1); PG8_STAGE(PG8_SB(1, 0), b3, voffB); PG8_STAGE(PG8_SB(1, 1), b3 + hstep, voffB); PG8_STAGE(PG8_SA(1, 0), a3, voffA);
	s_setprio 1
	s_waitcnt lgkmcnt(0)
	v_mfma_f32_16x16x32_bf16 v[56:59], v[144:147], v[190:193], v[56:59]
	v_mfma_f32_16x16x32_bf16 v[60:63], v[166:169], v[190:193], v[60:63]
	v_mfma_f32_16x16x32_bf16 v[40:43], v[144:147], v[198:201], v[40:43]
	v_mfma_f32_16x16x32_bf16 v[44:47], v[166:169], v[198:201], v[44:47]
	v_mfma_f32_16x16x32_bf16 v[24:27], v[144:147], v[206:209], v[24:27]
	v_mfma_f32_16x16x32_bf16 v[28:31], v[166:169], v[206:209], v[28:31]
	v_mfma_f32_16x16x32_bf16 v[8:11], v[144:147], v[214:217], v[8:11]
	v_mfma_f32_16x16x32_bf16 v[12:15], v[166:169], v[214:217], v[12:15]
	v_mfma_f32_16x16x32_bf16 v[56:59], v[162:165], v[194:197], v[56:59]
	v_mfma_f32_16x16x32_bf16 v[60:63], v[170:173], v[194:197], v[60:63]
	v_mfma_f32_16x16x32_bf16 v[40:43], v[162:165], v[202:205], v[40:43]
	v_mfma_f32_16x16x32_bf16 v[44:47], v[170:173], v[202:205], v[44:47]
	v_mfma_f32_16x16x32_bf16 v[24:27], v[162:165], v[210:213], v[24:27]
	v_mfma_f32_16x16x32_bf16 v[28:31], v[170:173], v[210:213], v[28:31]
	v_mfma_f32_16x16x32_bf16 v[8:11], v[162:165], v[218:221], v[8:11]
	v_mfma_f32_16x16x32_bf16 v[12:15], v[170:173], v[218:221], v[12:15]
	s_setprio 0
	s_setprio 1
	v_mfma_f32_16x16x32_bf16 v[52:55], v[174:177], v[190:193], v[52:55]
	v_mfma_f32_16x16x32_bf16 v[48:51], v[182:185], v[190:193], v[48:51]
	v_mfma_f32_16x16x32_bf16 v[36:39], v[174:177], v[198:201], v[36:39]
	v_mfma_f32_16x16x32_bf16 v[32:35], v[182:185], v[198:201], v[32:35]
	v_mfma_f32_16x16x32_bf16 v[20:23], v[174:177], v[206:209], v[20:23]
	v_mfma_f32_16x16x32_bf16 v[16:19], v[182:185], v[206:209], v[16:19]
	v_mfma_f32_16x16x32_bf16 v[4:7], v[174:177], v[214:217], v[4:7]
	v_mfma_f32_16x16x32_bf16 v[0:3], v[182:185], v[214:217], v[0:3]
	v_mfma_f32_16x16x32_bf16 v[52:55], v[178:181], v[194:197], v[52:55]
	v_mfma_f32_16x16x32_bf16 v[48:51], v[186:189], v[194:197], v[48:51]
	v_mfma_f32_16x16x32_bf16 v[36:39], v[178:181], v[202:205], v[36:39]
	v_mfma_f32_16x16x32_bf16 v[32:35], v[186:189], v[202:205], v[32:35]
	v_mfma_f32_16x16x32_bf16 v[20:23], v[178:181], v[210:213], v[20:23]
	v_mfma_f32_16x16x32_bf16 v[16:19], v[186:189], v[210:213], v[16:19]
	v_mfma_f32_16x16x32_bf16 v[4:7], v[178:181], v[218:221], v[4:7]
	v_mfma_f32_16x16x32_bf16 v[0:3], v[186:189], v[218:221], v[0:3]
	s_setprio 0
	s_barrier
	s_sleep 1
	s_add_i32 s74, 0, 0x18000
	s_add_i32 s75, 0, 0x1c000
	v_add_u32_e32 v170, s74, v151
	v_add_u32_e32 v186, s75, v151
	ds_read_b128 v[144:147], v170
	ds_read_b128 v[162:165], v170 offset:1024
	ds_read_b128 v[166:169], v170 offset:2048
	ds_read_b128 v[170:173], v170 offset:3072
	ds_read_b128 v[174:177], v186
	ds_read_b128 v[178:181], v186 offset:1024
	ds_read_b128 v[182:185], v186 offset:2048
	ds_read_b128 v[186:189], v186 offset:3072
	s_add_u32 s46, s46, 0xb0000
	s_addc_u32 s47, s47, 0
	s_mov_b32 m0, s50
	v_lshl_add_u64 v[228:229], s[46:47], 0, v[128:129]
	ds_read_b128 v[190:193], v156 offset:32768
	ds_read_b128 v[194:197], v156 offset:33792
	ds_read_b128 v[198:201], v156 offset:34816
	ds_read_b128 v[202:205], v156 offset:35840
	ds_read_b128 v[206:209], v156 offset:36864
	ds_read_b128 v[210:213], v156 offset:37888
	ds_read_b128 v[214:217], v156 offset:38912
	ds_read_b128 v[218:221], v156 offset:39936
	global_load_lds_dwordx4 v[228:229], off
	v_lshl_add_u64 v[228:229], s[46:47], 0, v[132:133]
	s_mov_b32 m0, s51
	s_nop 0
	global_load_lds_dwordx4 v[228:229], off
	s_waitcnt vmcnt(8)
	s_waitcnt lgkmcnt(0)
	s_barrier
	s_setprio 1
	s_waitcnt lgkmcnt(0)
	v_mfma_f32_16x16x32_bf16 v[124:127], v[144:147], v[190:193], v[124:127]
	v_mfma_f32_16x16x32_bf16 v[120:123], v[166:169], v[190:193], v[120:123]
	v_mfma_f32_16x16x32_bf16 v[104:107], v[144:147], v[198:201], v[104:107]
	v_mfma_f32_16x16x32_bf16 v[108:111], v[166:169], v[198:201], v[108:111]
	v_mfma_f32_16x16x32_bf16 v[88:91], v[144:147], v[206:209], v[88:91]
	v_mfma_f32_16x16x32_bf16 v[92:95], v[166:169], v[206:209], v[92:95]
	v_mfma_f32_16x16x32_bf16 v[72:75], v[144:147], v[214:217], v[72:75]
	v_mfma_f32_16x16x32_bf16 v[76:79], v[166:169], v[214:217], v[76:79]
	v_mfma_f32_16x16x32_bf16 v[124:127], v[162:165], v[194:197], v[124:127]
	v_mfma_f32_16x16x32_bf16 v[120:123], v[170:173], v[194:197], v[120:123]
	v_mfma_f32_16x16x32_bf16 v[104:107], v[162:165], v[202:205], v[104:107]
	v_mfma_f32_16x16x32_bf16 v[108:111], v[170:173], v[202:205], v[108:111]
	v_mfma_f32_16x16x32_bf16 v[88:91], v[162:165], v[210:213], v[88:91]
	v_mfma_f32_16x16x32_bf16 v[92:95], v[170:173], v[210:213], v[92:95]
	v_mfma_f32_16x16x32_bf16 v[72:75], v[162:165], v[218:221], v[72:75]
	v_mfma_f32_16x16x32_bf16 v[76:79], v[170:173], v[218:221], v[76:79]
	s_setprio 0
	s_setprio 1
	v_mfma_f32_16x16x32_bf16 v[116:119], v[174:177], v[190:193], v[116:119]
	v_mfma_f32_16x16x32_bf16 v[112:115], v[182:185], v[190:193], v[112:115]
	v_mfma_f32_16x16x32_bf16 v[100:103], v[174:177], v[198:201], v[100:103]
	v_mfma_f32_16x16x32_bf16 v[96:99], v[182:185], v[198:201], v[96:99]
	v_mfma_f32_16x16x32_bf16 v[84:87], v[174:177], v[206:209], v[84:87]
	v_mfma_f32_16x16x32_bf16 v[80:83], v[182:185], v[206:209], v[80:83]
	v_mfma_f32_16x16x32_bf16 v[68:71], v[174:177], v[214:217], v[68:71]
	v_mfma_f32_16x16x32_bf16 v[64:67], v[182:185], v[214:217], v[64:67]
	v_mfma_f32_16x16x32_bf16 v[116:119], v[178:181], v[194:197], v[116:119]
	v_mfma_f32_16x16x32_bf16 v[112:115], v[186:189], v[194:197], v[112:115]
	v_mfma_f32_16x16x32_bf16 v[100:103], v[178:181], v[202:205], v[100:103]
	v_mfma_f32_16x16x32_bf16 v[96:99], v[186:189], v[202:205], v[96:99]
	v_mfma_f32_16x16x32_bf16 v[84:87], v[178:181], v[210:213], v[84:87]
	v_mfma_f32_16x16x32_bf16 v[80:83], v[186:189], v[210:213], v[80:83]
	v_mfma_f32_16x16x32_bf16 v[68:71], v[178:181], v[218:221], v[68:71]
	v_mfma_f32_16x16x32_bf16 v[64:67], v[186:189], v[218:221], v[64:67]
	s_setprio 0
	s_barrier
; #define PG8_STAGE(bufoff, gbase, voff) do { _Pragma("unroll") for (int _i = 0; _i < 2; ++_i) \
;         __builtin_amdgcn_global_load_lds((const unsigned*)((const char*)(gbase) + (voff)[_i]), (PG8_LAS unsigned*)(lds + (bufoff) + ldsw + _i * 8192), 16, 0, 0); } while (0)
; #define PG8_LDA(dst, b, h) do { _Pragma("unroll") for (int m = 0; m < 4; ++m) _Pragma("unroll") for (int k = 0; k < 2; ++k) dst[m][k] = *(const PG8_LAS bf16x8*)(lds + PG8_SA(b, h) + aoff + m * 2048 + k * 1024); } while (0)
; #define PG8_MMA(ai, bj, At, Bt) do { __builtin_amdgcn_s_setprio(1); _Pragma("unroll") for (int m = 0; m < 4; ++m) _Pragma("unroll") for (int n = 0; n < 2; ++n) _Pragma("unroll") for (int k = 0; k < 2; ++k) \
;         acc[ai][bj][m][n] = __builtin_amdgcn_mfma_f32_16x16x32_bf16(Bt[n][k], At[m][k], acc[ai][bj][m][n], 0, 0, 0); __builtin_amdgcn_s_setprio(0); } while (0)
; #define PG8_WAIT_V(n) asm volatile("s_waitcnt vmcnt(" #n ")" ::: "memory")
; #define PG8_WAIT_L(n) asm volatile("s_waitcnt lgkmcnt(" #n ")" ::: "memory")
; #define PG8_BAR __builtin_amdgcn_s_barrier()
; #define PG8_SCHED __builtin_amdgcn_sched_barrier(0)
; template <class Epi, class Sched, bool ALIGN_EPI = false, bool SP2 = false>
; __device__ __forceinline__ void gemm_phase(PG8_LAS unsigned char* lds, const Gemm g, const Sched& S, const Epi& E) {
;     ...
;             PG8_WAIT_V(8); PG8_WAIT_L(0); PG8_BAR; PG8_MMA(0, 0, At, B0); PG8_MMA(0, 1, At, B1); PG8_BAR; PG8_SCHED;
;             PG8_LDA(At, 1, 1); PG8_STAGE(PG8_SB(1, 0), b3, voffB); PG8_STAGE(PG8_SB(1, 1), b3 + hstep, voffB); PG8_STAGE(PG8_SA(1, 0), a3, voffA);
;             PG8_WAIT_V(8); PG8_WAIT_L(0); PG8_BAR; PG8_MMA(1, 0, At, B0); PG8_MMA(1, 1, At, B1); PG8_BAR; PG8_SCHED;
;     ...
;         if constexpr (ALIGN_EPI) { if (wr == 0) PG8_BAR; }
	s_sleep 1
	s_add_i32 s46, s74, s33
	v_lshl_add_u64 v[148:149], v[148:149], 0, s[12:13]
	s_mov_b32 m0, s46
	ds_read_b128 v[190:193], v156 offset:49152
	ds_read_b128 v[194:197], v156 offset:50176
	ds_read_b128 v[198:201], v156 offset:51200
	ds_read_b128 v[202:205], v156 offset:52224
	ds_read_b128 v[206:209], v156 offset:53248
	ds_read_b128 v[210:213], v156 offset:54272
	ds_read_b128 v[214:217], v156 offset:55296
	ds_read_b128 v[218:221], v156 offset:56320
	global_load_lds_dwordx4 v[148:149], off
	s_add_i32 m0, s46, 0x2000
	s_add_u32 s44, s44, 0xb0080
	v_lshl_add_u64 v[148:149], v[222:223], 0, s[12:13]
	s_addc_u32 s45, s45, 0
	s_add_i32 s46, s75, s33
	global_load_lds_dwordx4 v[148:149], off
	v_lshl_add_u64 v[148:149], s[44:45], 0, v[130:131]
	s_mov_b32 m0, s46
	s_nop 0
	global_load_lds_dwordx4 v[148:149], off
	v_lshl_add_u64 v[148:149], s[44:45], 0, v[134:135]
	s_add_i32 m0, s46, 0x2000
	s_nop 0
	global_load_lds_dwordx4 v[148:149], off
	v_lshl_add_u64 v[148:149], v[224:225], 0, s[12:13]
	s_mov_b32 m0, s53
	s_nop 0
	global_load_lds_dwordx4 v[148:149], off
	v_lshl_add_u64 v[148:149], v[226:227], 0, s[12:13]
	s_mov_b32 m0, s60
	s_nop 0
	global_load_lds_dwordx4 v[148:149], off
	s_waitcnt vmcnt(8)
	s_waitcnt lgkmcnt(0)
	s_barrier
	s_setprio 1
	s_waitcnt lgkmcnt(0)
	v_mfma_f32_16x16x32_bf16 v[56:59], v[144:147], v[190:193], v[56:59]
	v_mfma_f32_16x16x32_bf16 v[60:63], v[166:169], v[190:193], v[60:63]
	v_mfma_f32_16x16x32_bf16 v[40:43], v[144:147], v[198:201], v[40:43]
	v_mfma_f32_16x16x32_bf16 v[44:47], v[166:169], v[198:201], v[44:47]
	v_mfma_f32_16x16x32_bf16 v[24:27], v[144:147], v[206:209], v[24:27]
	v_mfma_f32_16x16x32_bf16 v[28:31], v[166:169], v[206:209], v[28:31]
	v_mfma_f32_16x16x32_bf16 v[8:11], v[144:147], v[214:217], v[8:11]
	v_mfma_f32_16x16x32_bf16 v[12:15], v[166:169], v[214:217], v[12:15]
	v_mfma_f32_16x16x32_bf16 v[56:59], v[162:165], v[194:197], v[56:59]
	v_mfma_f32_16x16x32_bf16 v[60:63], v[170:173], v[194:197], v[60:63]
	v_mfma_f32_16x16x32_bf16 v[40:43], v[162:165], v[202:205], v[40:43]
	v_mfma_f32_16x16x32_bf16 v[44:47], v[170:173], v[202:205], v[44:47]
	v_mfma_f32_16x16x32_bf16 v[24:27], v[162:165], v[210:213], v[24:27]
	v_mfma_f32_16x16x32_bf16 v[28:31], v[170:173], v[210:213], v[28:31]
	v_mfma_f32_16x16x32_bf16 v[8:11], v[162:165], v[218:221], v[8:11]
	v_mfma_f32_16x16x32_bf16 v[12:15], v[170:173], v[218:221], v[12:15]
	s_setprio 0
	s_setprio 1
	v_mfma_f32_16x16x32_bf16 v[52:55], v[174:177], v[190:193], v[52:55]
	v_mfma_f32_16x16x32_bf16 v[48:51], v[182:185], v[190:193], v[48:51]
	v_mfma_f32_16x16x32_bf16 v[36:39], v[174:177], v[198:201], v[36:39]
	v_mfma_f32_16x16x32_bf16 v[32:35], v[182:185], v[198:201], v[32:35]
	v_mfma_f32_16x16x32_bf16 v[20:23], v[174:177], v[206:209], v[20:23]
	v_mfma_f32_16x16x32_bf16 v[16:19], v[182:185], v[206:209], v[16:19]
	v_mfma_f32_16x16x32_bf16 v[4:7], v[174:177], v[214:217], v[4:7]
	v_mfma_f32_16x16x32_bf16 v[0:3], v[182:185], v[214:217], v[0:3]
	v_mfma_f32_16x16x32_bf16 v[52:55], v[178:181], v[194:197], v[52:55]
	v_mfma_f32_16x16x32_bf16 v[48:51], v[186:189], v[194:197], v[48:51]
	v_mfma_f32_16x16x32_bf16 v[36:39], v[178:181], v[202:205], v[36:39]
	v_mfma_f32_16x16x32_bf16 v[32:35], v[186:189], v[202:205], v[32:35]
	v_mfma_f32_16x16x32_bf16 v[20:23], v[178:181], v[210:213], v[20:23]
	v_mfma_f32_16x16x32_bf16 v[16:19], v[186:189], v[210:213], v[16:19]
	v_mfma_f32_16x16x32_bf16 v[4:7], v[178:181], v[218:221], v[4:7]
	v_mfma_f32_16x16x32_bf16 v[0:3], v[186:189], v[218:221], v[0:3]
	s_setprio 0
	s_barrier
	s_sleep 1
	s_add_i32 s73, s73, 2
	s_add_u32 s4, s4, 0x100
	s_addc_u32 s5, s5, 0
	s_add_u32 s43, s43, 0x100
	s_addc_u32 s72, s72, 0
	s_cmp_gt_u32 s73, 41
	s_cbranch_scc0 .LBB0_970
	s_and_b64 vcc, exec, s[14:15]
	s_cbranch_vccz .LBB0_973
	s_barrier
